# LDS-DMA (global_load_lds, swizzled linear LDS image) for all unrolled K=1024 GEMM bodies incl RK_G1, DA_O, RK_O
# baseline (speedup 1.0000x reference)
; DEVI int TID() { int t = threadIdx.x; asm volatile("" : "+v"(t)); return t; }
;     ...
;   const int tid = TID(), lane = tid & 63, wave = tid >> 6, wm = wave >> 1, wn = wave & 1;
;   f32x16 acc[2][2];
; #pragma unroll
;   for (int i = 0; i < 2; ++i)
; #pragma unroll
;     for (int j = 0; j < 2; ++j) acc[i][j] = zero16();
;   const int lrow = tid >> 3, lkc = (tid & 7) * 8;
;   const bf16* Ag = jb.A + (size_t)max(m0 + lrow, 0) * jb.lda + lkc;
;   const bf16* Ag1 = jb.A + (ptrdiff_t)(m0 + lrow) * jb.lda + lkc;
;   const bf16* Bg = jb.Bt + (size_t)(n0 + lrow) * jb.K + lkc;
;   const size_t astep = (size_t)32 * jb.lda, bstep = (size_t)32 * jb.K;
;   if (kt1 < 0) kt1 = jb.K >> 6;
;   const int nk = kt1 - kt0;
;   Ag += (size_t)kt0 * 64; Ag1 += (size_t)kt0 * 64; Bg += (size_t)kt0 * 64;
;   u32x4 ra0[4], rb0[4], ra1[4], rb1[4];
;     ...
;   bf16* As1 = As + 2 * 128 * 72;
;   bf16* Bs1 = As1 + 128 * 72;
;   G_LOAD(ra0, rb0, 0);
;   if (nk > 1) G_LOAD(ra1, rb1, 1);
;   G_STORE(ra0, rb0, As, Bs);
;   __syncthreads();
.LBB0_20:
	s_ashr_i32 s2, s4, 31
	s_lshr_b32 s2, s2, 25
	s_add_i32 s2, s4, s2
	s_and_b32 s3, s2, 0xffffff80
	s_sub_i32 s3, s4, s3
	s_ashr_i32 s5, s3, 31
	s_lshr_b32 s5, s5, 28
	s_add_i32 s5, s3, s5
	s_and_b32 s14, s5, 0x1fffff0
	s_sub_i32 s3, s3, s14
	s_lshl_b32 s2, s2, 4
	s_and_b32 s2, s2, 0xfffff800
	s_lshl_b32 s3, s3, 7
	v_mov_b32_e32 v84, v208
	s_add_i32 s3, s3, s2
	s_lshl_b32 s2, s5, 3
	v_ashrrev_i32_e32 v82, 3, v84
	v_add_u32_e32 v0, s3, v82
	v_max_i32_e32 v96, 0, v0
	v_lshlrev_b32_e32 v1, 4, v84
	v_lshlrev_b64 v[2:3], 11, v[96:97]
	v_and_b32_e32 v96, 0x70, v1
	s_mov_b64 s[96:97], 0x80
	v_lshrrev_b32_e32 v178, 4, v208
	v_and_b32_e32 v178, 7, v178
	v_lshlrev_b32_e32 v178, 4, v178
	v_xor_b32_e32 v96, v96, v178
	v_lshrrev_b32_e32 v179, 6, v208
	v_lshlrev_b32_e32 v179, 10, v179
	v_lshrrev_b32_e32 v180, 5, v208
	v_lshrrev_b32_e32 v181, 1, v208
	v_xor_b32_e32 v180, v180, v181
	v_readfirstlane_b32 s94, v179
	v_and_b32_e32 v180, 1, v180
	v_lshlrev_b32_e32 v180, 4, v180
	v_and_b32_e32 v181, 31, v208
	v_lshlrev_b32_e32 v181, 7, v181
	v_or_b32_e32 v180, v180, v181
	v_lshrrev_b32_e32 v181, 7, v208
	v_lshlrev_b32_e32 v181, 13, v181
	v_or_b32_e32 v194, v180, v181
	v_bfe_u32 v181, v208, 6, 1
	v_lshlrev_b32_e32 v181, 13, v181
	v_or_b32_e32 v195, v180, v181
	v_bfe_u32 v178, v208, 2, 2
	v_xor_b32_e32 v179, 0, v178
	v_lshlrev_b32_e32 v179, 5, v179
	v_or_b32_e32 v170, v194, v179
	v_or_b32_e32 v174, v195, v179
	v_xor_b32_e32 v179, 1, v178
	v_lshlrev_b32_e32 v179, 5, v179
	v_or_b32_e32 v171, v194, v179
	v_or_b32_e32 v175, v195, v179
	v_xor_b32_e32 v179, 2, v178
	v_lshlrev_b32_e32 v179, 5, v179
	v_or_b32_e32 v172, v194, v179
	v_or_b32_e32 v176, v195, v179
	v_xor_b32_e32 v179, 3, v178
	v_lshlrev_b32_e32 v179, 5, v179
	v_or_b32_e32 v173, v194, v179
	v_or_b32_e32 v177, v195, v179
	v_ashrrev_i32_e32 v1, 31, v0
	v_lshlrev_b64 v[0:1], 11, v[0:1]
	s_and_b32 s2, s2, 0xffffff80
	v_lshl_add_u64 v[0:1], s[8:9], 0, v[0:1]
	v_lshl_add_u64 v[28:29], v[0:1], 0, v[96:97]
	v_add_u32_e32 v0, s2, v82
	v_ashrrev_i32_e32 v1, 31, v0
	v_lshlrev_b64 v[0:1], 11, v[0:1]
	v_lshl_add_u64 v[0:1], s[12:13], 0, v[0:1]
	v_add_co_u32_e32 v70, vcc, s63, v28
	v_lshl_add_u64 v[68:69], v[0:1], 0, v[96:97]
	s_nop 0
	v_addc_co_u32_e32 v71, vcc, 0, v29, vcc
	v_add_co_u32_e32 v72, vcc, s63, v68
	v_lshl_add_u64 v[2:3], s[8:9], 0, v[2:3]
	s_nop 0
	v_addc_co_u32_e32 v73, vcc, 0, v69, vcc
	v_add_co_u32_e32 v74, vcc, s64, v28
	v_lshl_add_u64 v[66:67], v[2:3], 0, v[96:97]
	s_nop 0
	v_addc_co_u32_e32 v75, vcc, 0, v29, vcc
	v_add_co_u32_e32 v76, vcc, s64, v68
	v_addc_co_u32_e32 v77, vcc, 0, v69, vcc
	v_add_co_u32_e32 v78, vcc, s65, v68
	s_nop 0
	v_addc_co_u32_e32 v79, vcc, 0, v69, vcc
	v_add_co_u32_e32 v80, vcc, s65, v28
	s_nop 0
	v_addc_co_u32_e32 v81, vcc, 0, v29, vcc
	v_ashrrev_i32_e32 v64, 1, v84
	v_lshrrev_b32_e32 v65, 1, v84
	v_and_b32_e32 v85, 0xffffffc0, v64
	v_and_b32_e32 v88, 16, v65
	v_and_or_b32 v64, v84, 31, v85
	v_mad_u64_u32 v[82:83], s[14:15], v82, s91, v[96:97]
	v_mad_u64_u32 v[64:65], s[14:15], v64, s91, v[88:89]
	v_add_u32_e32 v86, 0xd800, v82
	v_and_b32_e32 v65, 0x5f, v84
	v_mad_u32_u24 v83, v65, s91, v88
	s_mov_b32 s14, 23
	s_add_u32 m0, s94, 0x4000
	s_nop 1
	global_load_lds_dwordx4 v[68:69], off
	s_add_u32 m0, s94, 0x0
	s_nop 1
	global_load_lds_dwordx4 v[66:67], off
	s_add_u32 m0, s94, 0x5000
	s_nop 1
	global_load_lds_dwordx4 v[72:73], off
	s_add_u32 m0, s94, 0x6000
	s_nop 1
	global_load_lds_dwordx4 v[76:77], off
	s_add_u32 m0, s94, 0x7000
	s_nop 1
	global_load_lds_dwordx4 v[78:79], off
	s_add_u32 m0, s94, 0x1000
	s_nop 1
	global_load_lds_dwordx4 v[70:71], off
	s_add_u32 m0, s94, 0x2000
	s_nop 1
	global_load_lds_dwordx4 v[74:75], off
	s_add_u32 m0, s94, 0x3000
	s_nop 1
	global_load_lds_dwordx4 v[80:81], off
	s_waitcnt lgkmcnt(0)
	s_waitcnt vmcnt(0)
	s_barrier
	v_lshl_add_u64 v[66:67], v[66:67], 0, s[96:97]
	s_add_u32 m0, s94, 0x8000
	s_nop 1
	global_load_lds_dwordx4 v[66:67], off
	v_lshl_add_u64 v[68:69], v[68:69], 0, s[96:97]
	s_add_u32 m0, s94, 0xc000
	s_nop 1
	global_load_lds_dwordx4 v[68:69], off
	v_lshl_add_u64 v[70:71], v[70:71], 0, s[96:97]
	s_add_u32 m0, s94, 0x9000
	s_nop 1
	global_load_lds_dwordx4 v[70:71], off
	v_lshl_add_u64 v[72:73], v[72:73], 0, s[96:97]
	s_add_u32 m0, s94, 0xd000
	s_nop 1
	global_load_lds_dwordx4 v[72:73], off
	v_lshl_add_u64 v[74:75], v[74:75], 0, s[96:97]
	s_add_u32 m0, s94, 0xa000
	s_nop 1
	global_load_lds_dwordx4 v[74:75], off
	v_lshl_add_u64 v[76:77], v[76:77], 0, s[96:97]
	s_add_u32 m0, s94, 0xe000
	s_nop 1
	global_load_lds_dwordx4 v[76:77], off
	v_lshl_add_u64 v[80:81], v[80:81], 0, s[96:97]
	s_add_u32 m0, s94, 0xb000
	s_nop 1
	global_load_lds_dwordx4 v[80:81], off
	v_lshl_add_u64 v[78:79], v[78:79], 0, s[96:97]
	s_add_u32 m0, s94, 0xf000
	s_nop 1
	global_load_lds_dwordx4 v[78:79], off
	ds_read_b128 v[0:3], v170 offset:0
	ds_read_b128 v[4:7], v174 offset:16384
	ds_read_b128 v[88:91], v171 offset:0
	ds_read_b128 v[92:95], v175 offset:16384
	ds_read_b128 v[8:11], v174 offset:20480
	ds_read_b128 v[98:101], v175 offset:20480
	s_waitcnt lgkmcnt(4)
	v_mfma_f32_32x32x16_bf16 v[48:63], v[0:3], v[4:7], 0
	s_waitcnt lgkmcnt(1)
	v_mfma_f32_32x32x16_bf16 v[32:47], v[0:3], v[8:11], 0
	ds_read_b128 v[0:3], v170 offset:4096
	ds_read_b128 v[102:105], v171 offset:4096
	s_waitcnt lgkmcnt(1)
	v_mfma_f32_32x32x16_bf16 v[16:31], v[0:3], v[4:7], 0
	v_mfma_f32_32x32x16_bf16 v[0:15], v[0:3], v[8:11], 0
	v_mfma_f32_32x32x16_bf16 v[48:63], v[88:91], v[92:95], v[48:63]
	v_mfma_f32_32x32x16_bf16 v[32:47], v[88:91], v[98:101], v[32:47]
	s_waitcnt lgkmcnt(0)
	v_mfma_f32_32x32x16_bf16 v[16:31], v[102:105], v[92:95], v[16:31]
	v_mfma_f32_32x32x16_bf16 v[0:15], v[102:105], v[98:101], v[0:15]
	ds_read_b128 v[88:91], v172 offset:0
	ds_read_b128 v[92:95], v176 offset:16384
	ds_read_b128 v[98:101], v173 offset:0
	ds_read_b128 v[102:105], v177 offset:16384
	ds_read_b128 v[106:109], v176 offset:20480
	ds_read_b128 v[110:113], v177 offset:20480
	s_waitcnt lgkmcnt(4)
	v_mfma_f32_32x32x16_bf16 v[48:63], v[88:91], v[92:95], v[48:63]
	s_waitcnt lgkmcnt(1)
	v_mfma_f32_32x32x16_bf16 v[32:47], v[88:91], v[106:109], v[32:47]
	ds_read_b128 v[88:91], v172 offset:4096
	ds_read_b128 v[114:117], v173 offset:4096
	s_waitcnt lgkmcnt(1)
	v_mfma_f32_32x32x16_bf16 v[16:31], v[88:91], v[92:95], v[16:31]
	v_mfma_f32_32x32x16_bf16 v[0:15], v[88:91], v[106:109], v[0:15]
	v_mfma_f32_32x32x16_bf16 v[48:63], v[98:101], v[102:105], v[48:63]
	v_mfma_f32_32x32x16_bf16 v[32:47], v[98:101], v[110:113], v[32:47]
	s_waitcnt lgkmcnt(0)
	v_mfma_f32_32x32x16_bf16 v[16:31], v[114:117], v[102:105], v[16:31]
	s_waitcnt vmcnt(0)
	s_barrier
;     ...
;   bf16* As1 = As + 2 * 128 * 72;
;   bf16* Bs1 = As1 + 128 * 72;
;   G_LOAD(ra0, rb0, 0);
;   if (nk > 1) G_LOAD(ra1, rb1, 1);
;   G_STORE(ra0, rb0, As, Bs);
;   __syncthreads();
;   for (int kt = 0; kt < nk; kt += 2) {
;     if (kt + 2 < nk) G_LOAD(ra0, rb0, kt + 2);
;     if (kt + 1 < nk) G_STORE(ra1, rb1, As1, Bs1);
;     G_COMPUTE(As, Bs);
;     __syncthreads();
;     if (kt + 1 < nk) {
;       if (kt + 3 < nk) G_LOAD(ra1, rb1, kt + 3);
;       if (kt + 2 < nk) G_STORE(ra0, rb0, As, Bs);
;       G_COMPUTE(As1, Bs1);
;       __syncthreads();
;     }
;   }
	v_lshl_add_u64 v[66:67], v[66:67], 0, s[96:97]
	s_add_u32 m0, s94, 0x0
	s_nop 1
	global_load_lds_dwordx4 v[66:67], off
	v_lshl_add_u64 v[68:69], v[68:69], 0, s[96:97]
	s_add_u32 m0, s94, 0x4000
	s_nop 1
	global_load_lds_dwordx4 v[68:69], off
	v_lshl_add_u64 v[70:71], v[70:71], 0, s[96:97]
	s_add_u32 m0, s94, 0x1000
	s_nop 1
	global_load_lds_dwordx4 v[70:71], off
	v_lshl_add_u64 v[72:73], v[72:73], 0, s[96:97]
	s_add_u32 m0, s94, 0x5000
	s_nop 1
	global_load_lds_dwordx4 v[72:73], off
	v_lshl_add_u64 v[74:75], v[74:75], 0, s[96:97]
	s_add_u32 m0, s94, 0x2000
	s_nop 1
	global_load_lds_dwordx4 v[74:75], off
	v_lshl_add_u64 v[76:77], v[76:77], 0, s[96:97]
	s_add_u32 m0, s94, 0x6000
	s_nop 1
	global_load_lds_dwordx4 v[76:77], off
	v_lshl_add_u64 v[80:81], v[80:81], 0, s[96:97]
	s_add_u32 m0, s94, 0x3000
	s_nop 1
	global_load_lds_dwordx4 v[80:81], off
	v_lshl_add_u64 v[78:79], v[78:79], 0, s[96:97]
	s_add_u32 m0, s94, 0x7000
	s_nop 1
	global_load_lds_dwordx4 v[78:79], off
	v_mfma_f32_32x32x16_bf16 v[0:15], v[114:117], v[110:113], v[0:15]
	ds_read_b128 v[88:91], v170 offset:32768
	ds_read_b128 v[92:95], v174 offset:49152
	ds_read_b128 v[98:101], v171 offset:32768
	ds_read_b128 v[102:105], v175 offset:49152
	ds_read_b128 v[106:109], v174 offset:53248
	ds_read_b128 v[110:113], v175 offset:53248
	s_waitcnt lgkmcnt(4)
	v_mfma_f32_32x32x16_bf16 v[48:63], v[88:91], v[92:95], v[48:63]
	s_waitcnt lgkmcnt(1)
	v_mfma_f32_32x32x16_bf16 v[32:47], v[88:91], v[106:109], v[32:47]
	ds_read_b128 v[88:91], v170 offset:36864
	ds_read_b128 v[114:117], v171 offset:36864
	s_waitcnt lgkmcnt(1)
	v_mfma_f32_32x32x16_bf16 v[16:31], v[88:91], v[92:95], v[16:31]
	v_mfma_f32_32x32x16_bf16 v[0:15], v[88:91], v[106:109], v[0:15]
	v_mfma_f32_32x32x16_bf16 v[48:63], v[98:101], v[102:105], v[48:63]
	v_mfma_f32_32x32x16_bf16 v[32:47], v[98:101], v[110:113], v[32:47]
	s_waitcnt lgkmcnt(0)
	v_mfma_f32_32x32x16_bf16 v[16:31], v[114:117], v[102:105], v[16:31]
	ds_read_b128 v[88:91], v172 offset:32768
	ds_read_b128 v[92:95], v176 offset:49152
	ds_read_b128 v[98:101], v173 offset:32768
	ds_read_b128 v[102:105], v177 offset:49152
	v_mfma_f32_32x32x16_bf16 v[0:15], v[114:117], v[110:113], v[0:15]
	ds_read_b128 v[106:109], v176 offset:53248
	ds_read_b128 v[110:113], v177 offset:53248
	s_waitcnt lgkmcnt(4)
	v_mfma_f32_32x32x16_bf16 v[48:63], v[88:91], v[92:95], v[48:63]
	s_waitcnt lgkmcnt(1)
	v_mfma_f32_32x32x16_bf16 v[32:47], v[88:91], v[106:109], v[32:47]
	ds_read_b128 v[88:91], v172 offset:36864
	ds_read_b128 v[114:117], v173 offset:36864
	s_waitcnt lgkmcnt(1)
	v_mfma_f32_32x32x16_bf16 v[16:31], v[88:91], v[92:95], v[16:31]
	v_mfma_f32_32x32x16_bf16 v[0:15], v[88:91], v[106:109], v[0:15]
	v_mfma_f32_32x32x16_bf16 v[48:63], v[98:101], v[102:105], v[48:63]
	v_mfma_f32_32x32x16_bf16 v[32:47], v[98:101], v[110:113], v[32:47]
	s_waitcnt lgkmcnt(0)
	v_mfma_f32_32x32x16_bf16 v[16:31], v[114:117], v[102:105], v[16:31]
	s_waitcnt vmcnt(0)
	s_barrier
	v_lshl_add_u64 v[66:67], v[66:67], 0, s[96:97]
	s_add_u32 m0, s94, 0x8000
	s_nop 1
	global_load_lds_dwordx4 v[66:67], off
	v_lshl_add_u64 v[68:69], v[68:69], 0, s[96:97]
	s_add_u32 m0, s94, 0xc000
	s_nop 1
	global_load_lds_dwordx4 v[68:69], off
	v_lshl_add_u64 v[70:71], v[70:71], 0, s[96:97]
	s_add_u32 m0, s94, 0x9000
	s_nop 1
	global_load_lds_dwordx4 v[70:71], off
	v_lshl_add_u64 v[72:73], v[72:73], 0, s[96:97]
	s_add_u32 m0, s94, 0xd000
	s_nop 1
	global_load_lds_dwordx4 v[72:73], off
	v_lshl_add_u64 v[74:75], v[74:75], 0, s[96:97]
	s_add_u32 m0, s94, 0xa000
	s_nop 1
	global_load_lds_dwordx4 v[74:75], off
	v_lshl_add_u64 v[76:77], v[76:77], 0, s[96:97]
	s_add_u32 m0, s94, 0xe000
	s_nop 1
	global_load_lds_dwordx4 v[76:77], off
	v_lshl_add_u64 v[80:81], v[80:81], 0, s[96:97]
	s_add_u32 m0, s94, 0xb000
	s_nop 1
	global_load_lds_dwordx4 v[80:81], off
	v_lshl_add_u64 v[78:79], v[78:79], 0, s[96:97]
	s_add_u32 m0, s94, 0xf000
	s_nop 1
	global_load_lds_dwordx4 v[78:79], off
	v_mfma_f32_32x32x16_bf16 v[0:15], v[114:117], v[110:113], v[0:15]
	ds_read_b128 v[88:91], v170 offset:0
	ds_read_b128 v[92:95], v174 offset:16384
	ds_read_b128 v[98:101], v171 offset:0
	ds_read_b128 v[102:105], v175 offset:16384
	ds_read_b128 v[106:109], v174 offset:20480
	ds_read_b128 v[110:113], v175 offset:20480
	s_waitcnt lgkmcnt(4)
	v_mfma_f32_32x32x16_bf16 v[48:63], v[88:91], v[92:95], v[48:63]
	s_waitcnt lgkmcnt(1)
	v_mfma_f32_32x32x16_bf16 v[32:47], v[88:91], v[106:109], v[32:47]
	ds_read_b128 v[88:91], v170 offset:4096
	ds_read_b128 v[114:117], v171 offset:4096
	s_waitcnt lgkmcnt(1)
	v_mfma_f32_32x32x16_bf16 v[16:31], v[88:91], v[92:95], v[16:31]
	v_mfma_f32_32x32x16_bf16 v[0:15], v[88:91], v[106:109], v[0:15]
	v_mfma_f32_32x32x16_bf16 v[48:63], v[98:101], v[102:105], v[48:63]
	v_mfma_f32_32x32x16_bf16 v[32:47], v[98:101], v[110:113], v[32:47]
	s_waitcnt lgkmcnt(0)
	v_mfma_f32_32x32x16_bf16 v[16:31], v[114:117], v[102:105], v[16:31]
	ds_read_b128 v[88:91], v172 offset:0
	ds_read_b128 v[92:95], v176 offset:16384
	ds_read_b128 v[98:101], v173 offset:0
	ds_read_b128 v[102:105], v177 offset:16384
	v_mfma_f32_32x32x16_bf16 v[0:15], v[114:117], v[110:113], v[0:15]
	ds_read_b128 v[106:109], v176 offset:20480
	ds_read_b128 v[110:113], v177 offset:20480
	s_waitcnt lgkmcnt(4)
	v_mfma_f32_32x32x16_bf16 v[48:63], v[88:91], v[92:95], v[48:63]
	s_waitcnt lgkmcnt(1)
	v_mfma_f32_32x32x16_bf16 v[32:47], v[88:91], v[106:109], v[32:47]
	ds_read_b128 v[88:91], v172 offset:4096
	ds_read_b128 v[114:117], v173 offset:4096
	s_waitcnt lgkmcnt(1)
	v_mfma_f32_32x32x16_bf16 v[16:31], v[88:91], v[92:95], v[16:31]
	v_mfma_f32_32x32x16_bf16 v[0:15], v[88:91], v[106:109], v[0:15]
	v_mfma_f32_32x32x16_bf16 v[48:63], v[98:101], v[102:105], v[48:63]
	v_mfma_f32_32x32x16_bf16 v[32:47], v[98:101], v[110:113], v[32:47]
	s_waitcnt lgkmcnt(0)
	v_mfma_f32_32x32x16_bf16 v[16:31], v[114:117], v[102:105], v[16:31]
	s_waitcnt vmcnt(0)
	s_barrier
;     ...
;   bf16* As1 = As + 2 * 128 * 72;
;   bf16* Bs1 = As1 + 128 * 72;
;   G_LOAD(ra0, rb0, 0);
;   if (nk > 1) G_LOAD(ra1, rb1, 1);
;   G_STORE(ra0, rb0, As, Bs);
;   __syncthreads();
;   for (int kt = 0; kt < nk; kt += 2) {
;     if (kt + 2 < nk) G_LOAD(ra0, rb0, kt + 2);
;     if (kt + 1 < nk) G_STORE(ra1, rb1, As1, Bs1);
;     G_COMPUTE(As, Bs);
;     __syncthreads();
;     if (kt + 1 < nk) {
;       if (kt + 3 < nk) G_LOAD(ra1, rb1, kt + 3);
;       if (kt + 2 < nk) G_STORE(ra0, rb0, As, Bs);
;       G_COMPUTE(As1, Bs1);
;       __syncthreads();
;     }
;   }
	v_lshl_add_u64 v[66:67], v[66:67], 0, s[96:97]
	s_add_u32 m0, s94, 0x0
	s_nop 1
	global_load_lds_dwordx4 v[66:67], off
	v_lshl_add_u64 v[68:69], v[68:69], 0, s[96:97]
	s_add_u32 m0, s94, 0x4000
	s_nop 1
	global_load_lds_dwordx4 v[68:69], off
	v_lshl_add_u64 v[70:71], v[70:71], 0, s[96:97]
	s_add_u32 m0, s94, 0x1000
	s_nop 1
	global_load_lds_dwordx4 v[70:71], off
	v_lshl_add_u64 v[72:73], v[72:73], 0, s[96:97]
	s_add_u32 m0, s94, 0x5000
	s_nop 1
	global_load_lds_dwordx4 v[72:73], off
	v_lshl_add_u64 v[74:75], v[74:75], 0, s[96:97]
	s_add_u32 m0, s94, 0x2000
	s_nop 1
	global_load_lds_dwordx4 v[74:75], off
	v_lshl_add_u64 v[76:77], v[76:77], 0, s[96:97]
	s_add_u32 m0, s94, 0x6000
	s_nop 1
	global_load_lds_dwordx4 v[76:77], off
	v_lshl_add_u64 v[80:81], v[80:81], 0, s[96:97]
	s_add_u32 m0, s94, 0x3000
	s_nop 1
	global_load_lds_dwordx4 v[80:81], off
	v_lshl_add_u64 v[78:79], v[78:79], 0, s[96:97]
	s_add_u32 m0, s94, 0x7000
	s_nop 1
	global_load_lds_dwordx4 v[78:79], off
	v_mfma_f32_32x32x16_bf16 v[0:15], v[114:117], v[110:113], v[0:15]
	ds_read_b128 v[88:91], v170 offset:32768
	ds_read_b128 v[92:95], v174 offset:49152
	ds_read_b128 v[98:101], v171 offset:32768
	ds_read_b128 v[102:105], v175 offset:49152
	ds_read_b128 v[106:109], v174 offset:53248
	ds_read_b128 v[110:113], v175 offset:53248
	s_waitcnt lgkmcnt(4)
	v_mfma_f32_32x32x16_bf16 v[48:63], v[88:91], v[92:95], v[48:63]
	s_waitcnt lgkmcnt(1)
	v_mfma_f32_32x32x16_bf16 v[32:47], v[88:91], v[106:109], v[32:47]
	ds_read_b128 v[88:91], v170 offset:36864
	ds_read_b128 v[114:117], v171 offset:36864
	s_waitcnt lgkmcnt(1)
	v_mfma_f32_32x32x16_bf16 v[16:31], v[88:91], v[92:95], v[16:31]
	v_mfma_f32_32x32x16_bf16 v[0:15], v[88:91], v[106:109], v[0:15]
	v_mfma_f32_32x32x16_bf16 v[48:63], v[98:101], v[102:105], v[48:63]
	v_mfma_f32_32x32x16_bf16 v[32:47], v[98:101], v[110:113], v[32:47]
	s_waitcnt lgkmcnt(0)
	v_mfma_f32_32x32x16_bf16 v[16:31], v[114:117], v[102:105], v[16:31]
	ds_read_b128 v[88:91], v172 offset:32768
	ds_read_b128 v[92:95], v176 offset:49152
	ds_read_b128 v[98:101], v173 offset:32768
	ds_read_b128 v[102:105], v177 offset:49152
	v_mfma_f32_32x32x16_bf16 v[0:15], v[114:117], v[110:113], v[0:15]
	ds_read_b128 v[106:109], v176 offset:53248
	ds_read_b128 v[110:113], v177 offset:53248
	s_waitcnt lgkmcnt(4)
	v_mfma_f32_32x32x16_bf16 v[48:63], v[88:91], v[92:95], v[48:63]
	s_waitcnt lgkmcnt(1)
	v_mfma_f32_32x32x16_bf16 v[32:47], v[88:91], v[106:109], v[32:47]
	ds_read_b128 v[88:91], v172 offset:36864
	ds_read_b128 v[114:117], v173 offset:36864
	s_waitcnt lgkmcnt(1)
	v_mfma_f32_32x32x16_bf16 v[16:31], v[88:91], v[92:95], v[16:31]
	v_mfma_f32_32x32x16_bf16 v[0:15], v[88:91], v[106:109], v[0:15]
	v_mfma_f32_32x32x16_bf16 v[48:63], v[98:101], v[102:105], v[48:63]
	v_mfma_f32_32x32x16_bf16 v[32:47], v[98:101], v[110:113], v[32:47]
	s_waitcnt lgkmcnt(0)
	v_mfma_f32_32x32x16_bf16 v[16:31], v[114:117], v[102:105], v[16:31]
	s_waitcnt vmcnt(0)
	s_barrier
	v_lshl_add_u64 v[66:67], v[66:67], 0, s[96:97]
	s_add_u32 m0, s94, 0x8000
	s_nop 1
	global_load_lds_dwordx4 v[66:67], off
	v_lshl_add_u64 v[68:69], v[68:69], 0, s[96:97]
	s_add_u32 m0, s94, 0xc000
	s_nop 1
	global_load_lds_dwordx4 v[68:69], off
	v_lshl_add_u64 v[70:71], v[70:71], 0, s[96:97]
	s_add_u32 m0, s94, 0x9000
	s_nop 1
	global_load_lds_dwordx4 v[70:71], off
	v_lshl_add_u64 v[72:73], v[72:73], 0, s[96:97]
	s_add_u32 m0, s94, 0xd000
	s_nop 1
	global_load_lds_dwordx4 v[72:73], off
	v_lshl_add_u64 v[74:75], v[74:75], 0, s[96:97]
	s_add_u32 m0, s94, 0xa000
	s_nop 1
	global_load_lds_dwordx4 v[74:75], off
	v_lshl_add_u64 v[76:77], v[76:77], 0, s[96:97]
	s_add_u32 m0, s94, 0xe000
	s_nop 1
	global_load_lds_dwordx4 v[76:77], off
	v_lshl_add_u64 v[80:81], v[80:81], 0, s[96:97]
	s_add_u32 m0, s94, 0xb000
	s_nop 1
	global_load_lds_dwordx4 v[80:81], off
	v_lshl_add_u64 v[78:79], v[78:79], 0, s[96:97]
	s_add_u32 m0, s94, 0xf000
	s_nop 1
	global_load_lds_dwordx4 v[78:79], off
	v_mfma_f32_32x32x16_bf16 v[0:15], v[114:117], v[110:113], v[0:15]
	ds_read_b128 v[88:91], v170 offset:0
	ds_read_b128 v[92:95], v174 offset:16384
	ds_read_b128 v[98:101], v171 offset:0
	ds_read_b128 v[102:105], v175 offset:16384
	ds_read_b128 v[106:109], v174 offset:20480
	ds_read_b128 v[110:113], v175 offset:20480
	s_waitcnt lgkmcnt(4)
	v_mfma_f32_32x32x16_bf16 v[48:63], v[88:91], v[92:95], v[48:63]
	s_waitcnt lgkmcnt(1)
	v_mfma_f32_32x32x16_bf16 v[32:47], v[88:91], v[106:109], v[32:47]
	ds_read_b128 v[88:91], v170 offset:4096
	ds_read_b128 v[114:117], v171 offset:4096
	s_waitcnt lgkmcnt(1)
	v_mfma_f32_32x32x16_bf16 v[16:31], v[88:91], v[92:95], v[16:31]
	v_mfma_f32_32x32x16_bf16 v[0:15], v[88:91], v[106:109], v[0:15]
	v_mfma_f32_32x32x16_bf16 v[48:63], v[98:101], v[102:105], v[48:63]
	v_mfma_f32_32x32x16_bf16 v[32:47], v[98:101], v[110:113], v[32:47]
	s_waitcnt lgkmcnt(0)
	v_mfma_f32_32x32x16_bf16 v[16:31], v[114:117], v[102:105], v[16:31]
	ds_read_b128 v[88:91], v172 offset:0
	ds_read_b128 v[92:95], v176 offset:16384
	ds_read_b128 v[98:101], v173 offset:0
	ds_read_b128 v[102:105], v177 offset:16384
	v_mfma_f32_32x32x16_bf16 v[0:15], v[114:117], v[110:113], v[0:15]
	ds_read_b128 v[106:109], v176 offset:20480
	ds_read_b128 v[110:113], v177 offset:20480
	s_waitcnt lgkmcnt(4)
	v_mfma_f32_32x32x16_bf16 v[48:63], v[88:91], v[92:95], v[48:63]
	s_waitcnt lgkmcnt(1)
	v_mfma_f32_32x32x16_bf16 v[32:47], v[88:91], v[106:109], v[32:47]
	ds_read_b128 v[88:91], v172 offset:4096
	ds_read_b128 v[114:117], v173 offset:4096
	s_waitcnt lgkmcnt(1)
	v_mfma_f32_32x32x16_bf16 v[16:31], v[88:91], v[92:95], v[16:31]
	v_mfma_f32_32x32x16_bf16 v[0:15], v[88:91], v[106:109], v[0:15]
	v_mfma_f32_32x32x16_bf16 v[48:63], v[98:101], v[102:105], v[48:63]
	v_mfma_f32_32x32x16_bf16 v[32:47], v[98:101], v[110:113], v[32:47]
	s_waitcnt lgkmcnt(0)
	v_mfma_f32_32x32x16_bf16 v[16:31], v[114:117], v[102:105], v[16:31]
	s_waitcnt vmcnt(0)
	s_barrier
;     ...
;   bf16* As1 = As + 2 * 128 * 72;
;   bf16* Bs1 = As1 + 128 * 72;
;   G_LOAD(ra0, rb0, 0);
;   if (nk > 1) G_LOAD(ra1, rb1, 1);
;   G_STORE(ra0, rb0, As, Bs);
;   __syncthreads();
;   for (int kt = 0; kt < nk; kt += 2) {
;     if (kt + 2 < nk) G_LOAD(ra0, rb0, kt + 2);
;     if (kt + 1 < nk) G_STORE(ra1, rb1, As1, Bs1);
;     G_COMPUTE(As, Bs);
;     __syncthreads();
;     if (kt + 1 < nk) {
;       if (kt + 3 < nk) G_LOAD(ra1, rb1, kt + 3);
;       if (kt + 2 < nk) G_STORE(ra0, rb0, As, Bs);
;       G_COMPUTE(As1, Bs1);
;       __syncthreads();
;     }
;   }
	v_lshl_add_u64 v[66:67], v[66:67], 0, s[96:97]
	s_add_u32 m0, s94, 0x0
	s_nop 1
	global_load_lds_dwordx4 v[66:67], off
	v_lshl_add_u64 v[68:69], v[68:69], 0, s[96:97]
	s_add_u32 m0, s94, 0x4000
	s_nop 1
	global_load_lds_dwordx4 v[68:69], off
	v_lshl_add_u64 v[70:71], v[70:71], 0, s[96:97]
	s_add_u32 m0, s94, 0x1000
	s_nop 1
	global_load_lds_dwordx4 v[70:71], off
	v_lshl_add_u64 v[72:73], v[72:73], 0, s[96:97]
	s_add_u32 m0, s94, 0x5000
	s_nop 1
	global_load_lds_dwordx4 v[72:73], off
	v_lshl_add_u64 v[74:75], v[74:75], 0, s[96:97]
	s_add_u32 m0, s94, 0x2000
	s_nop 1
	global_load_lds_dwordx4 v[74:75], off
	v_lshl_add_u64 v[76:77], v[76:77], 0, s[96:97]
	s_add_u32 m0, s94, 0x6000
	s_nop 1
	global_load_lds_dwordx4 v[76:77], off
	v_lshl_add_u64 v[80:81], v[80:81], 0, s[96:97]
	s_add_u32 m0, s94, 0x3000
	s_nop 1
	global_load_lds_dwordx4 v[80:81], off
	v_lshl_add_u64 v[78:79], v[78:79], 0, s[96:97]
	s_add_u32 m0, s94, 0x7000
	s_nop 1
	global_load_lds_dwordx4 v[78:79], off
	v_mfma_f32_32x32x16_bf16 v[0:15], v[114:117], v[110:113], v[0:15]
	ds_read_b128 v[88:91], v170 offset:32768
	ds_read_b128 v[92:95], v174 offset:49152
	ds_read_b128 v[98:101], v171 offset:32768
	ds_read_b128 v[102:105], v175 offset:49152
	ds_read_b128 v[106:109], v174 offset:53248
	ds_read_b128 v[110:113], v175 offset:53248
	s_waitcnt lgkmcnt(4)
	v_mfma_f32_32x32x16_bf16 v[48:63], v[88:91], v[92:95], v[48:63]
	s_waitcnt lgkmcnt(1)
	v_mfma_f32_32x32x16_bf16 v[32:47], v[88:91], v[106:109], v[32:47]
	ds_read_b128 v[88:91], v170 offset:36864
	ds_read_b128 v[114:117], v171 offset:36864
	s_waitcnt lgkmcnt(1)
	v_mfma_f32_32x32x16_bf16 v[16:31], v[88:91], v[92:95], v[16:31]
	v_mfma_f32_32x32x16_bf16 v[0:15], v[88:91], v[106:109], v[0:15]
	v_mfma_f32_32x32x16_bf16 v[48:63], v[98:101], v[102:105], v[48:63]
	v_mfma_f32_32x32x16_bf16 v[32:47], v[98:101], v[110:113], v[32:47]
	s_waitcnt lgkmcnt(0)
	v_mfma_f32_32x32x16_bf16 v[16:31], v[114:117], v[102:105], v[16:31]
	ds_read_b128 v[88:91], v172 offset:32768
	ds_read_b128 v[92:95], v176 offset:49152
	ds_read_b128 v[98:101], v173 offset:32768
	ds_read_b128 v[102:105], v177 offset:49152
	v_mfma_f32_32x32x16_bf16 v[0:15], v[114:117], v[110:113], v[0:15]
	ds_read_b128 v[106:109], v176 offset:53248
	ds_read_b128 v[110:113], v177 offset:53248
	s_waitcnt lgkmcnt(4)
	v_mfma_f32_32x32x16_bf16 v[48:63], v[88:91], v[92:95], v[48:63]
	s_waitcnt lgkmcnt(1)
	v_mfma_f32_32x32x16_bf16 v[32:47], v[88:91], v[106:109], v[32:47]
	ds_read_b128 v[88:91], v172 offset:36864
	ds_read_b128 v[114:117], v173 offset:36864
	s_waitcnt lgkmcnt(1)
	v_mfma_f32_32x32x16_bf16 v[16:31], v[88:91], v[92:95], v[16:31]
	v_mfma_f32_32x32x16_bf16 v[0:15], v[88:91], v[106:109], v[0:15]
	v_mfma_f32_32x32x16_bf16 v[48:63], v[98:101], v[102:105], v[48:63]
	v_mfma_f32_32x32x16_bf16 v[32:47], v[98:101], v[110:113], v[32:47]
	s_waitcnt lgkmcnt(0)
	v_mfma_f32_32x32x16_bf16 v[16:31], v[114:117], v[102:105], v[16:31]
	s_waitcnt vmcnt(0)
	s_barrier
	v_lshl_add_u64 v[66:67], v[66:67], 0, s[96:97]
	s_add_u32 m0, s94, 0x8000
	s_nop 1
	global_load_lds_dwordx4 v[66:67], off
	v_lshl_add_u64 v[68:69], v[68:69], 0, s[96:97]
	s_add_u32 m0, s94, 0xc000
	s_nop 1
	global_load_lds_dwordx4 v[68:69], off
	v_lshl_add_u64 v[70:71], v[70:71], 0, s[96:97]
	s_add_u32 m0, s94, 0x9000
	s_nop 1
	global_load_lds_dwordx4 v[70:71], off
	v_lshl_add_u64 v[72:73], v[72:73], 0, s[96:97]
	s_add_u32 m0, s94, 0xd000
	s_nop 1
	global_load_lds_dwordx4 v[72:73], off
	v_lshl_add_u64 v[74:75], v[74:75], 0, s[96:97]
	s_add_u32 m0, s94, 0xa000
	s_nop 1
	global_load_lds_dwordx4 v[74:75], off
	v_lshl_add_u64 v[76:77], v[76:77], 0, s[96:97]
	s_add_u32 m0, s94, 0xe000
	s_nop 1
	global_load_lds_dwordx4 v[76:77], off
	v_lshl_add_u64 v[80:81], v[80:81], 0, s[96:97]
	s_add_u32 m0, s94, 0xb000
	s_nop 1
	global_load_lds_dwordx4 v[80:81], off
	v_lshl_add_u64 v[78:79], v[78:79], 0, s[96:97]
	s_add_u32 m0, s94, 0xf000
	s_nop 1
	global_load_lds_dwordx4 v[78:79], off
	v_mfma_f32_32x32x16_bf16 v[0:15], v[114:117], v[110:113], v[0:15]
	ds_read_b128 v[88:91], v170 offset:0
	ds_read_b128 v[92:95], v174 offset:16384
	ds_read_b128 v[98:101], v171 offset:0
	ds_read_b128 v[102:105], v175 offset:16384
	ds_read_b128 v[106:109], v174 offset:20480
	ds_read_b128 v[110:113], v175 offset:20480
	s_waitcnt lgkmcnt(4)
	v_mfma_f32_32x32x16_bf16 v[48:63], v[88:91], v[92:95], v[48:63]
	s_waitcnt lgkmcnt(1)
	v_mfma_f32_32x32x16_bf16 v[32:47], v[88:91], v[106:109], v[32:47]
	ds_read_b128 v[88:91], v170 offset:4096
	ds_read_b128 v[114:117], v171 offset:4096
	s_waitcnt lgkmcnt(1)
	v_mfma_f32_32x32x16_bf16 v[16:31], v[88:91], v[92:95], v[16:31]
	v_mfma_f32_32x32x16_bf16 v[0:15], v[88:91], v[106:109], v[0:15]
	v_mfma_f32_32x32x16_bf16 v[48:63], v[98:101], v[102:105], v[48:63]
	v_mfma_f32_32x32x16_bf16 v[32:47], v[98:101], v[110:113], v[32:47]
	s_waitcnt lgkmcnt(0)
	v_mfma_f32_32x32x16_bf16 v[16:31], v[114:117], v[102:105], v[16:31]
	ds_read_b128 v[88:91], v172 offset:0
	ds_read_b128 v[92:95], v176 offset:16384
	ds_read_b128 v[98:101], v173 offset:0
	ds_read_b128 v[102:105], v177 offset:16384
	v_mfma_f32_32x32x16_bf16 v[0:15], v[114:117], v[110:113], v[0:15]
	ds_read_b128 v[106:109], v176 offset:20480
	ds_read_b128 v[110:113], v177 offset:20480
	s_waitcnt lgkmcnt(4)
	v_mfma_f32_32x32x16_bf16 v[48:63], v[88:91], v[92:95], v[48:63]
	s_waitcnt lgkmcnt(1)
	v_mfma_f32_32x32x16_bf16 v[32:47], v[88:91], v[106:109], v[32:47]
	ds_read_b128 v[88:91], v172 offset:4096
	ds_read_b128 v[114:117], v173 offset:4096
	s_waitcnt lgkmcnt(1)
	v_mfma_f32_32x32x16_bf16 v[16:31], v[88:91], v[92:95], v[16:31]
	v_mfma_f32_32x32x16_bf16 v[0:15], v[88:91], v[106:109], v[0:15]
	v_mfma_f32_32x32x16_bf16 v[48:63], v[98:101], v[102:105], v[48:63]
	v_mfma_f32_32x32x16_bf16 v[32:47], v[98:101], v[110:113], v[32:47]
	s_waitcnt lgkmcnt(0)
	v_mfma_f32_32x32x16_bf16 v[16:31], v[114:117], v[102:105], v[16:31]
	s_waitcnt vmcnt(0)
	s_barrier
;     ...
;   bf16* As1 = As + 2 * 128 * 72;
;   bf16* Bs1 = As1 + 128 * 72;
;   G_LOAD(ra0, rb0, 0);
;   if (nk > 1) G_LOAD(ra1, rb1, 1);
;   G_STORE(ra0, rb0, As, Bs);
;   __syncthreads();
;   for (int kt = 0; kt < nk; kt += 2) {
;     if (kt + 2 < nk) G_LOAD(ra0, rb0, kt + 2);
;     if (kt + 1 < nk) G_STORE(ra1, rb1, As1, Bs1);
;     G_COMPUTE(As, Bs);
;     __syncthreads();
;     if (kt + 1 < nk) {
;       if (kt + 3 < nk) G_LOAD(ra1, rb1, kt + 3);
;       if (kt + 2 < nk) G_STORE(ra0, rb0, As, Bs);
;       G_COMPUTE(As1, Bs1);
;       __syncthreads();
;     }
;   }
	v_lshl_add_u64 v[66:67], v[66:67], 0, s[96:97]
	s_add_u32 m0, s94, 0x0
	s_nop 1
	global_load_lds_dwordx4 v[66:67], off
	v_lshl_add_u64 v[68:69], v[68:69], 0, s[96:97]
	s_add_u32 m0, s94, 0x4000
	s_nop 1
	global_load_lds_dwordx4 v[68:69], off
	v_lshl_add_u64 v[70:71], v[70:71], 0, s[96:97]
	s_add_u32 m0, s94, 0x1000
	s_nop 1
	global_load_lds_dwordx4 v[70:71], off
	v_lshl_add_u64 v[72:73], v[72:73], 0, s[96:97]
	s_add_u32 m0, s94, 0x5000
	s_nop 1
	global_load_lds_dwordx4 v[72:73], off
	v_lshl_add_u64 v[74:75], v[74:75], 0, s[96:97]
	s_add_u32 m0, s94, 0x2000
	s_nop 1
	global_load_lds_dwordx4 v[74:75], off
	v_lshl_add_u64 v[76:77], v[76:77], 0, s[96:97]
	s_add_u32 m0, s94, 0x6000
	s_nop 1
	global_load_lds_dwordx4 v[76:77], off
	v_lshl_add_u64 v[80:81], v[80:81], 0, s[96:97]
	s_add_u32 m0, s94, 0x3000
	s_nop 1
	global_load_lds_dwordx4 v[80:81], off
	v_lshl_add_u64 v[78:79], v[78:79], 0, s[96:97]
	s_add_u32 m0, s94, 0x7000
	s_nop 1
	global_load_lds_dwordx4 v[78:79], off
	v_mfma_f32_32x32x16_bf16 v[0:15], v[114:117], v[110:113], v[0:15]
	ds_read_b128 v[88:91], v170 offset:32768
	ds_read_b128 v[92:95], v174 offset:49152
	ds_read_b128 v[98:101], v171 offset:32768
	ds_read_b128 v[102:105], v175 offset:49152
	ds_read_b128 v[106:109], v174 offset:53248
	ds_read_b128 v[110:113], v175 offset:53248
	s_waitcnt lgkmcnt(4)
	v_mfma_f32_32x32x16_bf16 v[48:63], v[88:91], v[92:95], v[48:63]
	s_waitcnt lgkmcnt(1)
	v_mfma_f32_32x32x16_bf16 v[32:47], v[88:91], v[106:109], v[32:47]
	ds_read_b128 v[88:91], v170 offset:36864
	ds_read_b128 v[114:117], v171 offset:36864
	s_waitcnt lgkmcnt(1)
	v_mfma_f32_32x32x16_bf16 v[16:31], v[88:91], v[92:95], v[16:31]
	v_mfma_f32_32x32x16_bf16 v[0:15], v[88:91], v[106:109], v[0:15]
	v_mfma_f32_32x32x16_bf16 v[48:63], v[98:101], v[102:105], v[48:63]
	v_mfma_f32_32x32x16_bf16 v[32:47], v[98:101], v[110:113], v[32:47]
	s_waitcnt lgkmcnt(0)
	v_mfma_f32_32x32x16_bf16 v[16:31], v[114:117], v[102:105], v[16:31]
	ds_read_b128 v[88:91], v172 offset:32768
	ds_read_b128 v[92:95], v176 offset:49152
	ds_read_b128 v[98:101], v173 offset:32768
	ds_read_b128 v[102:105], v177 offset:49152
	v_mfma_f32_32x32x16_bf16 v[0:15], v[114:117], v[110:113], v[0:15]
	ds_read_b128 v[106:109], v176 offset:53248
	ds_read_b128 v[110:113], v177 offset:53248
	s_waitcnt lgkmcnt(4)
	v_mfma_f32_32x32x16_bf16 v[48:63], v[88:91], v[92:95], v[48:63]
	s_waitcnt lgkmcnt(1)
	v_mfma_f32_32x32x16_bf16 v[32:47], v[88:91], v[106:109], v[32:47]
	ds_read_b128 v[88:91], v172 offset:36864
	ds_read_b128 v[114:117], v173 offset:36864
	s_waitcnt lgkmcnt(1)
	v_mfma_f32_32x32x16_bf16 v[16:31], v[88:91], v[92:95], v[16:31]
	v_mfma_f32_32x32x16_bf16 v[0:15], v[88:91], v[106:109], v[0:15]
	v_mfma_f32_32x32x16_bf16 v[48:63], v[98:101], v[102:105], v[48:63]
	v_mfma_f32_32x32x16_bf16 v[32:47], v[98:101], v[110:113], v[32:47]
	s_waitcnt lgkmcnt(0)
	v_mfma_f32_32x32x16_bf16 v[16:31], v[114:117], v[102:105], v[16:31]
	s_waitcnt vmcnt(0)
	s_barrier
	v_lshl_add_u64 v[66:67], v[66:67], 0, s[96:97]
	s_add_u32 m0, s94, 0x8000
	s_nop 1
	global_load_lds_dwordx4 v[66:67], off
	v_lshl_add_u64 v[68:69], v[68:69], 0, s[96:97]
	s_add_u32 m0, s94, 0xc000
	s_nop 1
	global_load_lds_dwordx4 v[68:69], off
	v_lshl_add_u64 v[70:71], v[70:71], 0, s[96:97]
	s_add_u32 m0, s94, 0x9000
	s_nop 1
	global_load_lds_dwordx4 v[70:71], off
	v_lshl_add_u64 v[72:73], v[72:73], 0, s[96:97]
	s_add_u32 m0, s94, 0xd000
	s_nop 1
	global_load_lds_dwordx4 v[72:73], off
	v_lshl_add_u64 v[74:75], v[74:75], 0, s[96:97]
	s_add_u32 m0, s94, 0xa000
	s_nop 1
	global_load_lds_dwordx4 v[74:75], off
	v_lshl_add_u64 v[76:77], v[76:77], 0, s[96:97]
	s_add_u32 m0, s94, 0xe000
	s_nop 1
	global_load_lds_dwordx4 v[76:77], off
	v_lshl_add_u64 v[80:81], v[80:81], 0, s[96:97]
	s_add_u32 m0, s94, 0xb000
	s_nop 1
	global_load_lds_dwordx4 v[80:81], off
	v_lshl_add_u64 v[78:79], v[78:79], 0, s[96:97]
	s_add_u32 m0, s94, 0xf000
	s_nop 1
	global_load_lds_dwordx4 v[78:79], off
	v_mfma_f32_32x32x16_bf16 v[0:15], v[114:117], v[110:113], v[0:15]
	ds_read_b128 v[88:91], v170 offset:0
	ds_read_b128 v[92:95], v174 offset:16384
	ds_read_b128 v[98:101], v171 offset:0
	ds_read_b128 v[102:105], v175 offset:16384
	ds_read_b128 v[106:109], v174 offset:20480
	ds_read_b128 v[110:113], v175 offset:20480
	s_waitcnt lgkmcnt(4)
	v_mfma_f32_32x32x16_bf16 v[48:63], v[88:91], v[92:95], v[48:63]
	s_waitcnt lgkmcnt(1)
	v_mfma_f32_32x32x16_bf16 v[32:47], v[88:91], v[106:109], v[32:47]
	ds_read_b128 v[88:91], v170 offset:4096
	ds_read_b128 v[114:117], v171 offset:4096
	s_waitcnt lgkmcnt(1)
	v_mfma_f32_32x32x16_bf16 v[16:31], v[88:91], v[92:95], v[16:31]
	v_mfma_f32_32x32x16_bf16 v[0:15], v[88:91], v[106:109], v[0:15]
	v_mfma_f32_32x32x16_bf16 v[48:63], v[98:101], v[102:105], v[48:63]
	v_mfma_f32_32x32x16_bf16 v[32:47], v[98:101], v[110:113], v[32:47]
	s_waitcnt lgkmcnt(0)
	v_mfma_f32_32x32x16_bf16 v[16:31], v[114:117], v[102:105], v[16:31]
	ds_read_b128 v[88:91], v172 offset:0
	ds_read_b128 v[92:95], v176 offset:16384
	ds_read_b128 v[98:101], v173 offset:0
	ds_read_b128 v[102:105], v177 offset:16384
	v_mfma_f32_32x32x16_bf16 v[0:15], v[114:117], v[110:113], v[0:15]
	ds_read_b128 v[106:109], v176 offset:20480
	ds_read_b128 v[110:113], v177 offset:20480
	s_waitcnt lgkmcnt(4)
	v_mfma_f32_32x32x16_bf16 v[48:63], v[88:91], v[92:95], v[48:63]
	s_waitcnt lgkmcnt(1)
	v_mfma_f32_32x32x16_bf16 v[32:47], v[88:91], v[106:109], v[32:47]
	ds_read_b128 v[88:91], v172 offset:4096
	ds_read_b128 v[114:117], v173 offset:4096
	s_waitcnt lgkmcnt(1)
	v_mfma_f32_32x32x16_bf16 v[16:31], v[88:91], v[92:95], v[16:31]
	v_mfma_f32_32x32x16_bf16 v[0:15], v[88:91], v[106:109], v[0:15]
	v_mfma_f32_32x32x16_bf16 v[48:63], v[98:101], v[102:105], v[48:63]
	v_mfma_f32_32x32x16_bf16 v[32:47], v[98:101], v[110:113], v[32:47]
	s_waitcnt lgkmcnt(0)
	v_mfma_f32_32x32x16_bf16 v[16:31], v[114:117], v[102:105], v[16:31]
	s_waitcnt vmcnt(0)
	s_barrier
;     ...
;   bf16* As1 = As + 2 * 128 * 72;
;   bf16* Bs1 = As1 + 128 * 72;
;   G_LOAD(ra0, rb0, 0);
;   if (nk > 1) G_LOAD(ra1, rb1, 1);
;   G_STORE(ra0, rb0, As, Bs);
;   __syncthreads();
;   for (int kt = 0; kt < nk; kt += 2) {
;     if (kt + 2 < nk) G_LOAD(ra0, rb0, kt + 2);
;     if (kt + 1 < nk) G_STORE(ra1, rb1, As1, Bs1);
;     G_COMPUTE(As, Bs);
;     __syncthreads();
;     if (kt + 1 < nk) {
;       if (kt + 3 < nk) G_LOAD(ra1, rb1, kt + 3);
;       if (kt + 2 < nk) G_STORE(ra0, rb0, As, Bs);
;       G_COMPUTE(As1, Bs1);
;       __syncthreads();
;     }
;   }
	v_lshl_add_u64 v[66:67], v[66:67], 0, s[96:97]
	s_add_u32 m0, s94, 0x0
	s_nop 1
	global_load_lds_dwordx4 v[66:67], off
	v_lshl_add_u64 v[68:69], v[68:69], 0, s[96:97]
	s_add_u32 m0, s94, 0x4000
	s_nop 1
	global_load_lds_dwordx4 v[68:69], off
	v_lshl_add_u64 v[70:71], v[70:71], 0, s[96:97]
	s_add_u32 m0, s94, 0x1000
	s_nop 1
	global_load_lds_dwordx4 v[70:71], off
	v_lshl_add_u64 v[72:73], v[72:73], 0, s[96:97]
	s_add_u32 m0, s94, 0x5000
	s_nop 1
	global_load_lds_dwordx4 v[72:73], off
	v_lshl_add_u64 v[74:75], v[74:75], 0, s[96:97]
	s_add_u32 m0, s94, 0x2000
	s_nop 1
	global_load_lds_dwordx4 v[74:75], off
	v_lshl_add_u64 v[76:77], v[76:77], 0, s[96:97]
	s_add_u32 m0, s94, 0x6000
	s_nop 1
	global_load_lds_dwordx4 v[76:77], off
	v_lshl_add_u64 v[80:81], v[80:81], 0, s[96:97]
	s_add_u32 m0, s94, 0x3000
	s_nop 1
	global_load_lds_dwordx4 v[80:81], off
	v_lshl_add_u64 v[78:79], v[78:79], 0, s[96:97]
	s_add_u32 m0, s94, 0x7000
	s_nop 1
	global_load_lds_dwordx4 v[78:79], off
	v_mfma_f32_32x32x16_bf16 v[0:15], v[114:117], v[110:113], v[0:15]
	ds_read_b128 v[88:91], v170 offset:32768
	ds_read_b128 v[92:95], v174 offset:49152
	ds_read_b128 v[98:101], v171 offset:32768
	ds_read_b128 v[102:105], v175 offset:49152
	ds_read_b128 v[106:109], v174 offset:53248
	ds_read_b128 v[110:113], v175 offset:53248
	s_waitcnt lgkmcnt(4)
	v_mfma_f32_32x32x16_bf16 v[48:63], v[88:91], v[92:95], v[48:63]
	s_waitcnt lgkmcnt(1)
	v_mfma_f32_32x32x16_bf16 v[32:47], v[88:91], v[106:109], v[32:47]
	ds_read_b128 v[88:91], v170 offset:36864
	ds_read_b128 v[114:117], v171 offset:36864
	s_waitcnt lgkmcnt(1)
	v_mfma_f32_32x32x16_bf16 v[16:31], v[88:91], v[92:95], v[16:31]
	v_mfma_f32_32x32x16_bf16 v[0:15], v[88:91], v[106:109], v[0:15]
	v_mfma_f32_32x32x16_bf16 v[48:63], v[98:101], v[102:105], v[48:63]
	v_mfma_f32_32x32x16_bf16 v[32:47], v[98:101], v[110:113], v[32:47]
	s_waitcnt lgkmcnt(0)
	v_mfma_f32_32x32x16_bf16 v[16:31], v[114:117], v[102:105], v[16:31]
	ds_read_b128 v[88:91], v172 offset:32768
	ds_read_b128 v[92:95], v176 offset:49152
	ds_read_b128 v[98:101], v173 offset:32768
	ds_read_b128 v[102:105], v177 offset:49152
	v_mfma_f32_32x32x16_bf16 v[0:15], v[114:117], v[110:113], v[0:15]
	ds_read_b128 v[106:109], v176 offset:53248
	ds_read_b128 v[110:113], v177 offset:53248
	s_waitcnt lgkmcnt(4)
	v_mfma_f32_32x32x16_bf16 v[48:63], v[88:91], v[92:95], v[48:63]
	s_waitcnt lgkmcnt(1)
	v_mfma_f32_32x32x16_bf16 v[32:47], v[88:91], v[106:109], v[32:47]
	ds_read_b128 v[88:91], v172 offset:36864
	ds_read_b128 v[114:117], v173 offset:36864
	s_waitcnt lgkmcnt(1)
	v_mfma_f32_32x32x16_bf16 v[16:31], v[88:91], v[92:95], v[16:31]
	v_mfma_f32_32x32x16_bf16 v[0:15], v[88:91], v[106:109], v[0:15]
	v_mfma_f32_32x32x16_bf16 v[48:63], v[98:101], v[102:105], v[48:63]
	v_mfma_f32_32x32x16_bf16 v[32:47], v[98:101], v[110:113], v[32:47]
	s_waitcnt lgkmcnt(0)
	v_mfma_f32_32x32x16_bf16 v[16:31], v[114:117], v[102:105], v[16:31]
	s_waitcnt vmcnt(0)
	s_barrier
	v_lshl_add_u64 v[66:67], v[66:67], 0, s[96:97]
	s_add_u32 m0, s94, 0x8000
	s_nop 1
	global_load_lds_dwordx4 v[66:67], off
	v_lshl_add_u64 v[68:69], v[68:69], 0, s[96:97]
	s_add_u32 m0, s94, 0xc000
	s_nop 1
	global_load_lds_dwordx4 v[68:69], off
	v_lshl_add_u64 v[70:71], v[70:71], 0, s[96:97]
	s_add_u32 m0, s94, 0x9000
	s_nop 1
	global_load_lds_dwordx4 v[70:71], off
	v_lshl_add_u64 v[72:73], v[72:73], 0, s[96:97]
	s_add_u32 m0, s94, 0xd000
	s_nop 1
	global_load_lds_dwordx4 v[72:73], off
	v_lshl_add_u64 v[74:75], v[74:75], 0, s[96:97]
	s_add_u32 m0, s94, 0xa000
	s_nop 1
	global_load_lds_dwordx4 v[74:75], off
	v_lshl_add_u64 v[76:77], v[76:77], 0, s[96:97]
	s_add_u32 m0, s94, 0xe000
	s_nop 1
	global_load_lds_dwordx4 v[76:77], off
	v_lshl_add_u64 v[80:81], v[80:81], 0, s[96:97]
	s_add_u32 m0, s94, 0xb000
	s_nop 1
	global_load_lds_dwordx4 v[80:81], off
	v_lshl_add_u64 v[78:79], v[78:79], 0, s[96:97]
	s_add_u32 m0, s94, 0xf000
	s_nop 1
	global_load_lds_dwordx4 v[78:79], off
	v_mfma_f32_32x32x16_bf16 v[0:15], v[114:117], v[110:113], v[0:15]
	ds_read_b128 v[88:91], v170 offset:0
	ds_read_b128 v[92:95], v174 offset:16384
	ds_read_b128 v[98:101], v171 offset:0
	ds_read_b128 v[102:105], v175 offset:16384
	ds_read_b128 v[106:109], v174 offset:20480
	ds_read_b128 v[110:113], v175 offset:20480
	s_waitcnt lgkmcnt(4)
	v_mfma_f32_32x32x16_bf16 v[48:63], v[88:91], v[92:95], v[48:63]
	s_waitcnt lgkmcnt(1)
	v_mfma_f32_32x32x16_bf16 v[32:47], v[88:91], v[106:109], v[32:47]
	ds_read_b128 v[88:91], v170 offset:4096
	ds_read_b128 v[114:117], v171 offset:4096
	s_waitcnt lgkmcnt(1)
	v_mfma_f32_32x32x16_bf16 v[16:31], v[88:91], v[92:95], v[16:31]
	v_mfma_f32_32x32x16_bf16 v[0:15], v[88:91], v[106:109], v[0:15]
	v_mfma_f32_32x32x16_bf16 v[48:63], v[98:101], v[102:105], v[48:63]
	v_mfma_f32_32x32x16_bf16 v[32:47], v[98:101], v[110:113], v[32:47]
	s_waitcnt lgkmcnt(0)
	v_mfma_f32_32x32x16_bf16 v[16:31], v[114:117], v[102:105], v[16:31]
	ds_read_b128 v[88:91], v172 offset:0
	ds_read_b128 v[92:95], v176 offset:16384
	ds_read_b128 v[98:101], v173 offset:0
	ds_read_b128 v[102:105], v177 offset:16384
	v_mfma_f32_32x32x16_bf16 v[0:15], v[114:117], v[110:113], v[0:15]
	ds_read_b128 v[106:109], v176 offset:20480
	ds_read_b128 v[110:113], v177 offset:20480
	s_waitcnt lgkmcnt(4)
	v_mfma_f32_32x32x16_bf16 v[48:63], v[88:91], v[92:95], v[48:63]
	s_waitcnt lgkmcnt(1)
	v_mfma_f32_32x32x16_bf16 v[32:47], v[88:91], v[106:109], v[32:47]
	ds_read_b128 v[88:91], v172 offset:4096
	ds_read_b128 v[114:117], v173 offset:4096
	s_waitcnt lgkmcnt(1)
	v_mfma_f32_32x32x16_bf16 v[16:31], v[88:91], v[92:95], v[16:31]
	v_mfma_f32_32x32x16_bf16 v[0:15], v[88:91], v[106:109], v[0:15]
	v_mfma_f32_32x32x16_bf16 v[48:63], v[98:101], v[102:105], v[48:63]
	v_mfma_f32_32x32x16_bf16 v[32:47], v[98:101], v[110:113], v[32:47]
	s_waitcnt lgkmcnt(0)
	v_mfma_f32_32x32x16_bf16 v[16:31], v[114:117], v[102:105], v[16:31]
	s_waitcnt vmcnt(0)
	s_barrier
;     ...
;   bf16* As1 = As + 2 * 128 * 72;
;   bf16* Bs1 = As1 + 128 * 72;
;   G_LOAD(ra0, rb0, 0);
;   if (nk > 1) G_LOAD(ra1, rb1, 1);
;   G_STORE(ra0, rb0, As, Bs);
;   __syncthreads();
;   for (int kt = 0; kt < nk; kt += 2) {
;     if (kt + 2 < nk) G_LOAD(ra0, rb0, kt + 2);
;     if (kt + 1 < nk) G_STORE(ra1, rb1, As1, Bs1);
;     G_COMPUTE(As, Bs);
;     __syncthreads();
;     if (kt + 1 < nk) {
;       if (kt + 3 < nk) G_LOAD(ra1, rb1, kt + 3);
;       if (kt + 2 < nk) G_STORE(ra0, rb0, As, Bs);
;       G_COMPUTE(As1, Bs1);
;       __syncthreads();
;     }
;   }
	v_lshl_add_u64 v[66:67], v[66:67], 0, s[96:97]
	s_add_u32 m0, s94, 0x0
	s_nop 1
	global_load_lds_dwordx4 v[66:67], off
	v_lshl_add_u64 v[68:69], v[68:69], 0, s[96:97]
	s_add_u32 m0, s94, 0x4000
	s_nop 1
	global_load_lds_dwordx4 v[68:69], off
	v_lshl_add_u64 v[70:71], v[70:71], 0, s[96:97]
	s_add_u32 m0, s94, 0x1000
	s_nop 1
	global_load_lds_dwordx4 v[70:71], off
	v_lshl_add_u64 v[72:73], v[72:73], 0, s[96:97]
	s_add_u32 m0, s94, 0x5000
	s_nop 1
	global_load_lds_dwordx4 v[72:73], off
	v_lshl_add_u64 v[74:75], v[74:75], 0, s[96:97]
	s_add_u32 m0, s94, 0x2000
	s_nop 1
	global_load_lds_dwordx4 v[74:75], off
	v_lshl_add_u64 v[76:77], v[76:77], 0, s[96:97]
	s_add_u32 m0, s94, 0x6000
	s_nop 1
	global_load_lds_dwordx4 v[76:77], off
	v_lshl_add_u64 v[80:81], v[80:81], 0, s[96:97]
	s_add_u32 m0, s94, 0x3000
	s_nop 1
	global_load_lds_dwordx4 v[80:81], off
	v_lshl_add_u64 v[78:79], v[78:79], 0, s[96:97]
	s_add_u32 m0, s94, 0x7000
	s_nop 1
	global_load_lds_dwordx4 v[78:79], off
	v_mfma_f32_32x32x16_bf16 v[0:15], v[114:117], v[110:113], v[0:15]
	ds_read_b128 v[88:91], v170 offset:32768
	ds_read_b128 v[92:95], v174 offset:49152
	ds_read_b128 v[98:101], v171 offset:32768
	ds_read_b128 v[102:105], v175 offset:49152
	ds_read_b128 v[106:109], v174 offset:53248
	ds_read_b128 v[110:113], v175 offset:53248
	s_waitcnt lgkmcnt(4)
	v_mfma_f32_32x32x16_bf16 v[48:63], v[88:91], v[92:95], v[48:63]
	s_waitcnt lgkmcnt(1)
	v_mfma_f32_32x32x16_bf16 v[32:47], v[88:91], v[106:109], v[32:47]
	ds_read_b128 v[88:91], v170 offset:36864
	ds_read_b128 v[114:117], v171 offset:36864
	s_waitcnt lgkmcnt(1)
	v_mfma_f32_32x32x16_bf16 v[16:31], v[88:91], v[92:95], v[16:31]
	v_mfma_f32_32x32x16_bf16 v[0:15], v[88:91], v[106:109], v[0:15]
	v_mfma_f32_32x32x16_bf16 v[48:63], v[98:101], v[102:105], v[48:63]
	v_mfma_f32_32x32x16_bf16 v[32:47], v[98:101], v[110:113], v[32:47]
	s_waitcnt lgkmcnt(0)
	v_mfma_f32_32x32x16_bf16 v[16:31], v[114:117], v[102:105], v[16:31]
	ds_read_b128 v[88:91], v172 offset:32768
	ds_read_b128 v[92:95], v176 offset:49152
	ds_read_b128 v[98:101], v173 offset:32768
	ds_read_b128 v[102:105], v177 offset:49152
	v_mfma_f32_32x32x16_bf16 v[0:15], v[114:117], v[110:113], v[0:15]
	ds_read_b128 v[106:109], v176 offset:53248
	ds_read_b128 v[110:113], v177 offset:53248
	s_waitcnt lgkmcnt(4)
	v_mfma_f32_32x32x16_bf16 v[48:63], v[88:91], v[92:95], v[48:63]
	s_waitcnt lgkmcnt(1)
	v_mfma_f32_32x32x16_bf16 v[32:47], v[88:91], v[106:109], v[32:47]
	ds_read_b128 v[88:91], v172 offset:36864
	ds_read_b128 v[114:117], v173 offset:36864
	s_waitcnt lgkmcnt(1)
	v_mfma_f32_32x32x16_bf16 v[16:31], v[88:91], v[92:95], v[16:31]
	v_mfma_f32_32x32x16_bf16 v[0:15], v[88:91], v[106:109], v[0:15]
	v_mfma_f32_32x32x16_bf16 v[48:63], v[98:101], v[102:105], v[48:63]
	v_mfma_f32_32x32x16_bf16 v[32:47], v[98:101], v[110:113], v[32:47]
	s_waitcnt lgkmcnt(0)
	v_mfma_f32_32x32x16_bf16 v[16:31], v[114:117], v[102:105], v[16:31]
	s_waitcnt vmcnt(0)
	s_barrier
	v_lshl_add_u64 v[66:67], v[66:67], 0, s[96:97]
	s_add_u32 m0, s94, 0x8000
	s_nop 1
	global_load_lds_dwordx4 v[66:67], off
	v_lshl_add_u64 v[68:69], v[68:69], 0, s[96:97]
	s_add_u32 m0, s94, 0xc000
	s_nop 1
	global_load_lds_dwordx4 v[68:69], off
	v_lshl_add_u64 v[70:71], v[70:71], 0, s[96:97]
	s_add_u32 m0, s94, 0x9000
	s_nop 1
	global_load_lds_dwordx4 v[70:71], off
	v_lshl_add_u64 v[72:73], v[72:73], 0, s[96:97]
	s_add_u32 m0, s94, 0xd000
	s_nop 1
	global_load_lds_dwordx4 v[72:73], off
	v_lshl_add_u64 v[74:75], v[74:75], 0, s[96:97]
	s_add_u32 m0, s94, 0xa000
	s_nop 1
	global_load_lds_dwordx4 v[74:75], off
	v_lshl_add_u64 v[76:77], v[76:77], 0, s[96:97]
	s_add_u32 m0, s94, 0xe000
	s_nop 1
	global_load_lds_dwordx4 v[76:77], off
	v_lshl_add_u64 v[80:81], v[80:81], 0, s[96:97]
	s_add_u32 m0, s94, 0xb000
	s_nop 1
	global_load_lds_dwordx4 v[80:81], off
	v_lshl_add_u64 v[78:79], v[78:79], 0, s[96:97]
	s_add_u32 m0, s94, 0xf000
	s_nop 1
	global_load_lds_dwordx4 v[78:79], off
	v_mfma_f32_32x32x16_bf16 v[0:15], v[114:117], v[110:113], v[0:15]
	ds_read_b128 v[88:91], v170 offset:0
	ds_read_b128 v[92:95], v174 offset:16384
	ds_read_b128 v[98:101], v171 offset:0
	ds_read_b128 v[102:105], v175 offset:16384
	ds_read_b128 v[106:109], v174 offset:20480
	ds_read_b128 v[110:113], v175 offset:20480
	s_waitcnt lgkmcnt(4)
	v_mfma_f32_32x32x16_bf16 v[48:63], v[88:91], v[92:95], v[48:63]
	s_waitcnt lgkmcnt(1)
	v_mfma_f32_32x32x16_bf16 v[32:47], v[88:91], v[106:109], v[32:47]
	ds_read_b128 v[88:91], v170 offset:4096
	ds_read_b128 v[114:117], v171 offset:4096
	s_waitcnt lgkmcnt(1)
	v_mfma_f32_32x32x16_bf16 v[16:31], v[88:91], v[92:95], v[16:31]
	v_mfma_f32_32x32x16_bf16 v[0:15], v[88:91], v[106:109], v[0:15]
	v_mfma_f32_32x32x16_bf16 v[48:63], v[98:101], v[102:105], v[48:63]
	v_mfma_f32_32x32x16_bf16 v[32:47], v[98:101], v[110:113], v[32:47]
	s_waitcnt lgkmcnt(0)
	v_mfma_f32_32x32x16_bf16 v[16:31], v[114:117], v[102:105], v[16:31]
	ds_read_b128 v[88:91], v172 offset:0
	ds_read_b128 v[92:95], v176 offset:16384
	ds_read_b128 v[98:101], v173 offset:0
	ds_read_b128 v[102:105], v177 offset:16384
	v_mfma_f32_32x32x16_bf16 v[0:15], v[114:117], v[110:113], v[0:15]
	ds_read_b128 v[106:109], v176 offset:20480
	ds_read_b128 v[110:113], v177 offset:20480
	s_waitcnt lgkmcnt(4)
	v_mfma_f32_32x32x16_bf16 v[48:63], v[88:91], v[92:95], v[48:63]
	s_waitcnt lgkmcnt(1)
	v_mfma_f32_32x32x16_bf16 v[32:47], v[88:91], v[106:109], v[32:47]
	ds_read_b128 v[88:91], v172 offset:4096
	ds_read_b128 v[114:117], v173 offset:4096
	s_waitcnt lgkmcnt(1)
	v_mfma_f32_32x32x16_bf16 v[16:31], v[88:91], v[92:95], v[16:31]
	v_mfma_f32_32x32x16_bf16 v[0:15], v[88:91], v[106:109], v[0:15]
	v_mfma_f32_32x32x16_bf16 v[48:63], v[98:101], v[102:105], v[48:63]
	v_mfma_f32_32x32x16_bf16 v[32:47], v[98:101], v[110:113], v[32:47]
	s_waitcnt lgkmcnt(0)
	v_mfma_f32_32x32x16_bf16 v[16:31], v[114:117], v[102:105], v[16:31]
	s_waitcnt vmcnt(0)
	s_barrier
;     ...
;   bf16* As1 = As + 2 * 128 * 72;
;   bf16* Bs1 = As1 + 128 * 72;
;   G_LOAD(ra0, rb0, 0);
;   if (nk > 1) G_LOAD(ra1, rb1, 1);
;   G_STORE(ra0, rb0, As, Bs);
;   __syncthreads();
;   for (int kt = 0; kt < nk; kt += 2) {
;     if (kt + 2 < nk) G_LOAD(ra0, rb0, kt + 2);
;     if (kt + 1 < nk) G_STORE(ra1, rb1, As1, Bs1);
;     G_COMPUTE(As, Bs);
;     __syncthreads();
;     if (kt + 1 < nk) {
;       if (kt + 3 < nk) G_LOAD(ra1, rb1, kt + 3);
;       if (kt + 2 < nk) G_STORE(ra0, rb0, As, Bs);
;       G_COMPUTE(As1, Bs1);
;       __syncthreads();
;     }
;   }
	v_lshl_add_u64 v[66:67], v[66:67], 0, s[96:97]
	s_add_u32 m0, s94, 0x0
	s_nop 1
	global_load_lds_dwordx4 v[66:67], off
	v_lshl_add_u64 v[68:69], v[68:69], 0, s[96:97]
	s_add_u32 m0, s94, 0x4000
	s_nop 1
	global_load_lds_dwordx4 v[68:69], off
	v_lshl_add_u64 v[70:71], v[70:71], 0, s[96:97]
	s_add_u32 m0, s94, 0x1000
	s_nop 1
	global_load_lds_dwordx4 v[70:71], off
	v_lshl_add_u64 v[72:73], v[72:73], 0, s[96:97]
	s_add_u32 m0, s94, 0x5000
	s_nop 1
	global_load_lds_dwordx4 v[72:73], off
	v_lshl_add_u64 v[74:75], v[74:75], 0, s[96:97]
	s_add_u32 m0, s94, 0x2000
	s_nop 1
	global_load_lds_dwordx4 v[74:75], off
	v_lshl_add_u64 v[76:77], v[76:77], 0, s[96:97]
	s_add_u32 m0, s94, 0x6000
	s_nop 1
	global_load_lds_dwordx4 v[76:77], off
	v_lshl_add_u64 v[80:81], v[80:81], 0, s[96:97]
	s_add_u32 m0, s94, 0x3000
	s_nop 1
	global_load_lds_dwordx4 v[80:81], off
	v_lshl_add_u64 v[78:79], v[78:79], 0, s[96:97]
	s_add_u32 m0, s94, 0x7000
	s_nop 1
	global_load_lds_dwordx4 v[78:79], off
	v_mfma_f32_32x32x16_bf16 v[0:15], v[114:117], v[110:113], v[0:15]
	ds_read_b128 v[88:91], v170 offset:32768
	ds_read_b128 v[92:95], v174 offset:49152
	ds_read_b128 v[98:101], v171 offset:32768
	ds_read_b128 v[102:105], v175 offset:49152
	ds_read_b128 v[106:109], v174 offset:53248
	ds_read_b128 v[110:113], v175 offset:53248
	s_waitcnt lgkmcnt(4)
	v_mfma_f32_32x32x16_bf16 v[48:63], v[88:91], v[92:95], v[48:63]
	s_waitcnt lgkmcnt(1)
	v_mfma_f32_32x32x16_bf16 v[32:47], v[88:91], v[106:109], v[32:47]
	ds_read_b128 v[88:91], v170 offset:36864
	ds_read_b128 v[114:117], v171 offset:36864
	s_waitcnt lgkmcnt(1)
	v_mfma_f32_32x32x16_bf16 v[16:31], v[88:91], v[92:95], v[16:31]
	v_mfma_f32_32x32x16_bf16 v[0:15], v[88:91], v[106:109], v[0:15]
	v_mfma_f32_32x32x16_bf16 v[48:63], v[98:101], v[102:105], v[48:63]
	v_mfma_f32_32x32x16_bf16 v[32:47], v[98:101], v[110:113], v[32:47]
	s_waitcnt lgkmcnt(0)
	v_mfma_f32_32x32x16_bf16 v[16:31], v[114:117], v[102:105], v[16:31]
	ds_read_b128 v[88:91], v172 offset:32768
	ds_read_b128 v[92:95], v176 offset:49152
	ds_read_b128 v[98:101], v173 offset:32768
	ds_read_b128 v[102:105], v177 offset:49152
	v_mfma_f32_32x32x16_bf16 v[0:15], v[114:117], v[110:113], v[0:15]
	ds_read_b128 v[106:109], v176 offset:53248
	ds_read_b128 v[110:113], v177 offset:53248
	s_waitcnt lgkmcnt(4)
	v_mfma_f32_32x32x16_bf16 v[48:63], v[88:91], v[92:95], v[48:63]
	s_waitcnt lgkmcnt(1)
	v_mfma_f32_32x32x16_bf16 v[32:47], v[88:91], v[106:109], v[32:47]
	ds_read_b128 v[88:91], v172 offset:36864
	ds_read_b128 v[114:117], v173 offset:36864
	s_waitcnt lgkmcnt(1)
	v_mfma_f32_32x32x16_bf16 v[16:31], v[88:91], v[92:95], v[16:31]
	v_mfma_f32_32x32x16_bf16 v[0:15], v[88:91], v[106:109], v[0:15]
	v_mfma_f32_32x32x16_bf16 v[48:63], v[98:101], v[102:105], v[48:63]
	v_mfma_f32_32x32x16_bf16 v[32:47], v[98:101], v[110:113], v[32:47]
	s_nop 0
	s_nop 0
	s_nop 0
	s_nop 0
	s_nop 0
	s_nop 0
	s_nop 0
	s_waitcnt lgkmcnt(0)
	s_waitcnt vmcnt(0)
	s_barrier
	v_lshl_add_u64 v[66:67], v[66:67], 0, s[96:97]
	s_add_u32 m0, s94, 0x8000
	s_nop 1
	global_load_lds_dwordx4 v[66:67], off
	v_lshl_add_u64 v[68:69], v[68:69], 0, s[96:97]
	s_add_u32 m0, s94, 0xc000
	s_nop 1
	global_load_lds_dwordx4 v[68:69], off
	v_lshl_add_u64 v[70:71], v[70:71], 0, s[96:97]
	s_add_u32 m0, s94, 0x9000
	s_nop 1
	global_load_lds_dwordx4 v[70:71], off
	v_lshl_add_u64 v[72:73], v[72:73], 0, s[96:97]
	s_add_u32 m0, s94, 0xd000
	s_nop 1
	global_load_lds_dwordx4 v[72:73], off
	v_lshl_add_u64 v[74:75], v[74:75], 0, s[96:97]
	s_add_u32 m0, s94, 0xa000
	s_nop 1
	global_load_lds_dwordx4 v[74:75], off
	v_lshl_add_u64 v[76:77], v[76:77], 0, s[96:97]
	s_add_u32 m0, s94, 0xe000
	s_nop 1
	global_load_lds_dwordx4 v[76:77], off
	v_lshl_add_u64 v[80:81], v[80:81], 0, s[96:97]
	s_add_u32 m0, s94, 0xb000
	s_nop 1
	global_load_lds_dwordx4 v[80:81], off
	v_lshl_add_u64 v[78:79], v[78:79], 0, s[96:97]
	s_add_u32 m0, s94, 0xf000
	s_nop 1
	global_load_lds_dwordx4 v[78:79], off
	v_mfma_f32_32x32x16_bf16 v[16:31], v[114:117], v[102:105], v[16:31]
	ds_read_b128 v[66:69], v170 offset:0
	ds_read_b128 v[70:73], v174 offset:16384
	ds_read_b128 v[74:77], v171 offset:0
	ds_read_b128 v[78:81], v175 offset:16384
	ds_read_b128 v[86:89], v174 offset:20480
	ds_read_b128 v[90:93], v175 offset:20480
	v_mfma_f32_32x32x16_bf16 v[0:15], v[114:117], v[110:113], v[0:15]
	s_waitcnt lgkmcnt(4)
	v_mfma_f32_32x32x16_bf16 v[48:63], v[66:69], v[70:73], v[48:63]
	s_waitcnt lgkmcnt(1)
	v_mfma_f32_32x32x16_bf16 v[32:47], v[66:69], v[86:89], v[32:47]
	ds_read_b128 v[66:69], v170 offset:4096
	ds_read_b128 v[98:101], v171 offset:4096
	s_waitcnt lgkmcnt(1)
	v_mfma_f32_32x32x16_bf16 v[16:31], v[66:69], v[70:73], v[16:31]
	v_mfma_f32_32x32x16_bf16 v[0:15], v[66:69], v[86:89], v[0:15]
	v_mfma_f32_32x32x16_bf16 v[48:63], v[74:77], v[78:81], v[48:63]
	v_mfma_f32_32x32x16_bf16 v[32:47], v[74:77], v[90:93], v[32:47]
	s_waitcnt lgkmcnt(0)
	v_mfma_f32_32x32x16_bf16 v[16:31], v[98:101], v[78:81], v[16:31]
	ds_read_b128 v[66:69], v172 offset:0
	ds_read_b128 v[70:73], v176 offset:16384
	ds_read_b128 v[74:77], v173 offset:0
	ds_read_b128 v[78:81], v177 offset:16384
	v_mfma_f32_32x32x16_bf16 v[0:15], v[98:101], v[90:93], v[0:15]
	ds_read_b128 v[86:89], v176 offset:20480
	ds_read_b128 v[90:93], v177 offset:20480
	s_waitcnt lgkmcnt(4)
	v_mfma_f32_32x32x16_bf16 v[48:63], v[66:69], v[70:73], v[48:63]
	s_waitcnt lgkmcnt(1)
	v_mfma_f32_32x32x16_bf16 v[32:47], v[66:69], v[86:89], v[32:47]
	ds_read_b128 v[66:69], v172 offset:4096
	ds_read_b128 v[98:101], v173 offset:4096
	s_waitcnt lgkmcnt(0)
	s_waitcnt vmcnt(0)
	s_barrier
; #define PW(T, off) ((T*)(lndp(p.ws) + (off)))
; DEVI float bf2f(bf16 h) { return __uint_as_float(((unsigned)h) << 16); }
; DEVI int accrow(int r, int lane) { return (r & 3) + 8 * (r >> 2) + 4 * (lane >> 5); }
; template <int EPI>
; DEVI void gemm_epi(const Params& p, const GJob& jb, f32x16 (&acc)[2][2], int rbase, int cbase, int lane) {
;     ...
;       const int row = rbase + i * 32 + accrow(r, lane);
;       if (row < M) {
; #pragma unroll
;         for (int j = 0; j < 2; ++j) {
;           const int col = cbase + j * 32 + (lane & 31);
;           const float v = acc[i][j][r];
;           if (EPI == EPI_SSD_IN) {
;             if (col < 2048) ((bf16*)(ar + S_ZB))[(size_t)row * 2048 + col] = f2bf(v);
;             else if (col < 6144) ((bf16*)(ar + S_XBC))[(size_t)row * 4096 + col - 2048] = f2bf(v);
;             else if (col < 6176) ((float*)(ar + S_DTRAW))[(size_t)row * 32 + col - 6144] = v;
;           } else if (EPI == EPI_RESID) {
;             PW(bf16, W_Z)[(size_t)row * 1024 + col] = f2bf(ALPHA * bf2f(PW(bf16, W_Xb)[(size_t)row * 1024 + col]) + v);
;     ...
;   for (int kt = 0; kt < nk; kt += 2) {
;     if (kt + 2 < nk) G_LOAD(ra0, rb0, kt + 2);
;     if (kt + 1 < nk) G_STORE(ra1, rb1, As1, Bs1);
;     G_COMPUTE(As, Bs);
;     __syncthreads();
;     if (kt + 1 < nk) {
;       if (kt + 3 < nk) G_LOAD(ra1, rb1, kt + 3);
;       if (kt + 2 < nk) G_STORE(ra0, rb0, As, Bs);
;       G_COMPUTE(As1, Bs1);
;       __syncthreads();
;     }
;   }
;     ...
;   const int rbase = m0 + wm * 64, cbase = n0 + wn * 64;
	v_mfma_f32_32x32x16_bf16 v[16:31], v[66:69], v[70:73], v[16:31]
	v_mfma_f32_32x32x16_bf16 v[48:63], v[74:77], v[78:81], v[48:63]
	v_mfma_f32_32x32x16_bf16 v[32:47], v[74:77], v[90:93], v[32:47]
	v_mfma_f32_32x32x16_bf16 v[0:15], v[66:69], v[86:89], v[0:15]
	v_mfma_f32_32x32x16_bf16 v[16:31], v[98:101], v[78:81], v[16:31]
	ds_read_b128 v[66:69], v170 offset:32768
	ds_read_b128 v[70:73], v174 offset:49152
	ds_read_b128 v[74:77], v175 offset:49152
	ds_read_b128 v[78:81], v171 offset:32768
	ds_read_b128 v[86:89], v174 offset:53248
	s_waitcnt lgkmcnt(3)
	v_mfma_f32_32x32x16_bf16 v[48:63], v[66:69], v[70:73], v[48:63]
	s_waitcnt lgkmcnt(0)
	v_mfma_f32_32x32x16_bf16 v[32:47], v[66:69], v[86:89], v[32:47]
	ds_read_b128 v[66:69], v170 offset:36864
	v_mfma_f32_32x32x16_bf16 v[0:15], v[98:101], v[90:93], v[0:15]
	s_waitcnt lgkmcnt(0)
	v_mfma_f32_32x32x16_bf16 v[16:31], v[66:69], v[70:73], v[16:31]
	ds_read_b128 v[70:73], v171 offset:36864
	v_mfma_f32_32x32x16_bf16 v[0:15], v[66:69], v[86:89], v[0:15]
	ds_read_b128 v[66:69], v175 offset:53248
	v_mfma_f32_32x32x16_bf16 v[48:63], v[78:81], v[74:77], v[48:63]
	s_waitcnt lgkmcnt(0)
	v_mfma_f32_32x32x16_bf16 v[32:47], v[78:81], v[66:69], v[32:47]
	v_mfma_f32_32x32x16_bf16 v[16:31], v[70:73], v[74:77], v[16:31]
	v_mfma_f32_32x32x16_bf16 v[0:15], v[70:73], v[66:69], v[0:15]
	ds_read_b128 v[66:69], v172 offset:32768
	ds_read_b128 v[70:73], v176 offset:49152
	ds_read_b128 v[74:77], v176 offset:53248
	s_waitcnt lgkmcnt(1)
	v_mfma_f32_32x32x16_bf16 v[48:63], v[66:69], v[70:73], v[48:63]
	s_waitcnt lgkmcnt(0)
	v_mfma_f32_32x32x16_bf16 v[32:47], v[66:69], v[74:77], v[32:47]
	ds_read_b128 v[66:69], v172 offset:36864
	s_waitcnt lgkmcnt(0)
	v_mfma_f32_32x32x16_bf16 v[16:31], v[66:69], v[70:73], v[16:31]
	ds_read_b128 v[78:81], v177 offset:53248
	ds_read_b128 v[86:89], v177 offset:49152
	ds_read_b128 v[90:93], v173 offset:36864
	ds_read_b128 v[70:73], v173 offset:32768
	s_waitcnt lgkmcnt(0)
	s_barrier
	s_ashr_i32 s15, s14, 31
	s_lshl_b64 s[14:15], s[14:15], 3
	v_mfma_f32_32x32x16_bf16 v[0:15], v[66:69], v[74:77], v[0:15]
	s_add_u32 s14, s0, s14
	s_addc_u32 s15, s1, s15
	s_load_dwordx2 s[14:15], s[14:15], 0x0
	s_waitcnt lgkmcnt(0)
	s_mov_b32 s14, 26
	s_ashr_i32 s15, s14, 31
	v_mfma_f32_32x32x16_bf16 v[48:63], v[70:73], v[86:89], v[48:63]
	s_lshl_b64 s[14:15], s[14:15], 3
	s_add_u32 s14, s0, s14
	s_addc_u32 s15, s1, s15
	s_load_dwordx2 s[14:15], s[14:15], 0x0
	v_or_b32_e32 v66, s2, v65
	s_waitcnt lgkmcnt(0)
	v_or_b32_e32 v64, 32, v66
	v_mfma_f32_32x32x16_bf16 v[32:47], v[70:73], v[78:81], v[32:47]
	v_lshrrev_b32_e32 v72, 3, v84
	v_add_u32_e32 v70, s3, v85
	v_and_b32_e32 v71, 4, v72
	v_or_b32_e32 v68, v70, v71
	s_mov_b64 s[14:15], s[74:75]
	v_cmp_gt_i32_e32 vcc, s90, v68
	v_ashrrev_i32_e32 v67, 31, v66
	v_mfma_f32_32x32x16_bf16 v[16:31], v[90:93], v[86:89], v[16:31]
	v_ashrrev_i32_e32 v65, 31, v64
	v_mfma_f32_32x32x16_bf16 v[0:15], v[90:93], v[78:81], v[0:15]
	s_and_saveexec_b64 s[2:3], vcc
	s_cbranch_execz .LBB0_22
	v_ashrrev_i32_e32 v69, 31, v68
	v_lshlrev_b64 v[68:69], 10, v[68:69]
	v_lshl_add_u64 v[74:75], v[68:69], 0, v[66:67]
	s_mov_b64 s[14:15], s[74:75]
	v_lshlrev_b64 v[74:75], 1, v[74:75]
	v_lshl_add_u64 v[68:69], v[68:69], 0, v[64:65]
	v_lshl_add_u64 v[76:77], s[14:15], 0, v[74:75]
	v_add_co_u32_e32 v76, vcc, 0xf724000, v76
	s_mov_b64 s[14:15], s[74:75]
	s_nop 0
	v_addc_co_u32_e32 v77, vcc, 0, v77, vcc
	global_load_ushort v73, v[76:77], off
	v_lshlrev_b64 v[68:69], 1, v[68:69]
	v_lshl_add_u64 v[74:75], s[14:15], 0, v[74:75]
	v_add_co_u32_e32 v74, vcc, 0xb5a4000, v74
	s_mov_b64 s[14:15], s[74:75]
	s_nop 0
	v_addc_co_u32_e32 v75, vcc, 0, v75, vcc
	s_waitcnt vmcnt(0)
	v_lshlrev_b32_e32 v73, 16, v73
	v_fmamk_f32 v48, v73, 0x3fd744fd, v48
	v_cvt_pk_bf16_f32 v48, v48, s0
	global_store_short v[74:75], v48, off
	s_nop 0
	v_lshl_add_u64 v[74:75], s[14:15], 0, v[68:69]
	v_add_co_u32_e32 v74, vcc, s80, v74
	s_mov_b64 s[14:15], s[74:75]
	s_nop 0
	v_addc_co_u32_e32 v75, vcc, 0, v75, vcc
	global_load_ushort v48, v[74:75], off
	s_waitcnt vmcnt(0)
	v_lshlrev_b32_e32 v48, 16, v48
	v_lshl_add_u64 v[68:69], s[14:15], 0, v[68:69]
	v_fmamk_f32 v32, v48, 0x3fd744fd, v32
	v_add_co_u32_e32 v68, vcc, 0xb5a4000, v68
	v_cvt_pk_bf16_f32 v32, v32, s0
	s_nop 0
	v_addc_co_u32_e32 v69, vcc, 0, v69, vcc
	global_store_short v[68:69], v32, off

; DEVI int TID() { int t = threadIdx.x; asm volatile("" : "+v"(t)); return t; }
;   bf16* As = (bf16*)smem;
;   bf16* Bs = As + 128 * 72;
;   const int tid = TID(), lane = tid & 63, wave = tid >> 6, wm = wave >> 1, wn = wave & 1;
;   f32x16 acc[2][2];
; #pragma unroll
;   for (int i = 0; i < 2; ++i)
; #pragma unroll
;     for (int j = 0; j < 2; ++j) acc[i][j] = zero16();
;   const int lrow = tid >> 3, lkc = (tid & 7) * 8;
;   const bf16* Ag = jb.A + (size_t)max(m0 + lrow, 0) * jb.lda + lkc;
;   const bf16* Ag1 = jb.A + (ptrdiff_t)(m0 + lrow) * jb.lda + lkc;
;   const bf16* Bg = jb.Bt + (size_t)(n0 + lrow) * jb.K + lkc;
;   const size_t astep = (size_t)32 * jb.lda, bstep = (size_t)32 * jb.K;
;   if (kt1 < 0) kt1 = jb.K >> 6;
;   const int nk = kt1 - kt0;
;   Ag += (size_t)kt0 * 64; Ag1 += (size_t)kt0 * 64; Bg += (size_t)kt0 * 64;
;   u32x4 ra0[4], rb0[4], ra1[4], rb1[4];
;     ...
;   bf16* As1 = As + 2 * 128 * 72;
;   bf16* Bs1 = As1 + 128 * 72;
;   G_LOAD(ra0, rb0, 0);
;   if (nk > 1) G_LOAD(ra1, rb1, 1);
;   G_STORE(ra0, rb0, As, Bs);
;   __syncthreads();
;   for (int kt = 0; kt < nk; kt += 2) {
;     if (kt + 2 < nk) G_LOAD(ra0, rb0, kt + 2);
;     if (kt + 1 < nk) G_STORE(ra1, rb1, As1, Bs1);
;     G_COMPUTE(As, Bs);
.LBB0_668:
	s_mul_i32 s34, s34, s31
	s_sub_i32 s26, s33, s34
	s_add_i32 s30, s30, s26
	s_waitcnt vmcnt(2)
	v_mov_b32_e32 v85, v208
	s_lshl_b32 s26, s30, 7
	s_lshl_b32 s27, s35, 7
	v_ashrrev_i32_e32 v82, 3, v85
	v_add_u32_e32 v0, s26, v82
	v_lshlrev_b32_e32 v1, 4, v85
	v_and_b32_e32 v64, 0x70, v1
	s_mov_b64 s[96:97], 0x80
	v_lshrrev_b32_e32 v178, 4, v208
	v_and_b32_e32 v178, 7, v178
	v_lshlrev_b32_e32 v178, 4, v178
	v_xor_b32_e32 v64, v64, v178
	v_lshrrev_b32_e32 v179, 6, v208
	v_lshlrev_b32_e32 v179, 10, v179
	v_lshrrev_b32_e32 v180, 5, v208
	v_lshrrev_b32_e32 v181, 1, v208
	v_xor_b32_e32 v180, v180, v181
	v_readfirstlane_b32 s94, v179
	v_and_b32_e32 v180, 1, v180
	v_lshlrev_b32_e32 v180, 4, v180
	v_and_b32_e32 v181, 31, v208
	v_lshlrev_b32_e32 v181, 7, v181
	v_or_b32_e32 v180, v180, v181
	v_lshrrev_b32_e32 v181, 7, v208
	v_lshlrev_b32_e32 v181, 13, v181
	v_or_b32_e32 v194, v180, v181
	v_bfe_u32 v181, v208, 6, 1
	v_lshlrev_b32_e32 v181, 13, v181
	v_or_b32_e32 v195, v180, v181
	v_bfe_u32 v178, v208, 2, 2
	v_xor_b32_e32 v179, 0, v178
	v_lshlrev_b32_e32 v179, 5, v179
	v_or_b32_e32 v170, v194, v179
	v_or_b32_e32 v174, v195, v179
	v_xor_b32_e32 v179, 1, v178
	v_lshlrev_b32_e32 v179, 5, v179
	v_or_b32_e32 v171, v194, v179
	v_or_b32_e32 v175, v195, v179
	v_xor_b32_e32 v179, 2, v178
	v_lshlrev_b32_e32 v179, 5, v179
	v_or_b32_e32 v172, v194, v179
	v_or_b32_e32 v176, v195, v179
	v_xor_b32_e32 v179, 3, v178
	v_lshlrev_b32_e32 v179, 5, v179
	v_or_b32_e32 v173, v194, v179
	v_or_b32_e32 v177, v195, v179
	v_ashrrev_i32_e32 v1, 31, v0
	v_max_i32_e32 v2, 0, v0
	v_lshlrev_b64 v[0:1], 11, v[0:1]
	v_mov_b32_e32 v65, v97
	v_lshl_add_u64 v[0:1], s[4:5], 0, v[0:1]
	v_lshl_add_u64 v[28:29], v[0:1], 0, v[64:65]
	v_add_u32_e32 v0, s27, v82
	v_ashrrev_i32_e32 v1, 31, v0
	v_lshlrev_b64 v[0:1], 11, v[0:1]
	v_lshl_add_u64 v[0:1], s[2:3], 0, v[0:1]
	v_add_co_u32_e32 v70, vcc, s63, v28
	v_lshl_add_u64 v[68:69], v[0:1], 0, v[64:65]
	s_nop 0
	v_addc_co_u32_e32 v71, vcc, 0, v29, vcc
	v_add_co_u32_e32 v72, vcc, s63, v68
	v_mov_b32_e32 v3, v97
	s_nop 0
	v_addc_co_u32_e32 v73, vcc, 0, v69, vcc
	v_add_co_u32_e32 v74, vcc, s64, v28
	v_lshlrev_b64 v[2:3], 11, v[2:3]
	s_nop 0
	v_addc_co_u32_e32 v75, vcc, 0, v29, vcc
	v_add_co_u32_e32 v76, vcc, s64, v68
	v_lshl_add_u64 v[2:3], s[4:5], 0, v[2:3]
	s_nop 0
	v_addc_co_u32_e32 v77, vcc, 0, v69, vcc
	v_add_co_u32_e32 v78, vcc, s65, v68
	v_lshl_add_u64 v[66:67], v[2:3], 0, v[64:65]
	s_nop 0
	v_addc_co_u32_e32 v79, vcc, 0, v69, vcc
	v_add_co_u32_e32 v80, vcc, s65, v28
	v_addc_co_u32_e32 v81, vcc, 0, v29, vcc
	s_waitcnt lgkmcnt(0)
	v_ashrrev_i32_e32 v65, 1, v85
	v_and_b32_e32 v84, 31, v85
	v_lshrrev_b32_e32 v83, 1, v85
	v_and_b32_e32 v86, 0xffffffc0, v65
	s_waitcnt vmcnt(0)
	v_and_b32_e32 v88, 16, v83
	v_mad_u64_u32 v[82:83], s[2:3], v82, s91, v[64:65]
	v_or_b32_e32 v64, v86, v84
	v_add_u32_e32 v83, 0xd800, v82
	v_mad_u64_u32 v[64:65], s[2:3], v64, s91, v[88:89]
	s_mov_b64 s[2:3], -1
	s_add_u32 m0, s94, 0x4000
	s_nop 1
	global_load_lds_dwordx4 v[68:69], off
	s_add_u32 m0, s94, 0x0
	s_nop 1
	global_load_lds_dwordx4 v[66:67], off
	s_add_u32 m0, s94, 0x5000
	s_nop 1
	global_load_lds_dwordx4 v[72:73], off
	s_add_u32 m0, s94, 0x6000
	s_nop 1
	global_load_lds_dwordx4 v[76:77], off
	s_add_u32 m0, s94, 0x7000
	s_nop 1
	global_load_lds_dwordx4 v[78:79], off
	s_add_u32 m0, s94, 0x1000
	s_nop 1
	global_load_lds_dwordx4 v[70:71], off
	s_add_u32 m0, s94, 0x2000
	s_nop 1
	global_load_lds_dwordx4 v[74:75], off
	s_add_u32 m0, s94, 0x3000
	s_nop 1
	global_load_lds_dwordx4 v[80:81], off
	s_waitcnt lgkmcnt(0)
	s_waitcnt vmcnt(0)
	s_barrier
	v_lshl_add_u64 v[66:67], v[66:67], 0, s[96:97]
	s_add_u32 m0, s94, 0x8000
	s_nop 1
	global_load_lds_dwordx4 v[66:67], off
	v_lshl_add_u64 v[68:69], v[68:69], 0, s[96:97]
	s_add_u32 m0, s94, 0xc000
	s_nop 1
	global_load_lds_dwordx4 v[68:69], off
	v_lshl_add_u64 v[70:71], v[70:71], 0, s[96:97]
	s_add_u32 m0, s94, 0x9000
	s_nop 1
	global_load_lds_dwordx4 v[70:71], off
	v_lshl_add_u64 v[72:73], v[72:73], 0, s[96:97]
	s_add_u32 m0, s94, 0xd000
	s_nop 1
	global_load_lds_dwordx4 v[72:73], off
	v_lshl_add_u64 v[74:75], v[74:75], 0, s[96:97]
	s_add_u32 m0, s94, 0xa000
	s_nop 1
	global_load_lds_dwordx4 v[74:75], off
	v_lshl_add_u64 v[76:77], v[76:77], 0, s[96:97]
	s_add_u32 m0, s94, 0xe000
	s_nop 1
	global_load_lds_dwordx4 v[76:77], off
	v_lshl_add_u64 v[80:81], v[80:81], 0, s[96:97]
	s_add_u32 m0, s94, 0xb000
	s_nop 1
	global_load_lds_dwordx4 v[80:81], off
	v_lshl_add_u64 v[78:79], v[78:79], 0, s[96:97]
	s_add_u32 m0, s94, 0xf000
	s_nop 1
	global_load_lds_dwordx4 v[78:79], off
	ds_read_b128 v[0:3], v170 offset:0
	v_and_b32_e32 v4, 0x5f, v85
	v_mad_u32_u24 v65, v4, s91, v88
	ds_read_b128 v[4:7], v174 offset:16384
	ds_read_b128 v[88:91], v171 offset:0
	ds_read_b128 v[92:95], v175 offset:16384
	ds_read_b128 v[8:11], v174 offset:20480
	ds_read_b128 v[98:101], v175 offset:20480
	s_waitcnt lgkmcnt(4)
	v_mfma_f32_32x32x16_bf16 v[48:63], v[0:3], v[4:7], 0
	s_waitcnt lgkmcnt(1)
	v_mfma_f32_32x32x16_bf16 v[32:47], v[0:3], v[8:11], 0
	ds_read_b128 v[0:3], v170 offset:4096
	ds_read_b128 v[102:105], v171 offset:4096
	s_waitcnt lgkmcnt(1)
	v_mfma_f32_32x32x16_bf16 v[16:31], v[0:3], v[4:7], 0
	v_mfma_f32_32x32x16_bf16 v[0:15], v[0:3], v[8:11], 0
	v_mfma_f32_32x32x16_bf16 v[48:63], v[88:91], v[92:95], v[48:63]
	v_mfma_f32_32x32x16_bf16 v[32:47], v[88:91], v[98:101], v[32:47]
	s_waitcnt lgkmcnt(0)
	v_mfma_f32_32x32x16_bf16 v[16:31], v[102:105], v[92:95], v[16:31]
	v_mfma_f32_32x32x16_bf16 v[0:15], v[102:105], v[98:101], v[0:15]
	ds_read_b128 v[88:91], v172 offset:0
	ds_read_b128 v[92:95], v176 offset:16384
	ds_read_b128 v[98:101], v173 offset:0
	ds_read_b128 v[102:105], v177 offset:16384
	ds_read_b128 v[106:109], v176 offset:20480
	ds_read_b128 v[110:113], v177 offset:20480
	s_waitcnt lgkmcnt(4)
	v_mfma_f32_32x32x16_bf16 v[48:63], v[88:91], v[92:95], v[48:63]
	s_waitcnt lgkmcnt(1)
	v_mfma_f32_32x32x16_bf16 v[32:47], v[88:91], v[106:109], v[32:47]
	ds_read_b128 v[88:91], v172 offset:4096
	ds_read_b128 v[114:117], v173 offset:4096
	s_waitcnt lgkmcnt(1)
	v_mfma_f32_32x32x16_bf16 v[16:31], v[88:91], v[92:95], v[16:31]
	v_mfma_f32_32x32x16_bf16 v[0:15], v[88:91], v[106:109], v[0:15]
	v_mfma_f32_32x32x16_bf16 v[48:63], v[98:101], v[102:105], v[48:63]
	v_mfma_f32_32x32x16_bf16 v[32:47], v[98:101], v[110:113], v[32:47]
	s_waitcnt lgkmcnt(0)
	v_mfma_f32_32x32x16_bf16 v[16:31], v[114:117], v[102:105], v[16:31]
	s_waitcnt vmcnt(0)
	s_barrier
;     ...
;   bf16* As1 = As + 2 * 128 * 72;
;   bf16* Bs1 = As1 + 128 * 72;
;   G_LOAD(ra0, rb0, 0);
;   if (nk > 1) G_LOAD(ra1, rb1, 1);
;   G_STORE(ra0, rb0, As, Bs);
;   __syncthreads();
;   for (int kt = 0; kt < nk; kt += 2) {
;     if (kt + 2 < nk) G_LOAD(ra0, rb0, kt + 2);
;     if (kt + 1 < nk) G_STORE(ra1, rb1, As1, Bs1);
;     G_COMPUTE(As, Bs);
;     __syncthreads();
;     if (kt + 1 < nk) {
;       if (kt + 3 < nk) G_LOAD(ra1, rb1, kt + 3);
;       if (kt + 2 < nk) G_STORE(ra0, rb0, As, Bs);
;       G_COMPUTE(As1, Bs1);
;       __syncthreads();
;     }
;   }
	v_lshl_add_u64 v[66:67], v[66:67], 0, s[96:97]
	s_add_u32 m0, s94, 0x0
	s_nop 1
	global_load_lds_dwordx4 v[66:67], off
	v_lshl_add_u64 v[68:69], v[68:69], 0, s[96:97]
	s_add_u32 m0, s94, 0x4000
	s_nop 1
	global_load_lds_dwordx4 v[68:69], off
	v_lshl_add_u64 v[70:71], v[70:71], 0, s[96:97]
	s_add_u32 m0, s94, 0x1000
	s_nop 1
	global_load_lds_dwordx4 v[70:71], off
	v_lshl_add_u64 v[72:73], v[72:73], 0, s[96:97]
	s_add_u32 m0, s94, 0x5000
	s_nop 1
	global_load_lds_dwordx4 v[72:73], off
	v_lshl_add_u64 v[74:75], v[74:75], 0, s[96:97]
	s_add_u32 m0, s94, 0x2000
	s_nop 1
	global_load_lds_dwordx4 v[74:75], off
	v_lshl_add_u64 v[76:77], v[76:77], 0, s[96:97]
	s_add_u32 m0, s94, 0x6000
	s_nop 1
	global_load_lds_dwordx4 v[76:77], off
	v_lshl_add_u64 v[80:81], v[80:81], 0, s[96:97]
	s_add_u32 m0, s94, 0x3000
	s_nop 1
	global_load_lds_dwordx4 v[80:81], off
	v_lshl_add_u64 v[78:79], v[78:79], 0, s[96:97]
	s_add_u32 m0, s94, 0x7000
	s_nop 1
	global_load_lds_dwordx4 v[78:79], off
	v_mfma_f32_32x32x16_bf16 v[0:15], v[114:117], v[110:113], v[0:15]
	ds_read_b128 v[88:91], v170 offset:32768
	ds_read_b128 v[92:95], v174 offset:49152
	ds_read_b128 v[98:101], v171 offset:32768
	ds_read_b128 v[102:105], v175 offset:49152
	ds_read_b128 v[106:109], v174 offset:53248
	ds_read_b128 v[110:113], v175 offset:53248
	s_waitcnt lgkmcnt(4)
	v_mfma_f32_32x32x16_bf16 v[48:63], v[88:91], v[92:95], v[48:63]
	s_waitcnt lgkmcnt(1)
	v_mfma_f32_32x32x16_bf16 v[32:47], v[88:91], v[106:109], v[32:47]
	ds_read_b128 v[88:91], v170 offset:36864
	ds_read_b128 v[114:117], v171 offset:36864
	s_waitcnt lgkmcnt(1)
	v_mfma_f32_32x32x16_bf16 v[16:31], v[88:91], v[92:95], v[16:31]
	v_mfma_f32_32x32x16_bf16 v[0:15], v[88:91], v[106:109], v[0:15]
	v_mfma_f32_32x32x16_bf16 v[48:63], v[98:101], v[102:105], v[48:63]
	v_mfma_f32_32x32x16_bf16 v[32:47], v[98:101], v[110:113], v[32:47]
	s_waitcnt lgkmcnt(0)
	v_mfma_f32_32x32x16_bf16 v[16:31], v[114:117], v[102:105], v[16:31]
	ds_read_b128 v[88:91], v172 offset:32768
	ds_read_b128 v[92:95], v176 offset:49152
	ds_read_b128 v[98:101], v173 offset:32768
	ds_read_b128 v[102:105], v177 offset:49152
	v_mfma_f32_32x32x16_bf16 v[0:15], v[114:117], v[110:113], v[0:15]
	ds_read_b128 v[106:109], v176 offset:53248
	ds_read_b128 v[110:113], v177 offset:53248
	s_waitcnt lgkmcnt(4)
	v_mfma_f32_32x32x16_bf16 v[48:63], v[88:91], v[92:95], v[48:63]
	s_waitcnt lgkmcnt(1)
	v_mfma_f32_32x32x16_bf16 v[32:47], v[88:91], v[106:109], v[32:47]
	ds_read_b128 v[88:91], v172 offset:36864
	ds_read_b128 v[114:117], v173 offset:36864
	s_waitcnt lgkmcnt(1)
	v_mfma_f32_32x32x16_bf16 v[16:31], v[88:91], v[92:95], v[16:31]
	v_mfma_f32_32x32x16_bf16 v[0:15], v[88:91], v[106:109], v[0:15]
	v_mfma_f32_32x32x16_bf16 v[48:63], v[98:101], v[102:105], v[48:63]
	v_mfma_f32_32x32x16_bf16 v[32:47], v[98:101], v[110:113], v[32:47]
	s_waitcnt lgkmcnt(0)
	v_mfma_f32_32x32x16_bf16 v[16:31], v[114:117], v[102:105], v[16:31]
	s_waitcnt vmcnt(0)
	s_barrier
	v_lshl_add_u64 v[66:67], v[66:67], 0, s[96:97]
	s_add_u32 m0, s94, 0x8000
	s_nop 1
	global_load_lds_dwordx4 v[66:67], off
	v_lshl_add_u64 v[68:69], v[68:69], 0, s[96:97]
	s_add_u32 m0, s94, 0xc000
	s_nop 1
	global_load_lds_dwordx4 v[68:69], off
	v_lshl_add_u64 v[70:71], v[70:71], 0, s[96:97]
	s_add_u32 m0, s94, 0x9000
	s_nop 1
	global_load_lds_dwordx4 v[70:71], off
	v_lshl_add_u64 v[72:73], v[72:73], 0, s[96:97]
	s_add_u32 m0, s94, 0xd000
	s_nop 1
	global_load_lds_dwordx4 v[72:73], off
	v_lshl_add_u64 v[74:75], v[74:75], 0, s[96:97]
	s_add_u32 m0, s94, 0xa000
	s_nop 1
	global_load_lds_dwordx4 v[74:75], off
	v_lshl_add_u64 v[76:77], v[76:77], 0, s[96:97]
	s_add_u32 m0, s94, 0xe000
	s_nop 1
	global_load_lds_dwordx4 v[76:77], off
	v_lshl_add_u64 v[80:81], v[80:81], 0, s[96:97]
	s_add_u32 m0, s94, 0xb000
	s_nop 1
	global_load_lds_dwordx4 v[80:81], off
	v_lshl_add_u64 v[78:79], v[78:79], 0, s[96:97]
	s_add_u32 m0, s94, 0xf000
	s_nop 1
	global_load_lds_dwordx4 v[78:79], off
	v_mfma_f32_32x32x16_bf16 v[0:15], v[114:117], v[110:113], v[0:15]
	ds_read_b128 v[88:91], v170 offset:0
	ds_read_b128 v[92:95], v174 offset:16384
	ds_read_b128 v[98:101], v171 offset:0
	ds_read_b128 v[102:105], v175 offset:16384
	ds_read_b128 v[106:109], v174 offset:20480
	ds_read_b128 v[110:113], v175 offset:20480
	s_waitcnt lgkmcnt(4)
	v_mfma_f32_32x32x16_bf16 v[48:63], v[88:91], v[92:95], v[48:63]
	s_waitcnt lgkmcnt(1)
	v_mfma_f32_32x32x16_bf16 v[32:47], v[88:91], v[106:109], v[32:47]
	ds_read_b128 v[88:91], v170 offset:4096
	ds_read_b128 v[114:117], v171 offset:4096
	s_waitcnt lgkmcnt(1)
	v_mfma_f32_32x32x16_bf16 v[16:31], v[88:91], v[92:95], v[16:31]
	v_mfma_f32_32x32x16_bf16 v[0:15], v[88:91], v[106:109], v[0:15]
	v_mfma_f32_32x32x16_bf16 v[48:63], v[98:101], v[102:105], v[48:63]
	v_mfma_f32_32x32x16_bf16 v[32:47], v[98:101], v[110:113], v[32:47]
	s_waitcnt lgkmcnt(0)
	v_mfma_f32_32x32x16_bf16 v[16:31], v[114:117], v[102:105], v[16:31]
	ds_read_b128 v[88:91], v172 offset:0
	ds_read_b128 v[92:95], v176 offset:16384
	ds_read_b128 v[98:101], v173 offset:0
	ds_read_b128 v[102:105], v177 offset:16384
	v_mfma_f32_32x32x16_bf16 v[0:15], v[114:117], v[110:113], v[0:15]
	ds_read_b128 v[106:109], v176 offset:20480
	ds_read_b128 v[110:113], v177 offset:20480
	s_waitcnt lgkmcnt(4)
	v_mfma_f32_32x32x16_bf16 v[48:63], v[88:91], v[92:95], v[48:63]
	s_waitcnt lgkmcnt(1)
	v_mfma_f32_32x32x16_bf16 v[32:47], v[88:91], v[106:109], v[32:47]
	ds_read_b128 v[88:91], v172 offset:4096
	ds_read_b128 v[114:117], v173 offset:4096
	s_waitcnt lgkmcnt(1)
	v_mfma_f32_32x32x16_bf16 v[16:31], v[88:91], v[92:95], v[16:31]
	v_mfma_f32_32x32x16_bf16 v[0:15], v[88:91], v[106:109], v[0:15]
	v_mfma_f32_32x32x16_bf16 v[48:63], v[98:101], v[102:105], v[48:63]
	v_mfma_f32_32x32x16_bf16 v[32:47], v[98:101], v[110:113], v[32:47]
	s_waitcnt lgkmcnt(0)
	v_mfma_f32_32x32x16_bf16 v[16:31], v[114:117], v[102:105], v[16:31]
	s_waitcnt vmcnt(0)
	s_barrier
;     ...
;   bf16* As1 = As + 2 * 128 * 72;
;   bf16* Bs1 = As1 + 128 * 72;
;   G_LOAD(ra0, rb0, 0);
;   if (nk > 1) G_LOAD(ra1, rb1, 1);
;   G_STORE(ra0, rb0, As, Bs);
;   __syncthreads();
;   for (int kt = 0; kt < nk; kt += 2) {
;     if (kt + 2 < nk) G_LOAD(ra0, rb0, kt + 2);
;     if (kt + 1 < nk) G_STORE(ra1, rb1, As1, Bs1);
;     G_COMPUTE(As, Bs);
;     __syncthreads();
;     if (kt + 1 < nk) {
;       if (kt + 3 < nk) G_LOAD(ra1, rb1, kt + 3);
;       if (kt + 2 < nk) G_STORE(ra0, rb0, As, Bs);
;       G_COMPUTE(As1, Bs1);
;       __syncthreads();
;     }
;   }
	v_lshl_add_u64 v[66:67], v[66:67], 0, s[96:97]
	s_add_u32 m0, s94, 0x0
	s_nop 1
	global_load_lds_dwordx4 v[66:67], off
	v_lshl_add_u64 v[68:69], v[68:69], 0, s[96:97]
	s_add_u32 m0, s94, 0x4000
	s_nop 1
	global_load_lds_dwordx4 v[68:69], off
	v_lshl_add_u64 v[70:71], v[70:71], 0, s[96:97]
	s_add_u32 m0, s94, 0x1000
	s_nop 1
	global_load_lds_dwordx4 v[70:71], off
	v_lshl_add_u64 v[72:73], v[72:73], 0, s[96:97]
	s_add_u32 m0, s94, 0x5000
	s_nop 1
	global_load_lds_dwordx4 v[72:73], off
	v_lshl_add_u64 v[74:75], v[74:75], 0, s[96:97]
	s_add_u32 m0, s94, 0x2000
	s_nop 1
	global_load_lds_dwordx4 v[74:75], off
	v_lshl_add_u64 v[76:77], v[76:77], 0, s[96:97]
	s_add_u32 m0, s94, 0x6000
	s_nop 1
	global_load_lds_dwordx4 v[76:77], off
	v_lshl_add_u64 v[80:81], v[80:81], 0, s[96:97]
	s_add_u32 m0, s94, 0x3000
	s_nop 1
	global_load_lds_dwordx4 v[80:81], off
	v_lshl_add_u64 v[78:79], v[78:79], 0, s[96:97]
	s_add_u32 m0, s94, 0x7000
	s_nop 1
	global_load_lds_dwordx4 v[78:79], off
	v_mfma_f32_32x32x16_bf16 v[0:15], v[114:117], v[110:113], v[0:15]
	ds_read_b128 v[88:91], v170 offset:32768
	ds_read_b128 v[92:95], v174 offset:49152
	ds_read_b128 v[98:101], v171 offset:32768
	ds_read_b128 v[102:105], v175 offset:49152
	ds_read_b128 v[106:109], v174 offset:53248
	ds_read_b128 v[110:113], v175 offset:53248
	s_waitcnt lgkmcnt(4)
	v_mfma_f32_32x32x16_bf16 v[48:63], v[88:91], v[92:95], v[48:63]
	s_waitcnt lgkmcnt(1)
	v_mfma_f32_32x32x16_bf16 v[32:47], v[88:91], v[106:109], v[32:47]
	ds_read_b128 v[88:91], v170 offset:36864
	ds_read_b128 v[114:117], v171 offset:36864
	s_waitcnt lgkmcnt(1)
	v_mfma_f32_32x32x16_bf16 v[16:31], v[88:91], v[92:95], v[16:31]
	v_mfma_f32_32x32x16_bf16 v[0:15], v[88:91], v[106:109], v[0:15]
	v_mfma_f32_32x32x16_bf16 v[48:63], v[98:101], v[102:105], v[48:63]
	v_mfma_f32_32x32x16_bf16 v[32:47], v[98:101], v[110:113], v[32:47]
	s_waitcnt lgkmcnt(0)
	v_mfma_f32_32x32x16_bf16 v[16:31], v[114:117], v[102:105], v[16:31]
	ds_read_b128 v[88:91], v172 offset:32768
	ds_read_b128 v[92:95], v176 offset:49152
	ds_read_b128 v[98:101], v173 offset:32768
	ds_read_b128 v[102:105], v177 offset:49152
	v_mfma_f32_32x32x16_bf16 v[0:15], v[114:117], v[110:113], v[0:15]
	ds_read_b128 v[106:109], v176 offset:53248
	ds_read_b128 v[110:113], v177 offset:53248
	s_waitcnt lgkmcnt(4)
	v_mfma_f32_32x32x16_bf16 v[48:63], v[88:91], v[92:95], v[48:63]
	s_waitcnt lgkmcnt(1)
	v_mfma_f32_32x32x16_bf16 v[32:47], v[88:91], v[106:109], v[32:47]
	ds_read_b128 v[88:91], v172 offset:36864
	ds_read_b128 v[114:117], v173 offset:36864
	s_waitcnt lgkmcnt(1)
	v_mfma_f32_32x32x16_bf16 v[16:31], v[88:91], v[92:95], v[16:31]
	v_mfma_f32_32x32x16_bf16 v[0:15], v[88:91], v[106:109], v[0:15]
	v_mfma_f32_32x32x16_bf16 v[48:63], v[98:101], v[102:105], v[48:63]
	v_mfma_f32_32x32x16_bf16 v[32:47], v[98:101], v[110:113], v[32:47]
	s_waitcnt lgkmcnt(0)
	v_mfma_f32_32x32x16_bf16 v[16:31], v[114:117], v[102:105], v[16:31]
	s_waitcnt vmcnt(0)
	s_barrier
	v_lshl_add_u64 v[66:67], v[66:67], 0, s[96:97]
	s_add_u32 m0, s94, 0x8000
	s_nop 1
	global_load_lds_dwordx4 v[66:67], off
	v_lshl_add_u64 v[68:69], v[68:69], 0, s[96:97]
	s_add_u32 m0, s94, 0xc000
	s_nop 1
	global_load_lds_dwordx4 v[68:69], off
	v_lshl_add_u64 v[70:71], v[70:71], 0, s[96:97]
	s_add_u32 m0, s94, 0x9000
	s_nop 1
	global_load_lds_dwordx4 v[70:71], off
	v_lshl_add_u64 v[72:73], v[72:73], 0, s[96:97]
	s_add_u32 m0, s94, 0xd000
	s_nop 1
	global_load_lds_dwordx4 v[72:73], off
	v_lshl_add_u64 v[74:75], v[74:75], 0, s[96:97]
	s_add_u32 m0, s94, 0xa000
	s_nop 1
	global_load_lds_dwordx4 v[74:75], off
	v_lshl_add_u64 v[76:77], v[76:77], 0, s[96:97]
	s_add_u32 m0, s94, 0xe000
	s_nop 1
	global_load_lds_dwordx4 v[76:77], off
	v_lshl_add_u64 v[80:81], v[80:81], 0, s[96:97]
	s_add_u32 m0, s94, 0xb000
	s_nop 1
	global_load_lds_dwordx4 v[80:81], off
	v_lshl_add_u64 v[78:79], v[78:79], 0, s[96:97]
	s_add_u32 m0, s94, 0xf000
	s_nop 1
	global_load_lds_dwordx4 v[78:79], off
	v_mfma_f32_32x32x16_bf16 v[0:15], v[114:117], v[110:113], v[0:15]
	ds_read_b128 v[88:91], v170 offset:0
	ds_read_b128 v[92:95], v174 offset:16384
	ds_read_b128 v[98:101], v171 offset:0
	ds_read_b128 v[102:105], v175 offset:16384
	ds_read_b128 v[106:109], v174 offset:20480
	ds_read_b128 v[110:113], v175 offset:20480
	s_waitcnt lgkmcnt(4)
	v_mfma_f32_32x32x16_bf16 v[48:63], v[88:91], v[92:95], v[48:63]
	s_waitcnt lgkmcnt(1)
	v_mfma_f32_32x32x16_bf16 v[32:47], v[88:91], v[106:109], v[32:47]
	ds_read_b128 v[88:91], v170 offset:4096
	ds_read_b128 v[114:117], v171 offset:4096
	s_waitcnt lgkmcnt(1)
	v_mfma_f32_32x32x16_bf16 v[16:31], v[88:91], v[92:95], v[16:31]
	v_mfma_f32_32x32x16_bf16 v[0:15], v[88:91], v[106:109], v[0:15]
	v_mfma_f32_32x32x16_bf16 v[48:63], v[98:101], v[102:105], v[48:63]
	v_mfma_f32_32x32x16_bf16 v[32:47], v[98:101], v[110:113], v[32:47]
	s_waitcnt lgkmcnt(0)
	v_mfma_f32_32x32x16_bf16 v[16:31], v[114:117], v[102:105], v[16:31]
	ds_read_b128 v[88:91], v172 offset:0
	ds_read_b128 v[92:95], v176 offset:16384
	ds_read_b128 v[98:101], v173 offset:0
	ds_read_b128 v[102:105], v177 offset:16384
	v_mfma_f32_32x32x16_bf16 v[0:15], v[114:117], v[110:113], v[0:15]
	ds_read_b128 v[106:109], v176 offset:20480
	ds_read_b128 v[110:113], v177 offset:20480
	s_waitcnt lgkmcnt(4)
	v_mfma_f32_32x32x16_bf16 v[48:63], v[88:91], v[92:95], v[48:63]
	s_waitcnt lgkmcnt(1)
	v_mfma_f32_32x32x16_bf16 v[32:47], v[88:91], v[106:109], v[32:47]
	ds_read_b128 v[88:91], v172 offset:4096
	ds_read_b128 v[114:117], v173 offset:4096
	s_waitcnt lgkmcnt(1)
	v_mfma_f32_32x32x16_bf16 v[16:31], v[88:91], v[92:95], v[16:31]
	v_mfma_f32_32x32x16_bf16 v[0:15], v[88:91], v[106:109], v[0:15]
	v_mfma_f32_32x32x16_bf16 v[48:63], v[98:101], v[102:105], v[48:63]
	v_mfma_f32_32x32x16_bf16 v[32:47], v[98:101], v[110:113], v[32:47]
	s_waitcnt lgkmcnt(0)
	v_mfma_f32_32x32x16_bf16 v[16:31], v[114:117], v[102:105], v[16:31]
	s_waitcnt vmcnt(0)
	s_barrier
;     ...
;   bf16* As1 = As + 2 * 128 * 72;
;   bf16* Bs1 = As1 + 128 * 72;
;   G_LOAD(ra0, rb0, 0);
;   if (nk > 1) G_LOAD(ra1, rb1, 1);
;   G_STORE(ra0, rb0, As, Bs);
;   __syncthreads();
;   for (int kt = 0; kt < nk; kt += 2) {
;     if (kt + 2 < nk) G_LOAD(ra0, rb0, kt + 2);
;     if (kt + 1 < nk) G_STORE(ra1, rb1, As1, Bs1);
;     G_COMPUTE(As, Bs);
;     __syncthreads();
;     if (kt + 1 < nk) {
;       if (kt + 3 < nk) G_LOAD(ra1, rb1, kt + 3);
;       if (kt + 2 < nk) G_STORE(ra0, rb0, As, Bs);
;       G_COMPUTE(As1, Bs1);
;       __syncthreads();
;     }
;   }
	v_lshl_add_u64 v[66:67], v[66:67], 0, s[96:97]
	s_add_u32 m0, s94, 0x0
	s_nop 1
	global_load_lds_dwordx4 v[66:67], off
	v_lshl_add_u64 v[68:69], v[68:69], 0, s[96:97]
	s_add_u32 m0, s94, 0x4000
	s_nop 1
	global_load_lds_dwordx4 v[68:69], off
	v_lshl_add_u64 v[70:71], v[70:71], 0, s[96:97]
	s_add_u32 m0, s94, 0x1000
	s_nop 1
	global_load_lds_dwordx4 v[70:71], off
	v_lshl_add_u64 v[72:73], v[72:73], 0, s[96:97]
	s_add_u32 m0, s94, 0x5000
	s_nop 1
	global_load_lds_dwordx4 v[72:73], off
	v_lshl_add_u64 v[74:75], v[74:75], 0, s[96:97]
	s_add_u32 m0, s94, 0x2000
	s_nop 1
	global_load_lds_dwordx4 v[74:75], off
	v_lshl_add_u64 v[76:77], v[76:77], 0, s[96:97]
	s_add_u32 m0, s94, 0x6000
	s_nop 1
	global_load_lds_dwordx4 v[76:77], off
	v_lshl_add_u64 v[80:81], v[80:81], 0, s[96:97]
	s_add_u32 m0, s94, 0x3000
	s_nop 1
	global_load_lds_dwordx4 v[80:81], off
	v_lshl_add_u64 v[78:79], v[78:79], 0, s[96:97]
	s_add_u32 m0, s94, 0x7000
	s_nop 1
	global_load_lds_dwordx4 v[78:79], off
	v_mfma_f32_32x32x16_bf16 v[0:15], v[114:117], v[110:113], v[0:15]
	ds_read_b128 v[88:91], v170 offset:32768
	ds_read_b128 v[92:95], v174 offset:49152
	ds_read_b128 v[98:101], v171 offset:32768
	ds_read_b128 v[102:105], v175 offset:49152
	ds_read_b128 v[106:109], v174 offset:53248
	ds_read_b128 v[110:113], v175 offset:53248
	s_waitcnt lgkmcnt(4)
	v_mfma_f32_32x32x16_bf16 v[48:63], v[88:91], v[92:95], v[48:63]
	s_waitcnt lgkmcnt(1)
	v_mfma_f32_32x32x16_bf16 v[32:47], v[88:91], v[106:109], v[32:47]
	ds_read_b128 v[88:91], v170 offset:36864
	ds_read_b128 v[114:117], v171 offset:36864
	s_waitcnt lgkmcnt(1)
	v_mfma_f32_32x32x16_bf16 v[16:31], v[88:91], v[92:95], v[16:31]
	v_mfma_f32_32x32x16_bf16 v[0:15], v[88:91], v[106:109], v[0:15]
	v_mfma_f32_32x32x16_bf16 v[48:63], v[98:101], v[102:105], v[48:63]
	v_mfma_f32_32x32x16_bf16 v[32:47], v[98:101], v[110:113], v[32:47]
	s_waitcnt lgkmcnt(0)
	v_mfma_f32_32x32x16_bf16 v[16:31], v[114:117], v[102:105], v[16:31]
	ds_read_b128 v[88:91], v172 offset:32768
	ds_read_b128 v[92:95], v176 offset:49152
	ds_read_b128 v[98:101], v173 offset:32768
	ds_read_b128 v[102:105], v177 offset:49152
	v_mfma_f32_32x32x16_bf16 v[0:15], v[114:117], v[110:113], v[0:15]
	ds_read_b128 v[106:109], v176 offset:53248
	ds_read_b128 v[110:113], v177 offset:53248
	s_waitcnt lgkmcnt(4)
	v_mfma_f32_32x32x16_bf16 v[48:63], v[88:91], v[92:95], v[48:63]
	s_waitcnt lgkmcnt(1)
	v_mfma_f32_32x32x16_bf16 v[32:47], v[88:91], v[106:109], v[32:47]
	ds_read_b128 v[88:91], v172 offset:36864
	ds_read_b128 v[114:117], v173 offset:36864
	s_waitcnt lgkmcnt(1)
	v_mfma_f32_32x32x16_bf16 v[16:31], v[88:91], v[92:95], v[16:31]
	v_mfma_f32_32x32x16_bf16 v[0:15], v[88:91], v[106:109], v[0:15]
	v_mfma_f32_32x32x16_bf16 v[48:63], v[98:101], v[102:105], v[48:63]
	v_mfma_f32_32x32x16_bf16 v[32:47], v[98:101], v[110:113], v[32:47]
	s_waitcnt lgkmcnt(0)
	v_mfma_f32_32x32x16_bf16 v[16:31], v[114:117], v[102:105], v[16:31]
	s_waitcnt vmcnt(0)
	s_barrier
	v_lshl_add_u64 v[66:67], v[66:67], 0, s[96:97]
	s_add_u32 m0, s94, 0x8000
	s_nop 1
	global_load_lds_dwordx4 v[66:67], off
	v_lshl_add_u64 v[68:69], v[68:69], 0, s[96:97]
	s_add_u32 m0, s94, 0xc000
	s_nop 1
	global_load_lds_dwordx4 v[68:69], off
	v_lshl_add_u64 v[70:71], v[70:71], 0, s[96:97]
	s_add_u32 m0, s94, 0x9000
	s_nop 1
	global_load_lds_dwordx4 v[70:71], off
	v_lshl_add_u64 v[72:73], v[72:73], 0, s[96:97]
	s_add_u32 m0, s94, 0xd000
	s_nop 1
	global_load_lds_dwordx4 v[72:73], off
	v_lshl_add_u64 v[74:75], v[74:75], 0, s[96:97]
	s_add_u32 m0, s94, 0xa000
	s_nop 1
	global_load_lds_dwordx4 v[74:75], off
	v_lshl_add_u64 v[76:77], v[76:77], 0, s[96:97]
	s_add_u32 m0, s94, 0xe000
	s_nop 1
	global_load_lds_dwordx4 v[76:77], off
	v_lshl_add_u64 v[80:81], v[80:81], 0, s[96:97]
	s_add_u32 m0, s94, 0xb000
	s_nop 1
	global_load_lds_dwordx4 v[80:81], off
	v_lshl_add_u64 v[78:79], v[78:79], 0, s[96:97]
	s_add_u32 m0, s94, 0xf000
	s_nop 1
	global_load_lds_dwordx4 v[78:79], off
	v_mfma_f32_32x32x16_bf16 v[0:15], v[114:117], v[110:113], v[0:15]
	ds_read_b128 v[88:91], v170 offset:0
	ds_read_b128 v[92:95], v174 offset:16384
	ds_read_b128 v[98:101], v171 offset:0
	ds_read_b128 v[102:105], v175 offset:16384
	ds_read_b128 v[106:109], v174 offset:20480
	ds_read_b128 v[110:113], v175 offset:20480
	s_waitcnt lgkmcnt(4)
	v_mfma_f32_32x32x16_bf16 v[48:63], v[88:91], v[92:95], v[48:63]
	s_waitcnt lgkmcnt(1)
	v_mfma_f32_32x32x16_bf16 v[32:47], v[88:91], v[106:109], v[32:47]
	ds_read_b128 v[88:91], v170 offset:4096
	ds_read_b128 v[114:117], v171 offset:4096
	s_waitcnt lgkmcnt(1)
	v_mfma_f32_32x32x16_bf16 v[16:31], v[88:91], v[92:95], v[16:31]
	v_mfma_f32_32x32x16_bf16 v[0:15], v[88:91], v[106:109], v[0:15]
	v_mfma_f32_32x32x16_bf16 v[48:63], v[98:101], v[102:105], v[48:63]
	v_mfma_f32_32x32x16_bf16 v[32:47], v[98:101], v[110:113], v[32:47]
	s_waitcnt lgkmcnt(0)
	v_mfma_f32_32x32x16_bf16 v[16:31], v[114:117], v[102:105], v[16:31]
	ds_read_b128 v[88:91], v172 offset:0
	ds_read_b128 v[92:95], v176 offset:16384
	ds_read_b128 v[98:101], v173 offset:0
	ds_read_b128 v[102:105], v177 offset:16384
	v_mfma_f32_32x32x16_bf16 v[0:15], v[114:117], v[110:113], v[0:15]
	ds_read_b128 v[106:109], v176 offset:20480
	ds_read_b128 v[110:113], v177 offset:20480
	s_waitcnt lgkmcnt(4)
	v_mfma_f32_32x32x16_bf16 v[48:63], v[88:91], v[92:95], v[48:63]
	s_waitcnt lgkmcnt(1)
	v_mfma_f32_32x32x16_bf16 v[32:47], v[88:91], v[106:109], v[32:47]
	ds_read_b128 v[88:91], v172 offset:4096
	ds_read_b128 v[114:117], v173 offset:4096
	s_waitcnt lgkmcnt(1)
	v_mfma_f32_32x32x16_bf16 v[16:31], v[88:91], v[92:95], v[16:31]
	v_mfma_f32_32x32x16_bf16 v[0:15], v[88:91], v[106:109], v[0:15]
	v_mfma_f32_32x32x16_bf16 v[48:63], v[98:101], v[102:105], v[48:63]
	v_mfma_f32_32x32x16_bf16 v[32:47], v[98:101], v[110:113], v[32:47]
	s_waitcnt lgkmcnt(0)
	v_mfma_f32_32x32x16_bf16 v[16:31], v[114:117], v[102:105], v[16:31]
	s_waitcnt vmcnt(0)
	s_barrier
;     ...
;   bf16* As1 = As + 2 * 128 * 72;
;   bf16* Bs1 = As1 + 128 * 72;
;   G_LOAD(ra0, rb0, 0);
;   if (nk > 1) G_LOAD(ra1, rb1, 1);
;   G_STORE(ra0, rb0, As, Bs);
;   __syncthreads();
;   for (int kt = 0; kt < nk; kt += 2) {
;     if (kt + 2 < nk) G_LOAD(ra0, rb0, kt + 2);
;     if (kt + 1 < nk) G_STORE(ra1, rb1, As1, Bs1);
;     G_COMPUTE(As, Bs);
;     __syncthreads();
;     if (kt + 1 < nk) {
;       if (kt + 3 < nk) G_LOAD(ra1, rb1, kt + 3);
;       if (kt + 2 < nk) G_STORE(ra0, rb0, As, Bs);
;       G_COMPUTE(As1, Bs1);
;       __syncthreads();
;     }
;   }
	v_lshl_add_u64 v[66:67], v[66:67], 0, s[96:97]
	s_add_u32 m0, s94, 0x0
	s_nop 1
	global_load_lds_dwordx4 v[66:67], off
	v_lshl_add_u64 v[68:69], v[68:69], 0, s[96:97]
	s_add_u32 m0, s94, 0x4000
	s_nop 1
	global_load_lds_dwordx4 v[68:69], off
	v_lshl_add_u64 v[70:71], v[70:71], 0, s[96:97]
	s_add_u32 m0, s94, 0x1000
	s_nop 1
	global_load_lds_dwordx4 v[70:71], off
	v_lshl_add_u64 v[72:73], v[72:73], 0, s[96:97]
	s_add_u32 m0, s94, 0x5000
	s_nop 1
	global_load_lds_dwordx4 v[72:73], off
	v_lshl_add_u64 v[74:75], v[74:75], 0, s[96:97]
	s_add_u32 m0, s94, 0x2000
	s_nop 1
	global_load_lds_dwordx4 v[74:75], off
	v_lshl_add_u64 v[76:77], v[76:77], 0, s[96:97]
	s_add_u32 m0, s94, 0x6000
	s_nop 1
	global_load_lds_dwordx4 v[76:77], off
	v_lshl_add_u64 v[80:81], v[80:81], 0, s[96:97]
	s_add_u32 m0, s94, 0x3000
	s_nop 1
	global_load_lds_dwordx4 v[80:81], off
	v_lshl_add_u64 v[78:79], v[78:79], 0, s[96:97]
	s_add_u32 m0, s94, 0x7000
	s_nop 1
	global_load_lds_dwordx4 v[78:79], off
	v_mfma_f32_32x32x16_bf16 v[0:15], v[114:117], v[110:113], v[0:15]
	ds_read_b128 v[88:91], v170 offset:32768
	ds_read_b128 v[92:95], v174 offset:49152
	ds_read_b128 v[98:101], v171 offset:32768
	ds_read_b128 v[102:105], v175 offset:49152
	ds_read_b128 v[106:109], v174 offset:53248
	ds_read_b128 v[110:113], v175 offset:53248
	s_waitcnt lgkmcnt(4)
	v_mfma_f32_32x32x16_bf16 v[48:63], v[88:91], v[92:95], v[48:63]
	s_waitcnt lgkmcnt(1)
	v_mfma_f32_32x32x16_bf16 v[32:47], v[88:91], v[106:109], v[32:47]
	ds_read_b128 v[88:91], v170 offset:36864
	ds_read_b128 v[114:117], v171 offset:36864
	s_waitcnt lgkmcnt(1)
	v_mfma_f32_32x32x16_bf16 v[16:31], v[88:91], v[92:95], v[16:31]
	v_mfma_f32_32x32x16_bf16 v[0:15], v[88:91], v[106:109], v[0:15]
	v_mfma_f32_32x32x16_bf16 v[48:63], v[98:101], v[102:105], v[48:63]
	v_mfma_f32_32x32x16_bf16 v[32:47], v[98:101], v[110:113], v[32:47]
	s_waitcnt lgkmcnt(0)
	v_mfma_f32_32x32x16_bf16 v[16:31], v[114:117], v[102:105], v[16:31]
	ds_read_b128 v[88:91], v172 offset:32768
	ds_read_b128 v[92:95], v176 offset:49152
	ds_read_b128 v[98:101], v173 offset:32768
	ds_read_b128 v[102:105], v177 offset:49152
	v_mfma_f32_32x32x16_bf16 v[0:15], v[114:117], v[110:113], v[0:15]
	ds_read_b128 v[106:109], v176 offset:53248
	ds_read_b128 v[110:113], v177 offset:53248
	s_waitcnt lgkmcnt(4)
	v_mfma_f32_32x32x16_bf16 v[48:63], v[88:91], v[92:95], v[48:63]
	s_waitcnt lgkmcnt(1)
	v_mfma_f32_32x32x16_bf16 v[32:47], v[88:91], v[106:109], v[32:47]
	ds_read_b128 v[88:91], v172 offset:36864
	ds_read_b128 v[114:117], v173 offset:36864
	s_waitcnt lgkmcnt(1)
	v_mfma_f32_32x32x16_bf16 v[16:31], v[88:91], v[92:95], v[16:31]
	v_mfma_f32_32x32x16_bf16 v[0:15], v[88:91], v[106:109], v[0:15]
	v_mfma_f32_32x32x16_bf16 v[48:63], v[98:101], v[102:105], v[48:63]
	v_mfma_f32_32x32x16_bf16 v[32:47], v[98:101], v[110:113], v[32:47]
	s_waitcnt lgkmcnt(0)
	v_mfma_f32_32x32x16_bf16 v[16:31], v[114:117], v[102:105], v[16:31]
	s_waitcnt vmcnt(0)
	s_barrier
	v_lshl_add_u64 v[66:67], v[66:67], 0, s[96:97]
	s_add_u32 m0, s94, 0x8000
	s_nop 1
	global_load_lds_dwordx4 v[66:67], off
	v_lshl_add_u64 v[68:69], v[68:69], 0, s[96:97]
	s_add_u32 m0, s94, 0xc000
	s_nop 1
	global_load_lds_dwordx4 v[68:69], off
	v_lshl_add_u64 v[70:71], v[70:71], 0, s[96:97]
	s_add_u32 m0, s94, 0x9000
	s_nop 1
	global_load_lds_dwordx4 v[70:71], off
	v_lshl_add_u64 v[72:73], v[72:73], 0, s[96:97]
	s_add_u32 m0, s94, 0xd000
	s_nop 1
	global_load_lds_dwordx4 v[72:73], off
	v_lshl_add_u64 v[74:75], v[74:75], 0, s[96:97]
	s_add_u32 m0, s94, 0xa000
	s_nop 1
	global_load_lds_dwordx4 v[74:75], off
	v_lshl_add_u64 v[76:77], v[76:77], 0, s[96:97]
	s_add_u32 m0, s94, 0xe000
	s_nop 1
	global_load_lds_dwordx4 v[76:77], off
	v_lshl_add_u64 v[80:81], v[80:81], 0, s[96:97]
	s_add_u32 m0, s94, 0xb000
	s_nop 1
	global_load_lds_dwordx4 v[80:81], off
	v_lshl_add_u64 v[78:79], v[78:79], 0, s[96:97]
	s_add_u32 m0, s94, 0xf000
	s_nop 1
	global_load_lds_dwordx4 v[78:79], off
	v_mfma_f32_32x32x16_bf16 v[0:15], v[114:117], v[110:113], v[0:15]
	ds_read_b128 v[88:91], v170 offset:0
	ds_read_b128 v[92:95], v174 offset:16384
	ds_read_b128 v[98:101], v171 offset:0
	ds_read_b128 v[102:105], v175 offset:16384
	ds_read_b128 v[106:109], v174 offset:20480
	ds_read_b128 v[110:113], v175 offset:20480
	s_waitcnt lgkmcnt(4)
	v_mfma_f32_32x32x16_bf16 v[48:63], v[88:91], v[92:95], v[48:63]
	s_waitcnt lgkmcnt(1)
	v_mfma_f32_32x32x16_bf16 v[32:47], v[88:91], v[106:109], v[32:47]
	ds_read_b128 v[88:91], v170 offset:4096
	ds_read_b128 v[114:117], v171 offset:4096
	s_waitcnt lgkmcnt(1)
	v_mfma_f32_32x32x16_bf16 v[16:31], v[88:91], v[92:95], v[16:31]
	v_mfma_f32_32x32x16_bf16 v[0:15], v[88:91], v[106:109], v[0:15]
	v_mfma_f32_32x32x16_bf16 v[48:63], v[98:101], v[102:105], v[48:63]
	v_mfma_f32_32x32x16_bf16 v[32:47], v[98:101], v[110:113], v[32:47]
	s_waitcnt lgkmcnt(0)
	v_mfma_f32_32x32x16_bf16 v[16:31], v[114:117], v[102:105], v[16:31]
	ds_read_b128 v[88:91], v172 offset:0
	ds_read_b128 v[92:95], v176 offset:16384
	ds_read_b128 v[98:101], v173 offset:0
	ds_read_b128 v[102:105], v177 offset:16384
	v_mfma_f32_32x32x16_bf16 v[0:15], v[114:117], v[110:113], v[0:15]
	ds_read_b128 v[106:109], v176 offset:20480
	ds_read_b128 v[110:113], v177 offset:20480
	s_waitcnt lgkmcnt(4)
	v_mfma_f32_32x32x16_bf16 v[48:63], v[88:91], v[92:95], v[48:63]
	s_waitcnt lgkmcnt(1)
	v_mfma_f32_32x32x16_bf16 v[32:47], v[88:91], v[106:109], v[32:47]
	ds_read_b128 v[88:91], v172 offset:4096
	ds_read_b128 v[114:117], v173 offset:4096
	s_waitcnt lgkmcnt(1)
	v_mfma_f32_32x32x16_bf16 v[16:31], v[88:91], v[92:95], v[16:31]
	v_mfma_f32_32x32x16_bf16 v[0:15], v[88:91], v[106:109], v[0:15]
	v_mfma_f32_32x32x16_bf16 v[48:63], v[98:101], v[102:105], v[48:63]
	v_mfma_f32_32x32x16_bf16 v[32:47], v[98:101], v[110:113], v[32:47]
	s_waitcnt lgkmcnt(0)
	v_mfma_f32_32x32x16_bf16 v[16:31], v[114:117], v[102:105], v[16:31]
	s_waitcnt vmcnt(0)
	s_barrier
;     ...
;   bf16* As1 = As + 2 * 128 * 72;
;   bf16* Bs1 = As1 + 128 * 72;
;   G_LOAD(ra0, rb0, 0);
;   if (nk > 1) G_LOAD(ra1, rb1, 1);
;   G_STORE(ra0, rb0, As, Bs);
;   __syncthreads();
;   for (int kt = 0; kt < nk; kt += 2) {
;     if (kt + 2 < nk) G_LOAD(ra0, rb0, kt + 2);
;     if (kt + 1 < nk) G_STORE(ra1, rb1, As1, Bs1);
;     G_COMPUTE(As, Bs);
;     __syncthreads();
;     if (kt + 1 < nk) {
;       if (kt + 3 < nk) G_LOAD(ra1, rb1, kt + 3);
;       if (kt + 2 < nk) G_STORE(ra0, rb0, As, Bs);
;       G_COMPUTE(As1, Bs1);
;       __syncthreads();
;     }
;   }
	v_lshl_add_u64 v[66:67], v[66:67], 0, s[96:97]
	s_add_u32 m0, s94, 0x0
	s_nop 1
	global_load_lds_dwordx4 v[66:67], off
	v_lshl_add_u64 v[68:69], v[68:69], 0, s[96:97]
	s_add_u32 m0, s94, 0x4000
	s_nop 1
	global_load_lds_dwordx4 v[68:69], off
	v_lshl_add_u64 v[70:71], v[70:71], 0, s[96:97]
	s_add_u32 m0, s94, 0x1000
	s_nop 1
	global_load_lds_dwordx4 v[70:71], off
	v_lshl_add_u64 v[72:73], v[72:73], 0, s[96:97]
	s_add_u32 m0, s94, 0x5000
	s_nop 1
	global_load_lds_dwordx4 v[72:73], off
	v_lshl_add_u64 v[74:75], v[74:75], 0, s[96:97]
	s_add_u32 m0, s94, 0x2000
	s_nop 1
	global_load_lds_dwordx4 v[74:75], off
	v_lshl_add_u64 v[76:77], v[76:77], 0, s[96:97]
	s_add_u32 m0, s94, 0x6000
	s_nop 1
	global_load_lds_dwordx4 v[76:77], off
	v_lshl_add_u64 v[80:81], v[80:81], 0, s[96:97]
	s_add_u32 m0, s94, 0x3000
	s_nop 1
	global_load_lds_dwordx4 v[80:81], off
	v_lshl_add_u64 v[78:79], v[78:79], 0, s[96:97]
	s_add_u32 m0, s94, 0x7000
	s_nop 1
	global_load_lds_dwordx4 v[78:79], off
	v_mfma_f32_32x32x16_bf16 v[0:15], v[114:117], v[110:113], v[0:15]
	ds_read_b128 v[88:91], v170 offset:32768
	ds_read_b128 v[92:95], v174 offset:49152
	ds_read_b128 v[98:101], v171 offset:32768
	ds_read_b128 v[102:105], v175 offset:49152
	ds_read_b128 v[106:109], v174 offset:53248
	ds_read_b128 v[110:113], v175 offset:53248
	s_waitcnt lgkmcnt(4)
	v_mfma_f32_32x32x16_bf16 v[48:63], v[88:91], v[92:95], v[48:63]
	s_waitcnt lgkmcnt(1)
	v_mfma_f32_32x32x16_bf16 v[32:47], v[88:91], v[106:109], v[32:47]
	ds_read_b128 v[88:91], v170 offset:36864
	ds_read_b128 v[114:117], v171 offset:36864
	s_waitcnt lgkmcnt(1)
	v_mfma_f32_32x32x16_bf16 v[16:31], v[88:91], v[92:95], v[16:31]
	v_mfma_f32_32x32x16_bf16 v[0:15], v[88:91], v[106:109], v[0:15]
	v_mfma_f32_32x32x16_bf16 v[48:63], v[98:101], v[102:105], v[48:63]
	v_mfma_f32_32x32x16_bf16 v[32:47], v[98:101], v[110:113], v[32:47]
	s_waitcnt lgkmcnt(0)
	v_mfma_f32_32x32x16_bf16 v[16:31], v[114:117], v[102:105], v[16:31]
	ds_read_b128 v[88:91], v172 offset:32768
	ds_read_b128 v[92:95], v176 offset:49152
	ds_read_b128 v[98:101], v173 offset:32768
	ds_read_b128 v[102:105], v177 offset:49152
	v_mfma_f32_32x32x16_bf16 v[0:15], v[114:117], v[110:113], v[0:15]
	ds_read_b128 v[106:109], v176 offset:53248
	ds_read_b128 v[110:113], v177 offset:53248
	s_waitcnt lgkmcnt(4)
	v_mfma_f32_32x32x16_bf16 v[48:63], v[88:91], v[92:95], v[48:63]
	s_waitcnt lgkmcnt(1)
	v_mfma_f32_32x32x16_bf16 v[32:47], v[88:91], v[106:109], v[32:47]
	ds_read_b128 v[88:91], v172 offset:36864
	ds_read_b128 v[114:117], v173 offset:36864
	s_waitcnt lgkmcnt(1)
	v_mfma_f32_32x32x16_bf16 v[16:31], v[88:91], v[92:95], v[16:31]
	v_mfma_f32_32x32x16_bf16 v[0:15], v[88:91], v[106:109], v[0:15]
	v_mfma_f32_32x32x16_bf16 v[48:63], v[98:101], v[102:105], v[48:63]
	v_mfma_f32_32x32x16_bf16 v[32:47], v[98:101], v[110:113], v[32:47]
	s_waitcnt lgkmcnt(0)
	v_mfma_f32_32x32x16_bf16 v[16:31], v[114:117], v[102:105], v[16:31]
	s_waitcnt vmcnt(0)
	s_barrier
	v_lshl_add_u64 v[66:67], v[66:67], 0, s[96:97]
	s_add_u32 m0, s94, 0x8000
	s_nop 1
	global_load_lds_dwordx4 v[66:67], off
	v_lshl_add_u64 v[68:69], v[68:69], 0, s[96:97]
	s_add_u32 m0, s94, 0xc000
	s_nop 1
	global_load_lds_dwordx4 v[68:69], off
	v_lshl_add_u64 v[70:71], v[70:71], 0, s[96:97]
	s_add_u32 m0, s94, 0x9000
	s_nop 1
	global_load_lds_dwordx4 v[70:71], off
	v_lshl_add_u64 v[72:73], v[72:73], 0, s[96:97]
	s_add_u32 m0, s94, 0xd000
	s_nop 1
	global_load_lds_dwordx4 v[72:73], off
	v_lshl_add_u64 v[74:75], v[74:75], 0, s[96:97]
	s_add_u32 m0, s94, 0xa000
	s_nop 1
	global_load_lds_dwordx4 v[74:75], off
	v_lshl_add_u64 v[76:77], v[76:77], 0, s[96:97]
	s_add_u32 m0, s94, 0xe000
	s_nop 1
	global_load_lds_dwordx4 v[76:77], off
	v_lshl_add_u64 v[80:81], v[80:81], 0, s[96:97]
	s_add_u32 m0, s94, 0xb000
	s_nop 1
	global_load_lds_dwordx4 v[80:81], off
	v_lshl_add_u64 v[78:79], v[78:79], 0, s[96:97]
	s_add_u32 m0, s94, 0xf000
	s_nop 1
	global_load_lds_dwordx4 v[78:79], off
	v_mfma_f32_32x32x16_bf16 v[0:15], v[114:117], v[110:113], v[0:15]
	ds_read_b128 v[88:91], v170 offset:0
	ds_read_b128 v[92:95], v174 offset:16384
	ds_read_b128 v[98:101], v171 offset:0
	ds_read_b128 v[102:105], v175 offset:16384
	ds_read_b128 v[106:109], v174 offset:20480
	ds_read_b128 v[110:113], v175 offset:20480
	s_waitcnt lgkmcnt(4)
	v_mfma_f32_32x32x16_bf16 v[48:63], v[88:91], v[92:95], v[48:63]
	s_waitcnt lgkmcnt(1)
	v_mfma_f32_32x32x16_bf16 v[32:47], v[88:91], v[106:109], v[32:47]
	ds_read_b128 v[88:91], v170 offset:4096
	ds_read_b128 v[114:117], v171 offset:4096
	s_waitcnt lgkmcnt(1)
	v_mfma_f32_32x32x16_bf16 v[16:31], v[88:91], v[92:95], v[16:31]
	v_mfma_f32_32x32x16_bf16 v[0:15], v[88:91], v[106:109], v[0:15]
	v_mfma_f32_32x32x16_bf16 v[48:63], v[98:101], v[102:105], v[48:63]
	v_mfma_f32_32x32x16_bf16 v[32:47], v[98:101], v[110:113], v[32:47]
	s_waitcnt lgkmcnt(0)
	v_mfma_f32_32x32x16_bf16 v[16:31], v[114:117], v[102:105], v[16:31]
	ds_read_b128 v[88:91], v172 offset:0
	ds_read_b128 v[92:95], v176 offset:16384
	ds_read_b128 v[98:101], v173 offset:0
	ds_read_b128 v[102:105], v177 offset:16384
	v_mfma_f32_32x32x16_bf16 v[0:15], v[114:117], v[110:113], v[0:15]
	ds_read_b128 v[106:109], v176 offset:20480
	ds_read_b128 v[110:113], v177 offset:20480
	s_waitcnt lgkmcnt(4)
	v_mfma_f32_32x32x16_bf16 v[48:63], v[88:91], v[92:95], v[48:63]
	s_waitcnt lgkmcnt(1)
	v_mfma_f32_32x32x16_bf16 v[32:47], v[88:91], v[106:109], v[32:47]
	ds_read_b128 v[88:91], v172 offset:4096
	ds_read_b128 v[114:117], v173 offset:4096
	s_waitcnt lgkmcnt(1)
	v_mfma_f32_32x32x16_bf16 v[16:31], v[88:91], v[92:95], v[16:31]
	v_mfma_f32_32x32x16_bf16 v[0:15], v[88:91], v[106:109], v[0:15]
	v_mfma_f32_32x32x16_bf16 v[48:63], v[98:101], v[102:105], v[48:63]
	v_mfma_f32_32x32x16_bf16 v[32:47], v[98:101], v[110:113], v[32:47]
	s_waitcnt lgkmcnt(0)
	v_mfma_f32_32x32x16_bf16 v[16:31], v[114:117], v[102:105], v[16:31]
	s_waitcnt vmcnt(0)
	s_barrier
;     ...
;   bf16* As1 = As + 2 * 128 * 72;
;   bf16* Bs1 = As1 + 128 * 72;
;   G_LOAD(ra0, rb0, 0);
;   if (nk > 1) G_LOAD(ra1, rb1, 1);
;   G_STORE(ra0, rb0, As, Bs);
;   __syncthreads();
;   for (int kt = 0; kt < nk; kt += 2) {
;     if (kt + 2 < nk) G_LOAD(ra0, rb0, kt + 2);
;     if (kt + 1 < nk) G_STORE(ra1, rb1, As1, Bs1);
;     G_COMPUTE(As, Bs);
;     __syncthreads();
;     if (kt + 1 < nk) {
;       if (kt + 3 < nk) G_LOAD(ra1, rb1, kt + 3);
;       if (kt + 2 < nk) G_STORE(ra0, rb0, As, Bs);
;       G_COMPUTE(As1, Bs1);
;       __syncthreads();
;     }
;   }
	v_lshl_add_u64 v[66:67], v[66:67], 0, s[96:97]
	s_add_u32 m0, s94, 0x0
	s_nop 1
	global_load_lds_dwordx4 v[66:67], off
	v_lshl_add_u64 v[68:69], v[68:69], 0, s[96:97]
	s_add_u32 m0, s94, 0x4000
	s_nop 1
	global_load_lds_dwordx4 v[68:69], off
	v_lshl_add_u64 v[70:71], v[70:71], 0, s[96:97]
	s_add_u32 m0, s94, 0x1000
	s_nop 1
	global_load_lds_dwordx4 v[70:71], off
	v_lshl_add_u64 v[72:73], v[72:73], 0, s[96:97]
	s_add_u32 m0, s94, 0x5000
	s_nop 1
	global_load_lds_dwordx4 v[72:73], off
	v_lshl_add_u64 v[74:75], v[74:75], 0, s[96:97]
	s_add_u32 m0, s94, 0x2000
	s_nop 1
	global_load_lds_dwordx4 v[74:75], off
	v_lshl_add_u64 v[76:77], v[76:77], 0, s[96:97]
	s_add_u32 m0, s94, 0x6000
	s_nop 1
	global_load_lds_dwordx4 v[76:77], off
	v_lshl_add_u64 v[80:81], v[80:81], 0, s[96:97]
	s_add_u32 m0, s94, 0x3000
	s_nop 1
	global_load_lds_dwordx4 v[80:81], off
	v_lshl_add_u64 v[78:79], v[78:79], 0, s[96:97]
	s_add_u32 m0, s94, 0x7000
	s_nop 1
	global_load_lds_dwordx4 v[78:79], off
	v_mfma_f32_32x32x16_bf16 v[0:15], v[114:117], v[110:113], v[0:15]
	ds_read_b128 v[88:91], v170 offset:32768
	ds_read_b128 v[92:95], v174 offset:49152
	ds_read_b128 v[98:101], v171 offset:32768
	ds_read_b128 v[102:105], v175 offset:49152
	ds_read_b128 v[106:109], v174 offset:53248
	ds_read_b128 v[110:113], v175 offset:53248
	s_waitcnt lgkmcnt(4)
	v_mfma_f32_32x32x16_bf16 v[48:63], v[88:91], v[92:95], v[48:63]
	s_waitcnt lgkmcnt(1)
	v_mfma_f32_32x32x16_bf16 v[32:47], v[88:91], v[106:109], v[32:47]
	ds_read_b128 v[88:91], v170 offset:36864
	ds_read_b128 v[114:117], v171 offset:36864
	s_waitcnt lgkmcnt(1)
	v_mfma_f32_32x32x16_bf16 v[16:31], v[88:91], v[92:95], v[16:31]
	v_mfma_f32_32x32x16_bf16 v[0:15], v[88:91], v[106:109], v[0:15]
	v_mfma_f32_32x32x16_bf16 v[48:63], v[98:101], v[102:105], v[48:63]
	v_mfma_f32_32x32x16_bf16 v[32:47], v[98:101], v[110:113], v[32:47]
	s_waitcnt lgkmcnt(0)
	v_mfma_f32_32x32x16_bf16 v[16:31], v[114:117], v[102:105], v[16:31]
	ds_read_b128 v[88:91], v172 offset:32768
	ds_read_b128 v[92:95], v176 offset:49152
	ds_read_b128 v[98:101], v173 offset:32768
	ds_read_b128 v[102:105], v177 offset:49152
	v_mfma_f32_32x32x16_bf16 v[0:15], v[114:117], v[110:113], v[0:15]
	ds_read_b128 v[106:109], v176 offset:53248
	ds_read_b128 v[110:113], v177 offset:53248
	s_waitcnt lgkmcnt(4)
	v_mfma_f32_32x32x16_bf16 v[48:63], v[88:91], v[92:95], v[48:63]
	s_waitcnt lgkmcnt(1)
	v_mfma_f32_32x32x16_bf16 v[32:47], v[88:91], v[106:109], v[32:47]
	ds_read_b128 v[88:91], v172 offset:36864
	ds_read_b128 v[114:117], v173 offset:36864
	s_waitcnt lgkmcnt(1)
	v_mfma_f32_32x32x16_bf16 v[16:31], v[88:91], v[92:95], v[16:31]
	v_mfma_f32_32x32x16_bf16 v[0:15], v[88:91], v[106:109], v[0:15]
	v_mfma_f32_32x32x16_bf16 v[48:63], v[98:101], v[102:105], v[48:63]
	v_mfma_f32_32x32x16_bf16 v[32:47], v[98:101], v[110:113], v[32:47]
	s_waitcnt lgkmcnt(0)
	v_mfma_f32_32x32x16_bf16 v[16:31], v[114:117], v[102:105], v[16:31]
	s_waitcnt vmcnt(0)
	s_barrier
	v_lshl_add_u64 v[66:67], v[66:67], 0, s[96:97]
	s_add_u32 m0, s94, 0x8000
	s_nop 1
	global_load_lds_dwordx4 v[66:67], off
	v_lshl_add_u64 v[68:69], v[68:69], 0, s[96:97]
	s_add_u32 m0, s94, 0xc000
	s_nop 1
	global_load_lds_dwordx4 v[68:69], off
	v_lshl_add_u64 v[70:71], v[70:71], 0, s[96:97]
	s_add_u32 m0, s94, 0x9000
	s_nop 1
	global_load_lds_dwordx4 v[70:71], off
	v_lshl_add_u64 v[72:73], v[72:73], 0, s[96:97]
	s_add_u32 m0, s94, 0xd000
	s_nop 1
	global_load_lds_dwordx4 v[72:73], off
	v_lshl_add_u64 v[74:75], v[74:75], 0, s[96:97]
	s_add_u32 m0, s94, 0xa000
	s_nop 1
	global_load_lds_dwordx4 v[74:75], off
	v_lshl_add_u64 v[76:77], v[76:77], 0, s[96:97]
	s_add_u32 m0, s94, 0xe000
	s_nop 1
	global_load_lds_dwordx4 v[76:77], off
	v_lshl_add_u64 v[80:81], v[80:81], 0, s[96:97]
	s_add_u32 m0, s94, 0xb000
	s_nop 1
	global_load_lds_dwordx4 v[80:81], off
	v_lshl_add_u64 v[78:79], v[78:79], 0, s[96:97]
	s_add_u32 m0, s94, 0xf000
	s_nop 1
	global_load_lds_dwordx4 v[78:79], off
	v_mfma_f32_32x32x16_bf16 v[0:15], v[114:117], v[110:113], v[0:15]
	ds_read_b128 v[88:91], v170 offset:0
	ds_read_b128 v[92:95], v174 offset:16384
	ds_read_b128 v[98:101], v171 offset:0
	ds_read_b128 v[102:105], v175 offset:16384
	ds_read_b128 v[106:109], v174 offset:20480
	ds_read_b128 v[110:113], v175 offset:20480
	s_waitcnt lgkmcnt(4)
	v_mfma_f32_32x32x16_bf16 v[48:63], v[88:91], v[92:95], v[48:63]
	s_waitcnt lgkmcnt(1)
	v_mfma_f32_32x32x16_bf16 v[32:47], v[88:91], v[106:109], v[32:47]
	ds_read_b128 v[88:91], v170 offset:4096
	ds_read_b128 v[114:117], v171 offset:4096
	s_waitcnt lgkmcnt(1)
	v_mfma_f32_32x32x16_bf16 v[16:31], v[88:91], v[92:95], v[16:31]
	v_mfma_f32_32x32x16_bf16 v[0:15], v[88:91], v[106:109], v[0:15]
	v_mfma_f32_32x32x16_bf16 v[48:63], v[98:101], v[102:105], v[48:63]
	v_mfma_f32_32x32x16_bf16 v[32:47], v[98:101], v[110:113], v[32:47]
	s_waitcnt lgkmcnt(0)
	v_mfma_f32_32x32x16_bf16 v[16:31], v[114:117], v[102:105], v[16:31]
	ds_read_b128 v[88:91], v172 offset:0
	ds_read_b128 v[92:95], v176 offset:16384
	ds_read_b128 v[98:101], v173 offset:0
	ds_read_b128 v[102:105], v177 offset:16384
	v_mfma_f32_32x32x16_bf16 v[0:15], v[114:117], v[110:113], v[0:15]
	ds_read_b128 v[106:109], v176 offset:20480
	ds_read_b128 v[110:113], v177 offset:20480
	s_waitcnt lgkmcnt(4)
	v_mfma_f32_32x32x16_bf16 v[48:63], v[88:91], v[92:95], v[48:63]
	s_waitcnt lgkmcnt(1)
	v_mfma_f32_32x32x16_bf16 v[32:47], v[88:91], v[106:109], v[32:47]
	ds_read_b128 v[88:91], v172 offset:4096
	ds_read_b128 v[114:117], v173 offset:4096
	s_waitcnt lgkmcnt(1)
	v_mfma_f32_32x32x16_bf16 v[16:31], v[88:91], v[92:95], v[16:31]
	v_mfma_f32_32x32x16_bf16 v[0:15], v[88:91], v[106:109], v[0:15]
	v_mfma_f32_32x32x16_bf16 v[48:63], v[98:101], v[102:105], v[48:63]
	v_mfma_f32_32x32x16_bf16 v[32:47], v[98:101], v[110:113], v[32:47]
	s_waitcnt lgkmcnt(0)
	v_mfma_f32_32x32x16_bf16 v[16:31], v[114:117], v[102:105], v[16:31]
	s_waitcnt vmcnt(0)
	s_barrier
;     ...
;   bf16* As1 = As + 2 * 128 * 72;
;   bf16* Bs1 = As1 + 128 * 72;
;   G_LOAD(ra0, rb0, 0);
;   if (nk > 1) G_LOAD(ra1, rb1, 1);
;   G_STORE(ra0, rb0, As, Bs);
;   __syncthreads();
;   for (int kt = 0; kt < nk; kt += 2) {
;     if (kt + 2 < nk) G_LOAD(ra0, rb0, kt + 2);
;     if (kt + 1 < nk) G_STORE(ra1, rb1, As1, Bs1);
;     G_COMPUTE(As, Bs);
;     __syncthreads();
;     if (kt + 1 < nk) {
;       if (kt + 3 < nk) G_LOAD(ra1, rb1, kt + 3);
;       if (kt + 2 < nk) G_STORE(ra0, rb0, As, Bs);
;       G_COMPUTE(As1, Bs1);
;       __syncthreads();
;     }
;   }
	v_lshl_add_u64 v[66:67], v[66:67], 0, s[96:97]
	s_add_u32 m0, s94, 0x0
	s_nop 1
	global_load_lds_dwordx4 v[66:67], off
	v_lshl_add_u64 v[68:69], v[68:69], 0, s[96:97]
	s_add_u32 m0, s94, 0x4000
	s_nop 1
	global_load_lds_dwordx4 v[68:69], off
	v_lshl_add_u64 v[70:71], v[70:71], 0, s[96:97]
	s_add_u32 m0, s94, 0x1000
	s_nop 1
	global_load_lds_dwordx4 v[70:71], off
	v_lshl_add_u64 v[72:73], v[72:73], 0, s[96:97]
	s_add_u32 m0, s94, 0x5000
	s_nop 1
	global_load_lds_dwordx4 v[72:73], off
	v_lshl_add_u64 v[74:75], v[74:75], 0, s[96:97]
	s_add_u32 m0, s94, 0x2000
	s_nop 1
	global_load_lds_dwordx4 v[74:75], off
	v_lshl_add_u64 v[76:77], v[76:77], 0, s[96:97]
	s_add_u32 m0, s94, 0x6000
	s_nop 1
	global_load_lds_dwordx4 v[76:77], off
	v_lshl_add_u64 v[80:81], v[80:81], 0, s[96:97]
	s_add_u32 m0, s94, 0x3000
	s_nop 1
	global_load_lds_dwordx4 v[80:81], off
	v_lshl_add_u64 v[78:79], v[78:79], 0, s[96:97]
	s_add_u32 m0, s94, 0x7000
	s_nop 1
	global_load_lds_dwordx4 v[78:79], off
	v_mfma_f32_32x32x16_bf16 v[0:15], v[114:117], v[110:113], v[0:15]
	ds_read_b128 v[88:91], v170 offset:32768
	ds_read_b128 v[92:95], v174 offset:49152
	ds_read_b128 v[98:101], v171 offset:32768
	ds_read_b128 v[102:105], v175 offset:49152
	ds_read_b128 v[106:109], v174 offset:53248
	ds_read_b128 v[110:113], v175 offset:53248
	s_waitcnt lgkmcnt(4)
	v_mfma_f32_32x32x16_bf16 v[48:63], v[88:91], v[92:95], v[48:63]
	s_waitcnt lgkmcnt(1)
	v_mfma_f32_32x32x16_bf16 v[32:47], v[88:91], v[106:109], v[32:47]
	ds_read_b128 v[88:91], v170 offset:36864
	ds_read_b128 v[114:117], v171 offset:36864
	s_waitcnt lgkmcnt(1)
	v_mfma_f32_32x32x16_bf16 v[16:31], v[88:91], v[92:95], v[16:31]
	v_mfma_f32_32x32x16_bf16 v[0:15], v[88:91], v[106:109], v[0:15]
	v_mfma_f32_32x32x16_bf16 v[48:63], v[98:101], v[102:105], v[48:63]
	v_mfma_f32_32x32x16_bf16 v[32:47], v[98:101], v[110:113], v[32:47]
	s_waitcnt lgkmcnt(0)
	v_mfma_f32_32x32x16_bf16 v[16:31], v[114:117], v[102:105], v[16:31]
	ds_read_b128 v[88:91], v172 offset:32768
	ds_read_b128 v[92:95], v176 offset:49152
	ds_read_b128 v[98:101], v173 offset:32768
	ds_read_b128 v[102:105], v177 offset:49152
	v_mfma_f32_32x32x16_bf16 v[0:15], v[114:117], v[110:113], v[0:15]
	ds_read_b128 v[106:109], v176 offset:53248
	ds_read_b128 v[110:113], v177 offset:53248
	s_waitcnt lgkmcnt(4)
	v_mfma_f32_32x32x16_bf16 v[48:63], v[88:91], v[92:95], v[48:63]
	s_waitcnt lgkmcnt(1)
	v_mfma_f32_32x32x16_bf16 v[32:47], v[88:91], v[106:109], v[32:47]
	ds_read_b128 v[88:91], v172 offset:36864
	ds_read_b128 v[114:117], v173 offset:36864
	s_waitcnt lgkmcnt(1)
	v_mfma_f32_32x32x16_bf16 v[16:31], v[88:91], v[92:95], v[16:31]
	v_mfma_f32_32x32x16_bf16 v[0:15], v[88:91], v[106:109], v[0:15]
	v_mfma_f32_32x32x16_bf16 v[48:63], v[98:101], v[102:105], v[48:63]
	v_mfma_f32_32x32x16_bf16 v[32:47], v[98:101], v[110:113], v[32:47]
	s_nop 0
	s_nop 0
	s_nop 0
	s_nop 0
	s_nop 0
	s_nop 0
	s_nop 0
	s_waitcnt lgkmcnt(0)
	s_waitcnt vmcnt(0)
	s_barrier
	v_lshl_add_u64 v[66:67], v[66:67], 0, s[96:97]
	s_add_u32 m0, s94, 0x8000
	s_nop 1
	global_load_lds_dwordx4 v[66:67], off
	v_lshl_add_u64 v[68:69], v[68:69], 0, s[96:97]
	s_add_u32 m0, s94, 0xc000
	s_nop 1
	global_load_lds_dwordx4 v[68:69], off
	v_lshl_add_u64 v[70:71], v[70:71], 0, s[96:97]
	s_add_u32 m0, s94, 0x9000
	s_nop 1
	global_load_lds_dwordx4 v[70:71], off
	v_lshl_add_u64 v[72:73], v[72:73], 0, s[96:97]
	s_add_u32 m0, s94, 0xd000
	s_nop 1
	global_load_lds_dwordx4 v[72:73], off
	v_lshl_add_u64 v[74:75], v[74:75], 0, s[96:97]
	s_add_u32 m0, s94, 0xa000
	s_nop 1
	global_load_lds_dwordx4 v[74:75], off
	v_lshl_add_u64 v[76:77], v[76:77], 0, s[96:97]
	s_add_u32 m0, s94, 0xe000
	s_nop 1
	global_load_lds_dwordx4 v[76:77], off
	v_lshl_add_u64 v[80:81], v[80:81], 0, s[96:97]
	s_add_u32 m0, s94, 0xb000
	s_nop 1
	global_load_lds_dwordx4 v[80:81], off
	v_lshl_add_u64 v[78:79], v[78:79], 0, s[96:97]
	s_add_u32 m0, s94, 0xf000
	s_nop 1
	global_load_lds_dwordx4 v[78:79], off
	v_mfma_f32_32x32x16_bf16 v[16:31], v[114:117], v[102:105], v[16:31]
	ds_read_b128 v[66:69], v170 offset:0
	ds_read_b128 v[70:73], v174 offset:16384
	ds_read_b128 v[74:77], v171 offset:0
	ds_read_b128 v[78:81], v175 offset:16384
	ds_read_b128 v[88:91], v174 offset:20480
	ds_read_b128 v[92:95], v175 offset:20480
	v_mfma_f32_32x32x16_bf16 v[0:15], v[114:117], v[110:113], v[0:15]
	s_waitcnt lgkmcnt(4)
	v_mfma_f32_32x32x16_bf16 v[48:63], v[66:69], v[70:73], v[48:63]
	s_waitcnt lgkmcnt(1)
	v_mfma_f32_32x32x16_bf16 v[32:47], v[66:69], v[88:91], v[32:47]
	ds_read_b128 v[66:69], v170 offset:4096
	ds_read_b128 v[98:101], v171 offset:4096
	s_waitcnt lgkmcnt(1)
	v_mfma_f32_32x32x16_bf16 v[16:31], v[66:69], v[70:73], v[16:31]
	v_mfma_f32_32x32x16_bf16 v[0:15], v[66:69], v[88:91], v[0:15]
	v_mfma_f32_32x32x16_bf16 v[48:63], v[74:77], v[78:81], v[48:63]
	v_mfma_f32_32x32x16_bf16 v[32:47], v[74:77], v[92:95], v[32:47]
	s_waitcnt lgkmcnt(0)
	v_mfma_f32_32x32x16_bf16 v[16:31], v[98:101], v[78:81], v[16:31]
	ds_read_b128 v[66:69], v172 offset:0
	ds_read_b128 v[70:73], v176 offset:16384
	ds_read_b128 v[74:77], v173 offset:0
	ds_read_b128 v[78:81], v177 offset:16384
	v_mfma_f32_32x32x16_bf16 v[0:15], v[98:101], v[92:95], v[0:15]
	ds_read_b128 v[88:91], v176 offset:20480
	ds_read_b128 v[92:95], v177 offset:20480
	s_waitcnt lgkmcnt(4)
	v_mfma_f32_32x32x16_bf16 v[48:63], v[66:69], v[70:73], v[48:63]
	s_waitcnt lgkmcnt(1)
	v_mfma_f32_32x32x16_bf16 v[32:47], v[66:69], v[88:91], v[32:47]
	ds_read_b128 v[66:69], v172 offset:4096
	ds_read_b128 v[98:101], v173 offset:4096
	s_waitcnt lgkmcnt(0)
	s_waitcnt vmcnt(0)
	s_barrier
; #define PW(T, off) ((T*)(lndp(p.ws) + (off)))
; DEVI float bf2f(bf16 h) { return __uint_as_float(((unsigned)h) << 16); }
; DEVI int accrow(int r, int lane) { return (r & 3) + 8 * (r >> 2) + 4 * (lane >> 5); }
; template <int EPI>
; DEVI void gemm_epi(const Params& p, const GJob& jb, f32x16 (&acc)[2][2], int rbase, int cbase, int lane) {
;     ...
;   for (int i = 0; i < 2; ++i) {
; #pragma unroll
;     for (int r = 0; r < 16; ++r) {
;       const int row = rbase + i * 32 + accrow(r, lane);
;       if (row < M) {
; #pragma unroll
;         for (int j = 0; j < 2; ++j) {
;           const int col = cbase + j * 32 + (lane & 31);
;           const float v = acc[i][j][r];
;           if (EPI == EPI_SSD_IN) {
;             if (col < 2048) ((bf16*)(ar + S_ZB))[(size_t)row * 2048 + col] = f2bf(v);
;             else if (col < 6144) ((bf16*)(ar + S_XBC))[(size_t)row * 4096 + col - 2048] = f2bf(v);
;             else if (col < 6176) ((float*)(ar + S_DTRAW))[(size_t)row * 32 + col - 6144] = v;
;           } else if (EPI == EPI_RESID) {
;             PW(bf16, W_Z)[(size_t)row * 1024 + col] = f2bf(ALPHA * bf2f(PW(bf16, W_Xb)[(size_t)row * 1024 + col]) + v);
;           } else if (EPI == EPI_GU) {
;             ((bf16*)(ar + F_GU))[(size_t)row * 5632 + col] = f2bf(v);
;           } else if (EPI == EPI_BF16) {
;             ((bf16*)jb.of)[(size_t)row * 1024 + col] = f2bf(v);
;     ...
;     G_COMPUTE(As, Bs);
;     __syncthreads();
;     if (kt + 1 < nk) {
;       if (kt + 3 < nk) G_LOAD(ra1, rb1, kt + 3);
;       if (kt + 2 < nk) G_STORE(ra0, rb0, As, Bs);
;       G_COMPUTE(As1, Bs1);
;       __syncthreads();
;     }
;   }
;     ...
;   const int rbase = m0 + wm * 64, cbase = n0 + wn * 64;
;   switch (jb.epi) {
	v_mfma_f32_32x32x16_bf16 v[16:31], v[66:69], v[70:73], v[16:31]
	v_mfma_f32_32x32x16_bf16 v[48:63], v[74:77], v[78:81], v[48:63]
	v_mfma_f32_32x32x16_bf16 v[32:47], v[74:77], v[92:95], v[32:47]
	v_mfma_f32_32x32x16_bf16 v[0:15], v[66:69], v[88:91], v[0:15]
	v_mfma_f32_32x32x16_bf16 v[16:31], v[98:101], v[78:81], v[16:31]
	ds_read_b128 v[66:69], v170 offset:32768
	ds_read_b128 v[70:73], v174 offset:49152
	ds_read_b128 v[74:77], v175 offset:49152
	ds_read_b128 v[78:81], v171 offset:32768
	ds_read_b128 v[88:91], v174 offset:53248
	s_waitcnt lgkmcnt(3)
	v_mfma_f32_32x32x16_bf16 v[48:63], v[66:69], v[70:73], v[48:63]
	s_waitcnt lgkmcnt(0)
	v_mfma_f32_32x32x16_bf16 v[32:47], v[66:69], v[88:91], v[32:47]
	ds_read_b128 v[66:69], v170 offset:36864
	v_mfma_f32_32x32x16_bf16 v[0:15], v[98:101], v[92:95], v[0:15]
	s_waitcnt lgkmcnt(0)
	v_mfma_f32_32x32x16_bf16 v[16:31], v[66:69], v[70:73], v[16:31]
	ds_read_b128 v[70:73], v171 offset:36864
	v_mfma_f32_32x32x16_bf16 v[0:15], v[66:69], v[88:91], v[0:15]
	ds_read_b128 v[66:69], v175 offset:53248
	v_mfma_f32_32x32x16_bf16 v[48:63], v[78:81], v[74:77], v[48:63]
	s_waitcnt lgkmcnt(0)
	v_mfma_f32_32x32x16_bf16 v[32:47], v[78:81], v[66:69], v[32:47]
	v_mfma_f32_32x32x16_bf16 v[16:31], v[70:73], v[74:77], v[16:31]
	v_mfma_f32_32x32x16_bf16 v[0:15], v[70:73], v[66:69], v[0:15]
	ds_read_b128 v[66:69], v172 offset:32768
	ds_read_b128 v[70:73], v176 offset:49152
	ds_read_b128 v[74:77], v176 offset:53248
	s_waitcnt lgkmcnt(1)
	v_mfma_f32_32x32x16_bf16 v[48:63], v[66:69], v[70:73], v[48:63]
	s_waitcnt lgkmcnt(0)
	v_mfma_f32_32x32x16_bf16 v[32:47], v[66:69], v[74:77], v[32:47]
	ds_read_b128 v[66:69], v172 offset:36864
	s_waitcnt lgkmcnt(0)
	v_mfma_f32_32x32x16_bf16 v[16:31], v[66:69], v[70:73], v[16:31]
	v_mfma_f32_32x32x16_bf16 v[0:15], v[66:69], v[74:77], v[0:15]
	ds_read_b128 v[66:69], v173 offset:32768
	ds_read_b128 v[70:73], v177 offset:49152
	ds_read_b128 v[74:77], v177 offset:53248
	s_waitcnt lgkmcnt(1)
	v_mfma_f32_32x32x16_bf16 v[48:63], v[66:69], v[70:73], v[48:63]
	s_waitcnt lgkmcnt(0)
	v_mfma_f32_32x32x16_bf16 v[32:47], v[66:69], v[74:77], v[32:47]
	ds_read_b128 v[64:67], v173 offset:36864
	v_and_b32_e32 v69, 63, v85
	v_add_u32_e32 v68, s26, v86
	s_waitcnt lgkmcnt(0)
	s_barrier
	v_mfma_f32_32x32x16_bf16 v[16:31], v[64:67], v[70:73], v[16:31]
	v_and_or_b32 v71, v85, 64, s27
	v_mfma_f32_32x32x16_bf16 v[0:15], v[64:67], v[74:77], v[0:15]
	s_cmp_lt_i32 s29, 7
	s_cbranch_scc1 .LBB0_965
	s_cmp_gt_i32 s29, 10
	s_cbranch_scc0 .LBB0_735
	s_mov_b32 s2, 23
	s_ashr_i32 s3, s2, 31
	s_lshl_b64 s[2:3], s[2:3], 3
	s_add_u32 s2, s0, s2
	s_addc_u32 s3, s1, s3
	s_load_dwordx2 s[2:3], s[2:3], 0x0
	s_waitcnt lgkmcnt(0)
	s_mov_b32 s2, 26
	s_ashr_i32 s3, s2, 31
	s_lshl_b64 s[2:3], s[2:3], 3
	s_add_u32 s2, s0, s2
	s_addc_u32 s3, s1, s3
	v_lshrrev_b32_e32 v79, 3, v69
	s_load_dwordx2 s[2:3], s[2:3], 0x0
	v_and_b32_e32 v70, 4, v79
	s_waitcnt lgkmcnt(0)
	v_or_b32_e32 v64, v71, v84
	v_or_b32_e32 v66, v68, v70
	s_mov_b64 s[2:3], s[74:75]
	v_cmp_gt_i32_e32 vcc, s90, v66
	v_ashrrev_i32_e32 v65, 31, v64
	s_and_saveexec_b64 s[2:3], vcc
	s_cbranch_execz .LBB0_672
	v_ashrrev_i32_e32 v67, 31, v66
	v_lshlrev_b64 v[66:67], 11, v[66:67]
	v_lshl_add_u64 v[66:67], s[24:25], 0, v[66:67]
	v_cvt_pk_bf16_f32 v72, v48, s0
	v_lshl_add_u64 v[66:67], v[64:65], 1, v[66:67]
	v_cvt_pk_bf16_f32 v73, v32, s0
	global_store_short v[66:67], v72, off
	global_store_short v[66:67], v73, off offset:64

; DEVI int TID() { int t = threadIdx.x; asm volatile("" : "+v"(t)); return t; }
;     ...
;   const int tid = TID(), lane = tid & 63, wave = tid >> 6, wm = wave >> 1, wn = wave & 1;
;   f32x16 acc[2][2];
; #pragma unroll
;   for (int i = 0; i < 2; ++i)
; #pragma unroll
;     for (int j = 0; j < 2; ++j) acc[i][j] = zero16();
;   const int lrow = tid >> 3, lkc = (tid & 7) * 8;
;   const bf16* Ag = jb.A + (size_t)max(m0 + lrow, 0) * jb.lda + lkc;
;   const bf16* Ag1 = jb.A + (ptrdiff_t)(m0 + lrow) * jb.lda + lkc;
;   const bf16* Bg = jb.Bt + (size_t)(n0 + lrow) * jb.K + lkc;
;   const size_t astep = (size_t)32 * jb.lda, bstep = (size_t)32 * jb.K;
;   if (kt1 < 0) kt1 = jb.K >> 6;
;   const int nk = kt1 - kt0;
;   Ag += (size_t)kt0 * 64; Ag1 += (size_t)kt0 * 64; Bg += (size_t)kt0 * 64;
;   u32x4 ra0[4], rb0[4], ra1[4], rb1[4];
;     ...
;   bf16* As1 = As + 2 * 128 * 72;
;   bf16* Bs1 = As1 + 128 * 72;
;   G_LOAD(ra0, rb0, 0);
;   if (nk > 1) G_LOAD(ra1, rb1, 1);
;   G_STORE(ra0, rb0, As, Bs);
;   __syncthreads();
;   for (int kt = 0; kt < nk; kt += 2) {
;     if (kt + 2 < nk) G_LOAD(ra0, rb0, kt + 2);
;     if (kt + 1 < nk) G_STORE(ra1, rb1, As1, Bs1);
;     G_COMPUTE(As, Bs);
.LBB0_1317:
	s_ashr_i32 s2, s4, 31
	s_lshr_b32 s2, s2, 25
	s_add_i32 s2, s4, s2
	s_and_b32 s3, s2, 0xffffff80
	s_sub_i32 s3, s4, s3
	s_ashr_i32 s5, s3, 31
	s_lshr_b32 s5, s5, 28
	s_add_i32 s5, s3, s5
	s_and_b32 s14, s5, 0x1fffff0
	s_sub_i32 s3, s3, s14
	s_lshl_b32 s2, s2, 4
	s_and_b32 s2, s2, 0xfffff800
	s_lshl_b32 s3, s3, 7
	s_waitcnt vmcnt(2)
	v_mov_b32_e32 v84, v208
	s_add_i32 s3, s3, s2
	s_lshl_b32 s2, s5, 3
	v_ashrrev_i32_e32 v82, 3, v84
	v_add_u32_e32 v0, s3, v82
	v_max_i32_e32 v96, 0, v0
	v_lshlrev_b32_e32 v1, 4, v84
	v_lshlrev_b64 v[2:3], 11, v[96:97]
	v_and_b32_e32 v96, 0x70, v1
	s_mov_b64 s[96:97], 0x80
	v_lshrrev_b32_e32 v178, 4, v208
	v_and_b32_e32 v178, 7, v178
	v_lshlrev_b32_e32 v178, 4, v178
	v_xor_b32_e32 v96, v96, v178
	v_lshrrev_b32_e32 v179, 6, v208
	v_lshlrev_b32_e32 v179, 10, v179
	v_lshrrev_b32_e32 v180, 5, v208
	v_lshrrev_b32_e32 v181, 1, v208
	v_xor_b32_e32 v180, v180, v181
	v_readfirstlane_b32 s94, v179
	v_and_b32_e32 v180, 1, v180
	v_lshlrev_b32_e32 v180, 4, v180
	v_and_b32_e32 v181, 31, v208
	v_lshlrev_b32_e32 v181, 7, v181
	v_or_b32_e32 v180, v180, v181
	v_lshrrev_b32_e32 v181, 7, v208
	v_lshlrev_b32_e32 v181, 13, v181
	v_or_b32_e32 v194, v180, v181
	v_bfe_u32 v181, v208, 6, 1
	v_lshlrev_b32_e32 v181, 13, v181
	v_or_b32_e32 v195, v180, v181
	v_bfe_u32 v178, v208, 2, 2
	v_xor_b32_e32 v179, 0, v178
	v_lshlrev_b32_e32 v179, 5, v179
	v_or_b32_e32 v170, v194, v179
	v_or_b32_e32 v174, v195, v179
	v_xor_b32_e32 v179, 1, v178
	v_lshlrev_b32_e32 v179, 5, v179
	v_or_b32_e32 v171, v194, v179
	v_or_b32_e32 v175, v195, v179
	v_xor_b32_e32 v179, 2, v178
	v_lshlrev_b32_e32 v179, 5, v179
	v_or_b32_e32 v172, v194, v179
	v_or_b32_e32 v176, v195, v179
	v_xor_b32_e32 v179, 3, v178
	v_lshlrev_b32_e32 v179, 5, v179
	v_or_b32_e32 v173, v194, v179
	v_or_b32_e32 v177, v195, v179
	v_ashrrev_i32_e32 v1, 31, v0
	v_lshlrev_b64 v[0:1], 11, v[0:1]
	s_and_b32 s2, s2, 0xffffff80
	v_lshl_add_u64 v[0:1], s[8:9], 0, v[0:1]
	v_lshl_add_u64 v[28:29], v[0:1], 0, v[96:97]
	v_add_u32_e32 v0, s2, v82
	v_ashrrev_i32_e32 v1, 31, v0
	v_lshlrev_b64 v[0:1], 11, v[0:1]
	v_lshl_add_u64 v[0:1], s[12:13], 0, v[0:1]
	v_add_co_u32_e32 v70, vcc, s63, v28
	v_lshl_add_u64 v[68:69], v[0:1], 0, v[96:97]
	s_nop 0
	v_addc_co_u32_e32 v71, vcc, 0, v29, vcc
	v_add_co_u32_e32 v72, vcc, s63, v68
	v_lshl_add_u64 v[2:3], s[8:9], 0, v[2:3]
	s_nop 0
	v_addc_co_u32_e32 v73, vcc, 0, v69, vcc
	v_add_co_u32_e32 v74, vcc, s64, v28
	v_lshl_add_u64 v[66:67], v[2:3], 0, v[96:97]
	s_nop 0
	v_addc_co_u32_e32 v75, vcc, 0, v29, vcc
	v_add_co_u32_e32 v76, vcc, s64, v68
	v_addc_co_u32_e32 v77, vcc, 0, v69, vcc
	v_add_co_u32_e32 v78, vcc, s65, v68
	s_nop 0
	v_addc_co_u32_e32 v79, vcc, 0, v69, vcc
	v_add_co_u32_e32 v80, vcc, s65, v28
	s_nop 0
	v_addc_co_u32_e32 v81, vcc, 0, v29, vcc
	s_waitcnt lgkmcnt(0)
	v_ashrrev_i32_e32 v64, 1, v84
	v_lshrrev_b32_e32 v65, 1, v84
	v_and_b32_e32 v85, 0xffffffc0, v64
	s_waitcnt vmcnt(0)
	v_and_b32_e32 v88, 16, v65
	v_and_or_b32 v64, v84, 31, v85
	v_mad_u64_u32 v[82:83], s[14:15], v82, s91, v[96:97]
	v_mad_u64_u32 v[64:65], s[14:15], v64, s91, v[88:89]
	v_add_u32_e32 v86, 0xd800, v82
	v_and_b32_e32 v65, 0x5f, v84
	v_mad_u32_u24 v83, v65, s91, v88
	s_mov_b32 s14, 23
	s_add_u32 m0, s94, 0x4000
	s_nop 1
	global_load_lds_dwordx4 v[68:69], off
	s_add_u32 m0, s94, 0x0
	s_nop 1
	global_load_lds_dwordx4 v[66:67], off
	s_add_u32 m0, s94, 0x5000
	s_nop 1
	global_load_lds_dwordx4 v[72:73], off
	s_add_u32 m0, s94, 0x6000
	s_nop 1
	global_load_lds_dwordx4 v[76:77], off
	s_add_u32 m0, s94, 0x7000
	s_nop 1
	global_load_lds_dwordx4 v[78:79], off
	s_add_u32 m0, s94, 0x1000
	s_nop 1
	global_load_lds_dwordx4 v[70:71], off
	s_add_u32 m0, s94, 0x2000
	s_nop 1
	global_load_lds_dwordx4 v[74:75], off
	s_add_u32 m0, s94, 0x3000
	s_nop 1
	global_load_lds_dwordx4 v[80:81], off
	s_waitcnt lgkmcnt(0)
	s_waitcnt vmcnt(0)
	s_barrier
	v_lshl_add_u64 v[66:67], v[66:67], 0, s[96:97]
	s_add_u32 m0, s94, 0x8000
	s_nop 1
	global_load_lds_dwordx4 v[66:67], off
	v_lshl_add_u64 v[68:69], v[68:69], 0, s[96:97]
	s_add_u32 m0, s94, 0xc000
	s_nop 1
	global_load_lds_dwordx4 v[68:69], off
	v_lshl_add_u64 v[70:71], v[70:71], 0, s[96:97]
	s_add_u32 m0, s94, 0x9000
	s_nop 1
	global_load_lds_dwordx4 v[70:71], off
	v_lshl_add_u64 v[72:73], v[72:73], 0, s[96:97]
	s_add_u32 m0, s94, 0xd000
	s_nop 1
	global_load_lds_dwordx4 v[72:73], off
	v_lshl_add_u64 v[74:75], v[74:75], 0, s[96:97]
	s_add_u32 m0, s94, 0xa000
	s_nop 1
	global_load_lds_dwordx4 v[74:75], off
	v_lshl_add_u64 v[76:77], v[76:77], 0, s[96:97]
	s_add_u32 m0, s94, 0xe000
	s_nop 1
	global_load_lds_dwordx4 v[76:77], off
	v_lshl_add_u64 v[80:81], v[80:81], 0, s[96:97]
	s_add_u32 m0, s94, 0xb000
	s_nop 1
	global_load_lds_dwordx4 v[80:81], off
	v_lshl_add_u64 v[78:79], v[78:79], 0, s[96:97]
	s_add_u32 m0, s94, 0xf000
	s_nop 1
	global_load_lds_dwordx4 v[78:79], off
	ds_read_b128 v[0:3], v170 offset:0
	ds_read_b128 v[4:7], v174 offset:16384
	ds_read_b128 v[88:91], v171 offset:0
	ds_read_b128 v[92:95], v175 offset:16384
	ds_read_b128 v[8:11], v174 offset:20480
	ds_read_b128 v[98:101], v175 offset:20480
	s_waitcnt lgkmcnt(4)
	v_mfma_f32_32x32x16_bf16 v[48:63], v[0:3], v[4:7], 0
	s_waitcnt lgkmcnt(1)
	v_mfma_f32_32x32x16_bf16 v[32:47], v[0:3], v[8:11], 0
	ds_read_b128 v[0:3], v170 offset:4096
	ds_read_b128 v[102:105], v171 offset:4096
	s_waitcnt lgkmcnt(1)
	v_mfma_f32_32x32x16_bf16 v[16:31], v[0:3], v[4:7], 0
	v_mfma_f32_32x32x16_bf16 v[0:15], v[0:3], v[8:11], 0
	v_mfma_f32_32x32x16_bf16 v[48:63], v[88:91], v[92:95], v[48:63]
	v_mfma_f32_32x32x16_bf16 v[32:47], v[88:91], v[98:101], v[32:47]
	s_waitcnt lgkmcnt(0)
	v_mfma_f32_32x32x16_bf16 v[16:31], v[102:105], v[92:95], v[16:31]
	v_mfma_f32_32x32x16_bf16 v[0:15], v[102:105], v[98:101], v[0:15]
	ds_read_b128 v[88:91], v172 offset:0
	ds_read_b128 v[92:95], v176 offset:16384
	ds_read_b128 v[98:101], v173 offset:0
	ds_read_b128 v[102:105], v177 offset:16384
	ds_read_b128 v[106:109], v176 offset:20480
	ds_read_b128 v[110:113], v177 offset:20480
	s_waitcnt lgkmcnt(4)
	v_mfma_f32_32x32x16_bf16 v[48:63], v[88:91], v[92:95], v[48:63]
	s_waitcnt lgkmcnt(1)
	v_mfma_f32_32x32x16_bf16 v[32:47], v[88:91], v[106:109], v[32:47]
	ds_read_b128 v[88:91], v172 offset:4096
	ds_read_b128 v[114:117], v173 offset:4096
	s_waitcnt lgkmcnt(1)
	v_mfma_f32_32x32x16_bf16 v[16:31], v[88:91], v[92:95], v[16:31]
	v_mfma_f32_32x32x16_bf16 v[0:15], v[88:91], v[106:109], v[0:15]
	v_mfma_f32_32x32x16_bf16 v[48:63], v[98:101], v[102:105], v[48:63]
	v_mfma_f32_32x32x16_bf16 v[32:47], v[98:101], v[110:113], v[32:47]
	s_waitcnt lgkmcnt(0)
	v_mfma_f32_32x32x16_bf16 v[16:31], v[114:117], v[102:105], v[16:31]
	s_waitcnt vmcnt(0)
	s_barrier
;     ...
;   bf16* As1 = As + 2 * 128 * 72;
;   bf16* Bs1 = As1 + 128 * 72;
;   G_LOAD(ra0, rb0, 0);
;   if (nk > 1) G_LOAD(ra1, rb1, 1);
;   G_STORE(ra0, rb0, As, Bs);
;   __syncthreads();
;   for (int kt = 0; kt < nk; kt += 2) {
;     if (kt + 2 < nk) G_LOAD(ra0, rb0, kt + 2);
;     if (kt + 1 < nk) G_STORE(ra1, rb1, As1, Bs1);
;     G_COMPUTE(As, Bs);
;     __syncthreads();
;     if (kt + 1 < nk) {
;       if (kt + 3 < nk) G_LOAD(ra1, rb1, kt + 3);
;       if (kt + 2 < nk) G_STORE(ra0, rb0, As, Bs);
;       G_COMPUTE(As1, Bs1);
;       __syncthreads();
;     }
;   }
	v_lshl_add_u64 v[66:67], v[66:67], 0, s[96:97]
	s_add_u32 m0, s94, 0x0
	s_nop 1
	global_load_lds_dwordx4 v[66:67], off
	v_lshl_add_u64 v[68:69], v[68:69], 0, s[96:97]
	s_add_u32 m0, s94, 0x4000
	s_nop 1
	global_load_lds_dwordx4 v[68:69], off
	v_lshl_add_u64 v[70:71], v[70:71], 0, s[96:97]
	s_add_u32 m0, s94, 0x1000
	s_nop 1
	global_load_lds_dwordx4 v[70:71], off
	v_lshl_add_u64 v[72:73], v[72:73], 0, s[96:97]
	s_add_u32 m0, s94, 0x5000
	s_nop 1
	global_load_lds_dwordx4 v[72:73], off
	v_lshl_add_u64 v[74:75], v[74:75], 0, s[96:97]
	s_add_u32 m0, s94, 0x2000
	s_nop 1
	global_load_lds_dwordx4 v[74:75], off
	v_lshl_add_u64 v[76:77], v[76:77], 0, s[96:97]
	s_add_u32 m0, s94, 0x6000
	s_nop 1
	global_load_lds_dwordx4 v[76:77], off
	v_lshl_add_u64 v[80:81], v[80:81], 0, s[96:97]
	s_add_u32 m0, s94, 0x3000
	s_nop 1
	global_load_lds_dwordx4 v[80:81], off
	v_lshl_add_u64 v[78:79], v[78:79], 0, s[96:97]
	s_add_u32 m0, s94, 0x7000
	s_nop 1
	global_load_lds_dwordx4 v[78:79], off
	v_mfma_f32_32x32x16_bf16 v[0:15], v[114:117], v[110:113], v[0:15]
	ds_read_b128 v[88:91], v170 offset:32768
	ds_read_b128 v[92:95], v174 offset:49152
	ds_read_b128 v[98:101], v171 offset:32768
	ds_read_b128 v[102:105], v175 offset:49152
	ds_read_b128 v[106:109], v174 offset:53248
	ds_read_b128 v[110:113], v175 offset:53248
	s_waitcnt lgkmcnt(4)
	v_mfma_f32_32x32x16_bf16 v[48:63], v[88:91], v[92:95], v[48:63]
	s_waitcnt lgkmcnt(1)
	v_mfma_f32_32x32x16_bf16 v[32:47], v[88:91], v[106:109], v[32:47]
	ds_read_b128 v[88:91], v170 offset:36864
	ds_read_b128 v[114:117], v171 offset:36864
	s_waitcnt lgkmcnt(1)
	v_mfma_f32_32x32x16_bf16 v[16:31], v[88:91], v[92:95], v[16:31]
	v_mfma_f32_32x32x16_bf16 v[0:15], v[88:91], v[106:109], v[0:15]
	v_mfma_f32_32x32x16_bf16 v[48:63], v[98:101], v[102:105], v[48:63]
	v_mfma_f32_32x32x16_bf16 v[32:47], v[98:101], v[110:113], v[32:47]
	s_waitcnt lgkmcnt(0)
	v_mfma_f32_32x32x16_bf16 v[16:31], v[114:117], v[102:105], v[16:31]
	ds_read_b128 v[88:91], v172 offset:32768
	ds_read_b128 v[92:95], v176 offset:49152
	ds_read_b128 v[98:101], v173 offset:32768
	ds_read_b128 v[102:105], v177 offset:49152
	v_mfma_f32_32x32x16_bf16 v[0:15], v[114:117], v[110:113], v[0:15]
	ds_read_b128 v[106:109], v176 offset:53248
	ds_read_b128 v[110:113], v177 offset:53248
	s_waitcnt lgkmcnt(4)
	v_mfma_f32_32x32x16_bf16 v[48:63], v[88:91], v[92:95], v[48:63]
	s_waitcnt lgkmcnt(1)
	v_mfma_f32_32x32x16_bf16 v[32:47], v[88:91], v[106:109], v[32:47]
	ds_read_b128 v[88:91], v172 offset:36864
	ds_read_b128 v[114:117], v173 offset:36864
	s_waitcnt lgkmcnt(1)
	v_mfma_f32_32x32x16_bf16 v[16:31], v[88:91], v[92:95], v[16:31]
	v_mfma_f32_32x32x16_bf16 v[0:15], v[88:91], v[106:109], v[0:15]
	v_mfma_f32_32x32x16_bf16 v[48:63], v[98:101], v[102:105], v[48:63]
	v_mfma_f32_32x32x16_bf16 v[32:47], v[98:101], v[110:113], v[32:47]
	s_waitcnt lgkmcnt(0)
	v_mfma_f32_32x32x16_bf16 v[16:31], v[114:117], v[102:105], v[16:31]
	s_waitcnt vmcnt(0)
	s_barrier
	v_lshl_add_u64 v[66:67], v[66:67], 0, s[96:97]
	s_add_u32 m0, s94, 0x8000
	s_nop 1
	global_load_lds_dwordx4 v[66:67], off
	v_lshl_add_u64 v[68:69], v[68:69], 0, s[96:97]
	s_add_u32 m0, s94, 0xc000
	s_nop 1
	global_load_lds_dwordx4 v[68:69], off
	v_lshl_add_u64 v[70:71], v[70:71], 0, s[96:97]
	s_add_u32 m0, s94, 0x9000
	s_nop 1
	global_load_lds_dwordx4 v[70:71], off
	v_lshl_add_u64 v[72:73], v[72:73], 0, s[96:97]
	s_add_u32 m0, s94, 0xd000
	s_nop 1
	global_load_lds_dwordx4 v[72:73], off
	v_lshl_add_u64 v[74:75], v[74:75], 0, s[96:97]
	s_add_u32 m0, s94, 0xa000
	s_nop 1
	global_load_lds_dwordx4 v[74:75], off
	v_lshl_add_u64 v[76:77], v[76:77], 0, s[96:97]
	s_add_u32 m0, s94, 0xe000
	s_nop 1
	global_load_lds_dwordx4 v[76:77], off
	v_lshl_add_u64 v[80:81], v[80:81], 0, s[96:97]
	s_add_u32 m0, s94, 0xb000
	s_nop 1
	global_load_lds_dwordx4 v[80:81], off
	v_lshl_add_u64 v[78:79], v[78:79], 0, s[96:97]
	s_add_u32 m0, s94, 0xf000
	s_nop 1
	global_load_lds_dwordx4 v[78:79], off
	v_mfma_f32_32x32x16_bf16 v[0:15], v[114:117], v[110:113], v[0:15]
	ds_read_b128 v[88:91], v170 offset:0
	ds_read_b128 v[92:95], v174 offset:16384
	ds_read_b128 v[98:101], v171 offset:0
	ds_read_b128 v[102:105], v175 offset:16384
	ds_read_b128 v[106:109], v174 offset:20480
	ds_read_b128 v[110:113], v175 offset:20480
	s_waitcnt lgkmcnt(4)
	v_mfma_f32_32x32x16_bf16 v[48:63], v[88:91], v[92:95], v[48:63]
	s_waitcnt lgkmcnt(1)
	v_mfma_f32_32x32x16_bf16 v[32:47], v[88:91], v[106:109], v[32:47]
	ds_read_b128 v[88:91], v170 offset:4096
	ds_read_b128 v[114:117], v171 offset:4096
	s_waitcnt lgkmcnt(1)
	v_mfma_f32_32x32x16_bf16 v[16:31], v[88:91], v[92:95], v[16:31]
	v_mfma_f32_32x32x16_bf16 v[0:15], v[88:91], v[106:109], v[0:15]
	v_mfma_f32_32x32x16_bf16 v[48:63], v[98:101], v[102:105], v[48:63]
	v_mfma_f32_32x32x16_bf16 v[32:47], v[98:101], v[110:113], v[32:47]
	s_waitcnt lgkmcnt(0)
	v_mfma_f32_32x32x16_bf16 v[16:31], v[114:117], v[102:105], v[16:31]
	ds_read_b128 v[88:91], v172 offset:0
	ds_read_b128 v[92:95], v176 offset:16384
	ds_read_b128 v[98:101], v173 offset:0
	ds_read_b128 v[102:105], v177 offset:16384
	v_mfma_f32_32x32x16_bf16 v[0:15], v[114:117], v[110:113], v[0:15]
	ds_read_b128 v[106:109], v176 offset:20480
	ds_read_b128 v[110:113], v177 offset:20480
	s_waitcnt lgkmcnt(4)
	v_mfma_f32_32x32x16_bf16 v[48:63], v[88:91], v[92:95], v[48:63]
	s_waitcnt lgkmcnt(1)
	v_mfma_f32_32x32x16_bf16 v[32:47], v[88:91], v[106:109], v[32:47]
	ds_read_b128 v[88:91], v172 offset:4096
	ds_read_b128 v[114:117], v173 offset:4096
	s_waitcnt lgkmcnt(1)
	v_mfma_f32_32x32x16_bf16 v[16:31], v[88:91], v[92:95], v[16:31]
	v_mfma_f32_32x32x16_bf16 v[0:15], v[88:91], v[106:109], v[0:15]
	v_mfma_f32_32x32x16_bf16 v[48:63], v[98:101], v[102:105], v[48:63]
	v_mfma_f32_32x32x16_bf16 v[32:47], v[98:101], v[110:113], v[32:47]
	s_waitcnt lgkmcnt(0)
	v_mfma_f32_32x32x16_bf16 v[16:31], v[114:117], v[102:105], v[16:31]
	s_waitcnt vmcnt(0)
	s_barrier
;     ...
;   bf16* As1 = As + 2 * 128 * 72;
;   bf16* Bs1 = As1 + 128 * 72;
;   G_LOAD(ra0, rb0, 0);
;   if (nk > 1) G_LOAD(ra1, rb1, 1);
;   G_STORE(ra0, rb0, As, Bs);
;   __syncthreads();
;   for (int kt = 0; kt < nk; kt += 2) {
;     if (kt + 2 < nk) G_LOAD(ra0, rb0, kt + 2);
;     if (kt + 1 < nk) G_STORE(ra1, rb1, As1, Bs1);
;     G_COMPUTE(As, Bs);
;     __syncthreads();
;     if (kt + 1 < nk) {
;       if (kt + 3 < nk) G_LOAD(ra1, rb1, kt + 3);
;       if (kt + 2 < nk) G_STORE(ra0, rb0, As, Bs);
;       G_COMPUTE(As1, Bs1);
;       __syncthreads();
;     }
;   }
	v_lshl_add_u64 v[66:67], v[66:67], 0, s[96:97]
	s_add_u32 m0, s94, 0x0
	s_nop 1
	global_load_lds_dwordx4 v[66:67], off
	v_lshl_add_u64 v[68:69], v[68:69], 0, s[96:97]
	s_add_u32 m0, s94, 0x4000
	s_nop 1
	global_load_lds_dwordx4 v[68:69], off
	v_lshl_add_u64 v[70:71], v[70:71], 0, s[96:97]
	s_add_u32 m0, s94, 0x1000
	s_nop 1
	global_load_lds_dwordx4 v[70:71], off
	v_lshl_add_u64 v[72:73], v[72:73], 0, s[96:97]
	s_add_u32 m0, s94, 0x5000
	s_nop 1
	global_load_lds_dwordx4 v[72:73], off
	v_lshl_add_u64 v[74:75], v[74:75], 0, s[96:97]
	s_add_u32 m0, s94, 0x2000
	s_nop 1
	global_load_lds_dwordx4 v[74:75], off
	v_lshl_add_u64 v[76:77], v[76:77], 0, s[96:97]
	s_add_u32 m0, s94, 0x6000
	s_nop 1
	global_load_lds_dwordx4 v[76:77], off
	v_lshl_add_u64 v[80:81], v[80:81], 0, s[96:97]
	s_add_u32 m0, s94, 0x3000
	s_nop 1
	global_load_lds_dwordx4 v[80:81], off
	v_lshl_add_u64 v[78:79], v[78:79], 0, s[96:97]
	s_add_u32 m0, s94, 0x7000
	s_nop 1
	global_load_lds_dwordx4 v[78:79], off
	v_mfma_f32_32x32x16_bf16 v[0:15], v[114:117], v[110:113], v[0:15]
	ds_read_b128 v[88:91], v170 offset:32768
	ds_read_b128 v[92:95], v174 offset:49152
	ds_read_b128 v[98:101], v171 offset:32768
	ds_read_b128 v[102:105], v175 offset:49152
	ds_read_b128 v[106:109], v174 offset:53248
	ds_read_b128 v[110:113], v175 offset:53248
	s_waitcnt lgkmcnt(4)
	v_mfma_f32_32x32x16_bf16 v[48:63], v[88:91], v[92:95], v[48:63]
	s_waitcnt lgkmcnt(1)
	v_mfma_f32_32x32x16_bf16 v[32:47], v[88:91], v[106:109], v[32:47]
	ds_read_b128 v[88:91], v170 offset:36864
	ds_read_b128 v[114:117], v171 offset:36864
	s_waitcnt lgkmcnt(1)
	v_mfma_f32_32x32x16_bf16 v[16:31], v[88:91], v[92:95], v[16:31]
	v_mfma_f32_32x32x16_bf16 v[0:15], v[88:91], v[106:109], v[0:15]
	v_mfma_f32_32x32x16_bf16 v[48:63], v[98:101], v[102:105], v[48:63]
	v_mfma_f32_32x32x16_bf16 v[32:47], v[98:101], v[110:113], v[32:47]
	s_waitcnt lgkmcnt(0)
	v_mfma_f32_32x32x16_bf16 v[16:31], v[114:117], v[102:105], v[16:31]
	ds_read_b128 v[88:91], v172 offset:32768
	ds_read_b128 v[92:95], v176 offset:49152
	ds_read_b128 v[98:101], v173 offset:32768
	ds_read_b128 v[102:105], v177 offset:49152
	v_mfma_f32_32x32x16_bf16 v[0:15], v[114:117], v[110:113], v[0:15]
	ds_read_b128 v[106:109], v176 offset:53248
	ds_read_b128 v[110:113], v177 offset:53248
	s_waitcnt lgkmcnt(4)
	v_mfma_f32_32x32x16_bf16 v[48:63], v[88:91], v[92:95], v[48:63]
	s_waitcnt lgkmcnt(1)
	v_mfma_f32_32x32x16_bf16 v[32:47], v[88:91], v[106:109], v[32:47]
	ds_read_b128 v[88:91], v172 offset:36864
	ds_read_b128 v[114:117], v173 offset:36864
	s_waitcnt lgkmcnt(1)
	v_mfma_f32_32x32x16_bf16 v[16:31], v[88:91], v[92:95], v[16:31]
	v_mfma_f32_32x32x16_bf16 v[0:15], v[88:91], v[106:109], v[0:15]
	v_mfma_f32_32x32x16_bf16 v[48:63], v[98:101], v[102:105], v[48:63]
	v_mfma_f32_32x32x16_bf16 v[32:47], v[98:101], v[110:113], v[32:47]
	s_waitcnt lgkmcnt(0)
	v_mfma_f32_32x32x16_bf16 v[16:31], v[114:117], v[102:105], v[16:31]
	s_waitcnt vmcnt(0)
	s_barrier
	v_lshl_add_u64 v[66:67], v[66:67], 0, s[96:97]
	s_add_u32 m0, s94, 0x8000
	s_nop 1
	global_load_lds_dwordx4 v[66:67], off
	v_lshl_add_u64 v[68:69], v[68:69], 0, s[96:97]
	s_add_u32 m0, s94, 0xc000
	s_nop 1
	global_load_lds_dwordx4 v[68:69], off
	v_lshl_add_u64 v[70:71], v[70:71], 0, s[96:97]
	s_add_u32 m0, s94, 0x9000
	s_nop 1
	global_load_lds_dwordx4 v[70:71], off
	v_lshl_add_u64 v[72:73], v[72:73], 0, s[96:97]
	s_add_u32 m0, s94, 0xd000
	s_nop 1
	global_load_lds_dwordx4 v[72:73], off
	v_lshl_add_u64 v[74:75], v[74:75], 0, s[96:97]
	s_add_u32 m0, s94, 0xa000
	s_nop 1
	global_load_lds_dwordx4 v[74:75], off
	v_lshl_add_u64 v[76:77], v[76:77], 0, s[96:97]
	s_add_u32 m0, s94, 0xe000
	s_nop 1
	global_load_lds_dwordx4 v[76:77], off
	v_lshl_add_u64 v[80:81], v[80:81], 0, s[96:97]
	s_add_u32 m0, s94, 0xb000
	s_nop 1
	global_load_lds_dwordx4 v[80:81], off
	v_lshl_add_u64 v[78:79], v[78:79], 0, s[96:97]
	s_add_u32 m0, s94, 0xf000
	s_nop 1
	global_load_lds_dwordx4 v[78:79], off
	v_mfma_f32_32x32x16_bf16 v[0:15], v[114:117], v[110:113], v[0:15]
	ds_read_b128 v[88:91], v170 offset:0
	ds_read_b128 v[92:95], v174 offset:16384
	ds_read_b128 v[98:101], v171 offset:0
	ds_read_b128 v[102:105], v175 offset:16384
	ds_read_b128 v[106:109], v174 offset:20480
	ds_read_b128 v[110:113], v175 offset:20480
	s_waitcnt lgkmcnt(4)
	v_mfma_f32_32x32x16_bf16 v[48:63], v[88:91], v[92:95], v[48:63]
	s_waitcnt lgkmcnt(1)
	v_mfma_f32_32x32x16_bf16 v[32:47], v[88:91], v[106:109], v[32:47]
	ds_read_b128 v[88:91], v170 offset:4096
	ds_read_b128 v[114:117], v171 offset:4096
	s_waitcnt lgkmcnt(1)
	v_mfma_f32_32x32x16_bf16 v[16:31], v[88:91], v[92:95], v[16:31]
	v_mfma_f32_32x32x16_bf16 v[0:15], v[88:91], v[106:109], v[0:15]
	v_mfma_f32_32x32x16_bf16 v[48:63], v[98:101], v[102:105], v[48:63]
	v_mfma_f32_32x32x16_bf16 v[32:47], v[98:101], v[110:113], v[32:47]
	s_waitcnt lgkmcnt(0)
	v_mfma_f32_32x32x16_bf16 v[16:31], v[114:117], v[102:105], v[16:31]
	ds_read_b128 v[88:91], v172 offset:0
	ds_read_b128 v[92:95], v176 offset:16384
	ds_read_b128 v[98:101], v173 offset:0
	ds_read_b128 v[102:105], v177 offset:16384
	v_mfma_f32_32x32x16_bf16 v[0:15], v[114:117], v[110:113], v[0:15]
	ds_read_b128 v[106:109], v176 offset:20480
	ds_read_b128 v[110:113], v177 offset:20480
	s_waitcnt lgkmcnt(4)
	v_mfma_f32_32x32x16_bf16 v[48:63], v[88:91], v[92:95], v[48:63]
	s_waitcnt lgkmcnt(1)
	v_mfma_f32_32x32x16_bf16 v[32:47], v[88:91], v[106:109], v[32:47]
	ds_read_b128 v[88:91], v172 offset:4096
	ds_read_b128 v[114:117], v173 offset:4096
	s_waitcnt lgkmcnt(1)
	v_mfma_f32_32x32x16_bf16 v[16:31], v[88:91], v[92:95], v[16:31]
	v_mfma_f32_32x32x16_bf16 v[0:15], v[88:91], v[106:109], v[0:15]
	v_mfma_f32_32x32x16_bf16 v[48:63], v[98:101], v[102:105], v[48:63]
	v_mfma_f32_32x32x16_bf16 v[32:47], v[98:101], v[110:113], v[32:47]
	s_waitcnt lgkmcnt(0)
	v_mfma_f32_32x32x16_bf16 v[16:31], v[114:117], v[102:105], v[16:31]
	s_waitcnt vmcnt(0)
	s_barrier
;     ...
;   bf16* As1 = As + 2 * 128 * 72;
;   bf16* Bs1 = As1 + 128 * 72;
;   G_LOAD(ra0, rb0, 0);
;   if (nk > 1) G_LOAD(ra1, rb1, 1);
;   G_STORE(ra0, rb0, As, Bs);
;   __syncthreads();
;   for (int kt = 0; kt < nk; kt += 2) {
;     if (kt + 2 < nk) G_LOAD(ra0, rb0, kt + 2);
;     if (kt + 1 < nk) G_STORE(ra1, rb1, As1, Bs1);
;     G_COMPUTE(As, Bs);
;     __syncthreads();
;     if (kt + 1 < nk) {
;       if (kt + 3 < nk) G_LOAD(ra1, rb1, kt + 3);
;       if (kt + 2 < nk) G_STORE(ra0, rb0, As, Bs);
;       G_COMPUTE(As1, Bs1);
;       __syncthreads();
;     }
;   }
	v_lshl_add_u64 v[66:67], v[66:67], 0, s[96:97]
	s_add_u32 m0, s94, 0x0
	s_nop 1
	global_load_lds_dwordx4 v[66:67], off
	v_lshl_add_u64 v[68:69], v[68:69], 0, s[96:97]
	s_add_u32 m0, s94, 0x4000
	s_nop 1
	global_load_lds_dwordx4 v[68:69], off
	v_lshl_add_u64 v[70:71], v[70:71], 0, s[96:97]
	s_add_u32 m0, s94, 0x1000
	s_nop 1
	global_load_lds_dwordx4 v[70:71], off
	v_lshl_add_u64 v[72:73], v[72:73], 0, s[96:97]
	s_add_u32 m0, s94, 0x5000
	s_nop 1
	global_load_lds_dwordx4 v[72:73], off
	v_lshl_add_u64 v[74:75], v[74:75], 0, s[96:97]
	s_add_u32 m0, s94, 0x2000
	s_nop 1
	global_load_lds_dwordx4 v[74:75], off
	v_lshl_add_u64 v[76:77], v[76:77], 0, s[96:97]
	s_add_u32 m0, s94, 0x6000
	s_nop 1
	global_load_lds_dwordx4 v[76:77], off
	v_lshl_add_u64 v[80:81], v[80:81], 0, s[96:97]
	s_add_u32 m0, s94, 0x3000
	s_nop 1
	global_load_lds_dwordx4 v[80:81], off
	v_lshl_add_u64 v[78:79], v[78:79], 0, s[96:97]
	s_add_u32 m0, s94, 0x7000
	s_nop 1
	global_load_lds_dwordx4 v[78:79], off
	v_mfma_f32_32x32x16_bf16 v[0:15], v[114:117], v[110:113], v[0:15]
	ds_read_b128 v[88:91], v170 offset:32768
	ds_read_b128 v[92:95], v174 offset:49152
	ds_read_b128 v[98:101], v171 offset:32768
	ds_read_b128 v[102:105], v175 offset:49152
	ds_read_b128 v[106:109], v174 offset:53248
	ds_read_b128 v[110:113], v175 offset:53248
	s_waitcnt lgkmcnt(4)
	v_mfma_f32_32x32x16_bf16 v[48:63], v[88:91], v[92:95], v[48:63]
	s_waitcnt lgkmcnt(1)
	v_mfma_f32_32x32x16_bf16 v[32:47], v[88:91], v[106:109], v[32:47]
	ds_read_b128 v[88:91], v170 offset:36864
	ds_read_b128 v[114:117], v171 offset:36864
	s_waitcnt lgkmcnt(1)
	v_mfma_f32_32x32x16_bf16 v[16:31], v[88:91], v[92:95], v[16:31]
	v_mfma_f32_32x32x16_bf16 v[0:15], v[88:91], v[106:109], v[0:15]
	v_mfma_f32_32x32x16_bf16 v[48:63], v[98:101], v[102:105], v[48:63]
	v_mfma_f32_32x32x16_bf16 v[32:47], v[98:101], v[110:113], v[32:47]
	s_waitcnt lgkmcnt(0)
	v_mfma_f32_32x32x16_bf16 v[16:31], v[114:117], v[102:105], v[16:31]
	ds_read_b128 v[88:91], v172 offset:32768
	ds_read_b128 v[92:95], v176 offset:49152
	ds_read_b128 v[98:101], v173 offset:32768
	ds_read_b128 v[102:105], v177 offset:49152
	v_mfma_f32_32x32x16_bf16 v[0:15], v[114:117], v[110:113], v[0:15]
	ds_read_b128 v[106:109], v176 offset:53248
	ds_read_b128 v[110:113], v177 offset:53248
	s_waitcnt lgkmcnt(4)
	v_mfma_f32_32x32x16_bf16 v[48:63], v[88:91], v[92:95], v[48:63]
	s_waitcnt lgkmcnt(1)
	v_mfma_f32_32x32x16_bf16 v[32:47], v[88:91], v[106:109], v[32:47]
	ds_read_b128 v[88:91], v172 offset:36864
	ds_read_b128 v[114:117], v173 offset:36864
	s_waitcnt lgkmcnt(1)
	v_mfma_f32_32x32x16_bf16 v[16:31], v[88:91], v[92:95], v[16:31]
	v_mfma_f32_32x32x16_bf16 v[0:15], v[88:91], v[106:109], v[0:15]
	v_mfma_f32_32x32x16_bf16 v[48:63], v[98:101], v[102:105], v[48:63]
	v_mfma_f32_32x32x16_bf16 v[32:47], v[98:101], v[110:113], v[32:47]
	s_waitcnt lgkmcnt(0)
	v_mfma_f32_32x32x16_bf16 v[16:31], v[114:117], v[102:105], v[16:31]
	s_waitcnt vmcnt(0)
	s_barrier
	v_lshl_add_u64 v[66:67], v[66:67], 0, s[96:97]
	s_add_u32 m0, s94, 0x8000
	s_nop 1
	global_load_lds_dwordx4 v[66:67], off
	v_lshl_add_u64 v[68:69], v[68:69], 0, s[96:97]
	s_add_u32 m0, s94, 0xc000
	s_nop 1
	global_load_lds_dwordx4 v[68:69], off
	v_lshl_add_u64 v[70:71], v[70:71], 0, s[96:97]
	s_add_u32 m0, s94, 0x9000
	s_nop 1
	global_load_lds_dwordx4 v[70:71], off
	v_lshl_add_u64 v[72:73], v[72:73], 0, s[96:97]
	s_add_u32 m0, s94, 0xd000
	s_nop 1
	global_load_lds_dwordx4 v[72:73], off
	v_lshl_add_u64 v[74:75], v[74:75], 0, s[96:97]
	s_add_u32 m0, s94, 0xa000
	s_nop 1
	global_load_lds_dwordx4 v[74:75], off
	v_lshl_add_u64 v[76:77], v[76:77], 0, s[96:97]
	s_add_u32 m0, s94, 0xe000
	s_nop 1
	global_load_lds_dwordx4 v[76:77], off
	v_lshl_add_u64 v[80:81], v[80:81], 0, s[96:97]
	s_add_u32 m0, s94, 0xb000
	s_nop 1
	global_load_lds_dwordx4 v[80:81], off
	v_lshl_add_u64 v[78:79], v[78:79], 0, s[96:97]
	s_add_u32 m0, s94, 0xf000
	s_nop 1
	global_load_lds_dwordx4 v[78:79], off
	v_mfma_f32_32x32x16_bf16 v[0:15], v[114:117], v[110:113], v[0:15]
	ds_read_b128 v[88:91], v170 offset:0
	ds_read_b128 v[92:95], v174 offset:16384
	ds_read_b128 v[98:101], v171 offset:0
	ds_read_b128 v[102:105], v175 offset:16384
	ds_read_b128 v[106:109], v174 offset:20480
	ds_read_b128 v[110:113], v175 offset:20480
	s_waitcnt lgkmcnt(4)
	v_mfma_f32_32x32x16_bf16 v[48:63], v[88:91], v[92:95], v[48:63]
	s_waitcnt lgkmcnt(1)
	v_mfma_f32_32x32x16_bf16 v[32:47], v[88:91], v[106:109], v[32:47]
	ds_read_b128 v[88:91], v170 offset:4096
	ds_read_b128 v[114:117], v171 offset:4096
	s_waitcnt lgkmcnt(1)
	v_mfma_f32_32x32x16_bf16 v[16:31], v[88:91], v[92:95], v[16:31]
	v_mfma_f32_32x32x16_bf16 v[0:15], v[88:91], v[106:109], v[0:15]
	v_mfma_f32_32x32x16_bf16 v[48:63], v[98:101], v[102:105], v[48:63]
	v_mfma_f32_32x32x16_bf16 v[32:47], v[98:101], v[110:113], v[32:47]
	s_waitcnt lgkmcnt(0)
	v_mfma_f32_32x32x16_bf16 v[16:31], v[114:117], v[102:105], v[16:31]
	ds_read_b128 v[88:91], v172 offset:0
	ds_read_b128 v[92:95], v176 offset:16384
	ds_read_b128 v[98:101], v173 offset:0
	ds_read_b128 v[102:105], v177 offset:16384
	v_mfma_f32_32x32x16_bf16 v[0:15], v[114:117], v[110:113], v[0:15]
	ds_read_b128 v[106:109], v176 offset:20480
	ds_read_b128 v[110:113], v177 offset:20480
	s_waitcnt lgkmcnt(4)
	v_mfma_f32_32x32x16_bf16 v[48:63], v[88:91], v[92:95], v[48:63]
	s_waitcnt lgkmcnt(1)
	v_mfma_f32_32x32x16_bf16 v[32:47], v[88:91], v[106:109], v[32:47]
	ds_read_b128 v[88:91], v172 offset:4096
	ds_read_b128 v[114:117], v173 offset:4096
	s_waitcnt lgkmcnt(1)
	v_mfma_f32_32x32x16_bf16 v[16:31], v[88:91], v[92:95], v[16:31]
	v_mfma_f32_32x32x16_bf16 v[0:15], v[88:91], v[106:109], v[0:15]
	v_mfma_f32_32x32x16_bf16 v[48:63], v[98:101], v[102:105], v[48:63]
	v_mfma_f32_32x32x16_bf16 v[32:47], v[98:101], v[110:113], v[32:47]
	s_waitcnt lgkmcnt(0)
	v_mfma_f32_32x32x16_bf16 v[16:31], v[114:117], v[102:105], v[16:31]
	s_waitcnt vmcnt(0)
	s_barrier
;     ...
;   bf16* As1 = As + 2 * 128 * 72;
;   bf16* Bs1 = As1 + 128 * 72;
;   G_LOAD(ra0, rb0, 0);
;   if (nk > 1) G_LOAD(ra1, rb1, 1);
;   G_STORE(ra0, rb0, As, Bs);
;   __syncthreads();
;   for (int kt = 0; kt < nk; kt += 2) {
;     if (kt + 2 < nk) G_LOAD(ra0, rb0, kt + 2);
;     if (kt + 1 < nk) G_STORE(ra1, rb1, As1, Bs1);
;     G_COMPUTE(As, Bs);
;     __syncthreads();
;     if (kt + 1 < nk) {
;       if (kt + 3 < nk) G_LOAD(ra1, rb1, kt + 3);
;       if (kt + 2 < nk) G_STORE(ra0, rb0, As, Bs);
;       G_COMPUTE(As1, Bs1);
;       __syncthreads();
;     }
;   }
	v_lshl_add_u64 v[66:67], v[66:67], 0, s[96:97]
	s_add_u32 m0, s94, 0x0
	s_nop 1
	global_load_lds_dwordx4 v[66:67], off
	v_lshl_add_u64 v[68:69], v[68:69], 0, s[96:97]
	s_add_u32 m0, s94, 0x4000
	s_nop 1
	global_load_lds_dwordx4 v[68:69], off
	v_lshl_add_u64 v[70:71], v[70:71], 0, s[96:97]
	s_add_u32 m0, s94, 0x1000
	s_nop 1
	global_load_lds_dwordx4 v[70:71], off
	v_lshl_add_u64 v[72:73], v[72:73], 0, s[96:97]
	s_add_u32 m0, s94, 0x5000
	s_nop 1
	global_load_lds_dwordx4 v[72:73], off
	v_lshl_add_u64 v[74:75], v[74:75], 0, s[96:97]
	s_add_u32 m0, s94, 0x2000
	s_nop 1
	global_load_lds_dwordx4 v[74:75], off
	v_lshl_add_u64 v[76:77], v[76:77], 0, s[96:97]
	s_add_u32 m0, s94, 0x6000
	s_nop 1
	global_load_lds_dwordx4 v[76:77], off
	v_lshl_add_u64 v[80:81], v[80:81], 0, s[96:97]
	s_add_u32 m0, s94, 0x3000
	s_nop 1
	global_load_lds_dwordx4 v[80:81], off
	v_lshl_add_u64 v[78:79], v[78:79], 0, s[96:97]
	s_add_u32 m0, s94, 0x7000
	s_nop 1
	global_load_lds_dwordx4 v[78:79], off
	v_mfma_f32_32x32x16_bf16 v[0:15], v[114:117], v[110:113], v[0:15]
	ds_read_b128 v[88:91], v170 offset:32768
	ds_read_b128 v[92:95], v174 offset:49152
	ds_read_b128 v[98:101], v171 offset:32768
	ds_read_b128 v[102:105], v175 offset:49152
	ds_read_b128 v[106:109], v174 offset:53248
	ds_read_b128 v[110:113], v175 offset:53248
	s_waitcnt lgkmcnt(4)
	v_mfma_f32_32x32x16_bf16 v[48:63], v[88:91], v[92:95], v[48:63]
	s_waitcnt lgkmcnt(1)
	v_mfma_f32_32x32x16_bf16 v[32:47], v[88:91], v[106:109], v[32:47]
	ds_read_b128 v[88:91], v170 offset:36864
	ds_read_b128 v[114:117], v171 offset:36864
	s_waitcnt lgkmcnt(1)
	v_mfma_f32_32x32x16_bf16 v[16:31], v[88:91], v[92:95], v[16:31]
	v_mfma_f32_32x32x16_bf16 v[0:15], v[88:91], v[106:109], v[0:15]
	v_mfma_f32_32x32x16_bf16 v[48:63], v[98:101], v[102:105], v[48:63]
	v_mfma_f32_32x32x16_bf16 v[32:47], v[98:101], v[110:113], v[32:47]
	s_waitcnt lgkmcnt(0)
	v_mfma_f32_32x32x16_bf16 v[16:31], v[114:117], v[102:105], v[16:31]
	ds_read_b128 v[88:91], v172 offset:32768
	ds_read_b128 v[92:95], v176 offset:49152
	ds_read_b128 v[98:101], v173 offset:32768
	ds_read_b128 v[102:105], v177 offset:49152
	v_mfma_f32_32x32x16_bf16 v[0:15], v[114:117], v[110:113], v[0:15]
	ds_read_b128 v[106:109], v176 offset:53248
	ds_read_b128 v[110:113], v177 offset:53248
	s_waitcnt lgkmcnt(4)
	v_mfma_f32_32x32x16_bf16 v[48:63], v[88:91], v[92:95], v[48:63]
	s_waitcnt lgkmcnt(1)
	v_mfma_f32_32x32x16_bf16 v[32:47], v[88:91], v[106:109], v[32:47]
	ds_read_b128 v[88:91], v172 offset:36864
	ds_read_b128 v[114:117], v173 offset:36864
	s_waitcnt lgkmcnt(1)
	v_mfma_f32_32x32x16_bf16 v[16:31], v[88:91], v[92:95], v[16:31]
	v_mfma_f32_32x32x16_bf16 v[0:15], v[88:91], v[106:109], v[0:15]
	v_mfma_f32_32x32x16_bf16 v[48:63], v[98:101], v[102:105], v[48:63]
	v_mfma_f32_32x32x16_bf16 v[32:47], v[98:101], v[110:113], v[32:47]
	s_waitcnt lgkmcnt(0)
	v_mfma_f32_32x32x16_bf16 v[16:31], v[114:117], v[102:105], v[16:31]
	s_waitcnt vmcnt(0)
	s_barrier
	v_lshl_add_u64 v[66:67], v[66:67], 0, s[96:97]
	s_add_u32 m0, s94, 0x8000
	s_nop 1
	global_load_lds_dwordx4 v[66:67], off
	v_lshl_add_u64 v[68:69], v[68:69], 0, s[96:97]
	s_add_u32 m0, s94, 0xc000
	s_nop 1
	global_load_lds_dwordx4 v[68:69], off
	v_lshl_add_u64 v[70:71], v[70:71], 0, s[96:97]
	s_add_u32 m0, s94, 0x9000
	s_nop 1
	global_load_lds_dwordx4 v[70:71], off
	v_lshl_add_u64 v[72:73], v[72:73], 0, s[96:97]
	s_add_u32 m0, s94, 0xd000
	s_nop 1
	global_load_lds_dwordx4 v[72:73], off
	v_lshl_add_u64 v[74:75], v[74:75], 0, s[96:97]
	s_add_u32 m0, s94, 0xa000
	s_nop 1
	global_load_lds_dwordx4 v[74:75], off
	v_lshl_add_u64 v[76:77], v[76:77], 0, s[96:97]
	s_add_u32 m0, s94, 0xe000
	s_nop 1
	global_load_lds_dwordx4 v[76:77], off
	v_lshl_add_u64 v[80:81], v[80:81], 0, s[96:97]
	s_add_u32 m0, s94, 0xb000
	s_nop 1
	global_load_lds_dwordx4 v[80:81], off
	v_lshl_add_u64 v[78:79], v[78:79], 0, s[96:97]
	s_add_u32 m0, s94, 0xf000
	s_nop 1
	global_load_lds_dwordx4 v[78:79], off
	v_mfma_f32_32x32x16_bf16 v[0:15], v[114:117], v[110:113], v[0:15]
	ds_read_b128 v[88:91], v170 offset:0
	ds_read_b128 v[92:95], v174 offset:16384
	ds_read_b128 v[98:101], v171 offset:0
	ds_read_b128 v[102:105], v175 offset:16384
	ds_read_b128 v[106:109], v174 offset:20480
	ds_read_b128 v[110:113], v175 offset:20480
	s_waitcnt lgkmcnt(4)
	v_mfma_f32_32x32x16_bf16 v[48:63], v[88:91], v[92:95], v[48:63]
	s_waitcnt lgkmcnt(1)
	v_mfma_f32_32x32x16_bf16 v[32:47], v[88:91], v[106:109], v[32:47]
	ds_read_b128 v[88:91], v170 offset:4096
	ds_read_b128 v[114:117], v171 offset:4096
	s_waitcnt lgkmcnt(1)
	v_mfma_f32_32x32x16_bf16 v[16:31], v[88:91], v[92:95], v[16:31]
	v_mfma_f32_32x32x16_bf16 v[0:15], v[88:91], v[106:109], v[0:15]
	v_mfma_f32_32x32x16_bf16 v[48:63], v[98:101], v[102:105], v[48:63]
	v_mfma_f32_32x32x16_bf16 v[32:47], v[98:101], v[110:113], v[32:47]
	s_waitcnt lgkmcnt(0)
	v_mfma_f32_32x32x16_bf16 v[16:31], v[114:117], v[102:105], v[16:31]
	ds_read_b128 v[88:91], v172 offset:0
	ds_read_b128 v[92:95], v176 offset:16384
	ds_read_b128 v[98:101], v173 offset:0
	ds_read_b128 v[102:105], v177 offset:16384
	v_mfma_f32_32x32x16_bf16 v[0:15], v[114:117], v[110:113], v[0:15]
	ds_read_b128 v[106:109], v176 offset:20480
	ds_read_b128 v[110:113], v177 offset:20480
	s_waitcnt lgkmcnt(4)
	v_mfma_f32_32x32x16_bf16 v[48:63], v[88:91], v[92:95], v[48:63]
	s_waitcnt lgkmcnt(1)
	v_mfma_f32_32x32x16_bf16 v[32:47], v[88:91], v[106:109], v[32:47]
	ds_read_b128 v[88:91], v172 offset:4096
	ds_read_b128 v[114:117], v173 offset:4096
	s_waitcnt lgkmcnt(1)
	v_mfma_f32_32x32x16_bf16 v[16:31], v[88:91], v[92:95], v[16:31]
	v_mfma_f32_32x32x16_bf16 v[0:15], v[88:91], v[106:109], v[0:15]
	v_mfma_f32_32x32x16_bf16 v[48:63], v[98:101], v[102:105], v[48:63]
	v_mfma_f32_32x32x16_bf16 v[32:47], v[98:101], v[110:113], v[32:47]
	s_waitcnt lgkmcnt(0)
	v_mfma_f32_32x32x16_bf16 v[16:31], v[114:117], v[102:105], v[16:31]
	s_waitcnt vmcnt(0)
	s_barrier
;     ...
;   bf16* As1 = As + 2 * 128 * 72;
;   bf16* Bs1 = As1 + 128 * 72;
;   G_LOAD(ra0, rb0, 0);
;   if (nk > 1) G_LOAD(ra1, rb1, 1);
;   G_STORE(ra0, rb0, As, Bs);
;   __syncthreads();
;   for (int kt = 0; kt < nk; kt += 2) {
;     if (kt + 2 < nk) G_LOAD(ra0, rb0, kt + 2);
;     if (kt + 1 < nk) G_STORE(ra1, rb1, As1, Bs1);
;     G_COMPUTE(As, Bs);
;     __syncthreads();
;     if (kt + 1 < nk) {
;       if (kt + 3 < nk) G_LOAD(ra1, rb1, kt + 3);
;       if (kt + 2 < nk) G_STORE(ra0, rb0, As, Bs);
;       G_COMPUTE(As1, Bs1);
;       __syncthreads();
;     }
;   }
	v_lshl_add_u64 v[66:67], v[66:67], 0, s[96:97]
	s_add_u32 m0, s94, 0x0
	s_nop 1
	global_load_lds_dwordx4 v[66:67], off
	v_lshl_add_u64 v[68:69], v[68:69], 0, s[96:97]
	s_add_u32 m0, s94, 0x4000
	s_nop 1
	global_load_lds_dwordx4 v[68:69], off
	v_lshl_add_u64 v[70:71], v[70:71], 0, s[96:97]
	s_add_u32 m0, s94, 0x1000
	s_nop 1
	global_load_lds_dwordx4 v[70:71], off
	v_lshl_add_u64 v[72:73], v[72:73], 0, s[96:97]
	s_add_u32 m0, s94, 0x5000
	s_nop 1
	global_load_lds_dwordx4 v[72:73], off
	v_lshl_add_u64 v[74:75], v[74:75], 0, s[96:97]
	s_add_u32 m0, s94, 0x2000
	s_nop 1
	global_load_lds_dwordx4 v[74:75], off
	v_lshl_add_u64 v[76:77], v[76:77], 0, s[96:97]
	s_add_u32 m0, s94, 0x6000
	s_nop 1
	global_load_lds_dwordx4 v[76:77], off
	v_lshl_add_u64 v[80:81], v[80:81], 0, s[96:97]
	s_add_u32 m0, s94, 0x3000
	s_nop 1
	global_load_lds_dwordx4 v[80:81], off
	v_lshl_add_u64 v[78:79], v[78:79], 0, s[96:97]
	s_add_u32 m0, s94, 0x7000
	s_nop 1
	global_load_lds_dwordx4 v[78:79], off
	v_mfma_f32_32x32x16_bf16 v[0:15], v[114:117], v[110:113], v[0:15]
	ds_read_b128 v[88:91], v170 offset:32768
	ds_read_b128 v[92:95], v174 offset:49152
	ds_read_b128 v[98:101], v171 offset:32768
	ds_read_b128 v[102:105], v175 offset:49152
	ds_read_b128 v[106:109], v174 offset:53248
	ds_read_b128 v[110:113], v175 offset:53248
	s_waitcnt lgkmcnt(4)
	v_mfma_f32_32x32x16_bf16 v[48:63], v[88:91], v[92:95], v[48:63]
	s_waitcnt lgkmcnt(1)
	v_mfma_f32_32x32x16_bf16 v[32:47], v[88:91], v[106:109], v[32:47]
	ds_read_b128 v[88:91], v170 offset:36864
	ds_read_b128 v[114:117], v171 offset:36864
	s_waitcnt lgkmcnt(1)
	v_mfma_f32_32x32x16_bf16 v[16:31], v[88:91], v[92:95], v[16:31]
	v_mfma_f32_32x32x16_bf16 v[0:15], v[88:91], v[106:109], v[0:15]
	v_mfma_f32_32x32x16_bf16 v[48:63], v[98:101], v[102:105], v[48:63]
	v_mfma_f32_32x32x16_bf16 v[32:47], v[98:101], v[110:113], v[32:47]
	s_waitcnt lgkmcnt(0)
	v_mfma_f32_32x32x16_bf16 v[16:31], v[114:117], v[102:105], v[16:31]
	ds_read_b128 v[88:91], v172 offset:32768
	ds_read_b128 v[92:95], v176 offset:49152
	ds_read_b128 v[98:101], v173 offset:32768
	ds_read_b128 v[102:105], v177 offset:49152
	v_mfma_f32_32x32x16_bf16 v[0:15], v[114:117], v[110:113], v[0:15]
	ds_read_b128 v[106:109], v176 offset:53248
	ds_read_b128 v[110:113], v177 offset:53248
	s_waitcnt lgkmcnt(4)
	v_mfma_f32_32x32x16_bf16 v[48:63], v[88:91], v[92:95], v[48:63]
	s_waitcnt lgkmcnt(1)
	v_mfma_f32_32x32x16_bf16 v[32:47], v[88:91], v[106:109], v[32:47]
	ds_read_b128 v[88:91], v172 offset:36864
	ds_read_b128 v[114:117], v173 offset:36864
	s_waitcnt lgkmcnt(1)
	v_mfma_f32_32x32x16_bf16 v[16:31], v[88:91], v[92:95], v[16:31]
	v_mfma_f32_32x32x16_bf16 v[0:15], v[88:91], v[106:109], v[0:15]
	v_mfma_f32_32x32x16_bf16 v[48:63], v[98:101], v[102:105], v[48:63]
	v_mfma_f32_32x32x16_bf16 v[32:47], v[98:101], v[110:113], v[32:47]
	s_waitcnt lgkmcnt(0)
	v_mfma_f32_32x32x16_bf16 v[16:31], v[114:117], v[102:105], v[16:31]
	s_waitcnt vmcnt(0)
	s_barrier
	v_lshl_add_u64 v[66:67], v[66:67], 0, s[96:97]
	s_add_u32 m0, s94, 0x8000
	s_nop 1
	global_load_lds_dwordx4 v[66:67], off
	v_lshl_add_u64 v[68:69], v[68:69], 0, s[96:97]
	s_add_u32 m0, s94, 0xc000
	s_nop 1
	global_load_lds_dwordx4 v[68:69], off
	v_lshl_add_u64 v[70:71], v[70:71], 0, s[96:97]
	s_add_u32 m0, s94, 0x9000
	s_nop 1
	global_load_lds_dwordx4 v[70:71], off
	v_lshl_add_u64 v[72:73], v[72:73], 0, s[96:97]
	s_add_u32 m0, s94, 0xd000
	s_nop 1
	global_load_lds_dwordx4 v[72:73], off
	v_lshl_add_u64 v[74:75], v[74:75], 0, s[96:97]
	s_add_u32 m0, s94, 0xa000
	s_nop 1
	global_load_lds_dwordx4 v[74:75], off
	v_lshl_add_u64 v[76:77], v[76:77], 0, s[96:97]
	s_add_u32 m0, s94, 0xe000
	s_nop 1
	global_load_lds_dwordx4 v[76:77], off
	v_lshl_add_u64 v[80:81], v[80:81], 0, s[96:97]
	s_add_u32 m0, s94, 0xb000
	s_nop 1
	global_load_lds_dwordx4 v[80:81], off
	v_lshl_add_u64 v[78:79], v[78:79], 0, s[96:97]
	s_add_u32 m0, s94, 0xf000
	s_nop 1
	global_load_lds_dwordx4 v[78:79], off
	v_mfma_f32_32x32x16_bf16 v[0:15], v[114:117], v[110:113], v[0:15]
	ds_read_b128 v[88:91], v170 offset:0
	ds_read_b128 v[92:95], v174 offset:16384
	ds_read_b128 v[98:101], v171 offset:0
	ds_read_b128 v[102:105], v175 offset:16384
	ds_read_b128 v[106:109], v174 offset:20480
	ds_read_b128 v[110:113], v175 offset:20480
	s_waitcnt lgkmcnt(4)
	v_mfma_f32_32x32x16_bf16 v[48:63], v[88:91], v[92:95], v[48:63]
	s_waitcnt lgkmcnt(1)
	v_mfma_f32_32x32x16_bf16 v[32:47], v[88:91], v[106:109], v[32:47]
	ds_read_b128 v[88:91], v170 offset:4096
	ds_read_b128 v[114:117], v171 offset:4096
	s_waitcnt lgkmcnt(1)
	v_mfma_f32_32x32x16_bf16 v[16:31], v[88:91], v[92:95], v[16:31]
	v_mfma_f32_32x32x16_bf16 v[0:15], v[88:91], v[106:109], v[0:15]
	v_mfma_f32_32x32x16_bf16 v[48:63], v[98:101], v[102:105], v[48:63]
	v_mfma_f32_32x32x16_bf16 v[32:47], v[98:101], v[110:113], v[32:47]
	s_waitcnt lgkmcnt(0)
	v_mfma_f32_32x32x16_bf16 v[16:31], v[114:117], v[102:105], v[16:31]
	ds_read_b128 v[88:91], v172 offset:0
	ds_read_b128 v[92:95], v176 offset:16384
	ds_read_b128 v[98:101], v173 offset:0
	ds_read_b128 v[102:105], v177 offset:16384
	v_mfma_f32_32x32x16_bf16 v[0:15], v[114:117], v[110:113], v[0:15]
	ds_read_b128 v[106:109], v176 offset:20480
	ds_read_b128 v[110:113], v177 offset:20480
	s_waitcnt lgkmcnt(4)
	v_mfma_f32_32x32x16_bf16 v[48:63], v[88:91], v[92:95], v[48:63]
	s_waitcnt lgkmcnt(1)
	v_mfma_f32_32x32x16_bf16 v[32:47], v[88:91], v[106:109], v[32:47]
	ds_read_b128 v[88:91], v172 offset:4096
	ds_read_b128 v[114:117], v173 offset:4096
	s_waitcnt lgkmcnt(1)
	v_mfma_f32_32x32x16_bf16 v[16:31], v[88:91], v[92:95], v[16:31]
	v_mfma_f32_32x32x16_bf16 v[0:15], v[88:91], v[106:109], v[0:15]
	v_mfma_f32_32x32x16_bf16 v[48:63], v[98:101], v[102:105], v[48:63]
	v_mfma_f32_32x32x16_bf16 v[32:47], v[98:101], v[110:113], v[32:47]
	s_waitcnt lgkmcnt(0)
	v_mfma_f32_32x32x16_bf16 v[16:31], v[114:117], v[102:105], v[16:31]
	s_waitcnt vmcnt(0)
	s_barrier
;     ...
;   bf16* As1 = As + 2 * 128 * 72;
;   bf16* Bs1 = As1 + 128 * 72;
;   G_LOAD(ra0, rb0, 0);
;   if (nk > 1) G_LOAD(ra1, rb1, 1);
;   G_STORE(ra0, rb0, As, Bs);
;   __syncthreads();
;   for (int kt = 0; kt < nk; kt += 2) {
;     if (kt + 2 < nk) G_LOAD(ra0, rb0, kt + 2);
;     if (kt + 1 < nk) G_STORE(ra1, rb1, As1, Bs1);
;     G_COMPUTE(As, Bs);
;     __syncthreads();
;     if (kt + 1 < nk) {
;       if (kt + 3 < nk) G_LOAD(ra1, rb1, kt + 3);
;       if (kt + 2 < nk) G_STORE(ra0, rb0, As, Bs);
;       G_COMPUTE(As1, Bs1);
;       __syncthreads();
;     }
;   }
	v_lshl_add_u64 v[66:67], v[66:67], 0, s[96:97]
	s_add_u32 m0, s94, 0x0
	s_nop 1
	global_load_lds_dwordx4 v[66:67], off
	v_lshl_add_u64 v[68:69], v[68:69], 0, s[96:97]
	s_add_u32 m0, s94, 0x4000
	s_nop 1
	global_load_lds_dwordx4 v[68:69], off
	v_lshl_add_u64 v[70:71], v[70:71], 0, s[96:97]
	s_add_u32 m0, s94, 0x1000
	s_nop 1
	global_load_lds_dwordx4 v[70:71], off
	v_lshl_add_u64 v[72:73], v[72:73], 0, s[96:97]
	s_add_u32 m0, s94, 0x5000
	s_nop 1
	global_load_lds_dwordx4 v[72:73], off
	v_lshl_add_u64 v[74:75], v[74:75], 0, s[96:97]
	s_add_u32 m0, s94, 0x2000
	s_nop 1
	global_load_lds_dwordx4 v[74:75], off
	v_lshl_add_u64 v[76:77], v[76:77], 0, s[96:97]
	s_add_u32 m0, s94, 0x6000
	s_nop 1
	global_load_lds_dwordx4 v[76:77], off
	v_lshl_add_u64 v[80:81], v[80:81], 0, s[96:97]
	s_add_u32 m0, s94, 0x3000
	s_nop 1
	global_load_lds_dwordx4 v[80:81], off
	v_lshl_add_u64 v[78:79], v[78:79], 0, s[96:97]
	s_add_u32 m0, s94, 0x7000
	s_nop 1
	global_load_lds_dwordx4 v[78:79], off
	v_mfma_f32_32x32x16_bf16 v[0:15], v[114:117], v[110:113], v[0:15]
	ds_read_b128 v[88:91], v170 offset:32768
	ds_read_b128 v[92:95], v174 offset:49152
	ds_read_b128 v[98:101], v171 offset:32768
	ds_read_b128 v[102:105], v175 offset:49152
	ds_read_b128 v[106:109], v174 offset:53248
	ds_read_b128 v[110:113], v175 offset:53248
	s_waitcnt lgkmcnt(4)
	v_mfma_f32_32x32x16_bf16 v[48:63], v[88:91], v[92:95], v[48:63]
	s_waitcnt lgkmcnt(1)
	v_mfma_f32_32x32x16_bf16 v[32:47], v[88:91], v[106:109], v[32:47]
	ds_read_b128 v[88:91], v170 offset:36864
	ds_read_b128 v[114:117], v171 offset:36864
	s_waitcnt lgkmcnt(1)
	v_mfma_f32_32x32x16_bf16 v[16:31], v[88:91], v[92:95], v[16:31]
	v_mfma_f32_32x32x16_bf16 v[0:15], v[88:91], v[106:109], v[0:15]
	v_mfma_f32_32x32x16_bf16 v[48:63], v[98:101], v[102:105], v[48:63]
	v_mfma_f32_32x32x16_bf16 v[32:47], v[98:101], v[110:113], v[32:47]
	s_waitcnt lgkmcnt(0)
	v_mfma_f32_32x32x16_bf16 v[16:31], v[114:117], v[102:105], v[16:31]
	ds_read_b128 v[88:91], v172 offset:32768
	ds_read_b128 v[92:95], v176 offset:49152
	ds_read_b128 v[98:101], v173 offset:32768
	ds_read_b128 v[102:105], v177 offset:49152
	v_mfma_f32_32x32x16_bf16 v[0:15], v[114:117], v[110:113], v[0:15]
	ds_read_b128 v[106:109], v176 offset:53248
	ds_read_b128 v[110:113], v177 offset:53248
	s_waitcnt lgkmcnt(4)
	v_mfma_f32_32x32x16_bf16 v[48:63], v[88:91], v[92:95], v[48:63]
	s_waitcnt lgkmcnt(1)
	v_mfma_f32_32x32x16_bf16 v[32:47], v[88:91], v[106:109], v[32:47]
	ds_read_b128 v[88:91], v172 offset:36864
	ds_read_b128 v[114:117], v173 offset:36864
	s_waitcnt lgkmcnt(1)
	v_mfma_f32_32x32x16_bf16 v[16:31], v[88:91], v[92:95], v[16:31]
	v_mfma_f32_32x32x16_bf16 v[0:15], v[88:91], v[106:109], v[0:15]
	v_mfma_f32_32x32x16_bf16 v[48:63], v[98:101], v[102:105], v[48:63]
	v_mfma_f32_32x32x16_bf16 v[32:47], v[98:101], v[110:113], v[32:47]
	s_waitcnt lgkmcnt(0)
	v_mfma_f32_32x32x16_bf16 v[16:31], v[114:117], v[102:105], v[16:31]
	s_waitcnt vmcnt(0)
	s_barrier
	v_lshl_add_u64 v[66:67], v[66:67], 0, s[96:97]
	s_add_u32 m0, s94, 0x8000
	s_nop 1
	global_load_lds_dwordx4 v[66:67], off
	v_lshl_add_u64 v[68:69], v[68:69], 0, s[96:97]
	s_add_u32 m0, s94, 0xc000
	s_nop 1
	global_load_lds_dwordx4 v[68:69], off
	v_lshl_add_u64 v[70:71], v[70:71], 0, s[96:97]
	s_add_u32 m0, s94, 0x9000
	s_nop 1
	global_load_lds_dwordx4 v[70:71], off
	v_lshl_add_u64 v[72:73], v[72:73], 0, s[96:97]
	s_add_u32 m0, s94, 0xd000
	s_nop 1
	global_load_lds_dwordx4 v[72:73], off
	v_lshl_add_u64 v[74:75], v[74:75], 0, s[96:97]
	s_add_u32 m0, s94, 0xa000
	s_nop 1
	global_load_lds_dwordx4 v[74:75], off
	v_lshl_add_u64 v[76:77], v[76:77], 0, s[96:97]
	s_add_u32 m0, s94, 0xe000
	s_nop 1
	global_load_lds_dwordx4 v[76:77], off
	v_lshl_add_u64 v[80:81], v[80:81], 0, s[96:97]
	s_add_u32 m0, s94, 0xb000
	s_nop 1
	global_load_lds_dwordx4 v[80:81], off
	v_lshl_add_u64 v[78:79], v[78:79], 0, s[96:97]
	s_add_u32 m0, s94, 0xf000
	s_nop 1
	global_load_lds_dwordx4 v[78:79], off
	v_mfma_f32_32x32x16_bf16 v[0:15], v[114:117], v[110:113], v[0:15]
	ds_read_b128 v[88:91], v170 offset:0
	ds_read_b128 v[92:95], v174 offset:16384
	ds_read_b128 v[98:101], v171 offset:0
	ds_read_b128 v[102:105], v175 offset:16384
	ds_read_b128 v[106:109], v174 offset:20480
	ds_read_b128 v[110:113], v175 offset:20480
	s_waitcnt lgkmcnt(4)
	v_mfma_f32_32x32x16_bf16 v[48:63], v[88:91], v[92:95], v[48:63]
	s_waitcnt lgkmcnt(1)
	v_mfma_f32_32x32x16_bf16 v[32:47], v[88:91], v[106:109], v[32:47]
	ds_read_b128 v[88:91], v170 offset:4096
	ds_read_b128 v[114:117], v171 offset:4096
	s_waitcnt lgkmcnt(1)
	v_mfma_f32_32x32x16_bf16 v[16:31], v[88:91], v[92:95], v[16:31]
	v_mfma_f32_32x32x16_bf16 v[0:15], v[88:91], v[106:109], v[0:15]
	v_mfma_f32_32x32x16_bf16 v[48:63], v[98:101], v[102:105], v[48:63]
	v_mfma_f32_32x32x16_bf16 v[32:47], v[98:101], v[110:113], v[32:47]
	s_waitcnt lgkmcnt(0)
	v_mfma_f32_32x32x16_bf16 v[16:31], v[114:117], v[102:105], v[16:31]
	ds_read_b128 v[88:91], v172 offset:0
	ds_read_b128 v[92:95], v176 offset:16384
	ds_read_b128 v[98:101], v173 offset:0
	ds_read_b128 v[102:105], v177 offset:16384
	v_mfma_f32_32x32x16_bf16 v[0:15], v[114:117], v[110:113], v[0:15]
	ds_read_b128 v[106:109], v176 offset:20480
	ds_read_b128 v[110:113], v177 offset:20480
	s_waitcnt lgkmcnt(4)
	v_mfma_f32_32x32x16_bf16 v[48:63], v[88:91], v[92:95], v[48:63]
	s_waitcnt lgkmcnt(1)
	v_mfma_f32_32x32x16_bf16 v[32:47], v[88:91], v[106:109], v[32:47]
	ds_read_b128 v[88:91], v172 offset:4096
	ds_read_b128 v[114:117], v173 offset:4096
	s_waitcnt lgkmcnt(1)
	v_mfma_f32_32x32x16_bf16 v[16:31], v[88:91], v[92:95], v[16:31]
	v_mfma_f32_32x32x16_bf16 v[0:15], v[88:91], v[106:109], v[0:15]
	v_mfma_f32_32x32x16_bf16 v[48:63], v[98:101], v[102:105], v[48:63]
	v_mfma_f32_32x32x16_bf16 v[32:47], v[98:101], v[110:113], v[32:47]
	s_waitcnt lgkmcnt(0)
	v_mfma_f32_32x32x16_bf16 v[16:31], v[114:117], v[102:105], v[16:31]
	s_waitcnt vmcnt(0)
	s_barrier
;     ...
;   bf16* As1 = As + 2 * 128 * 72;
;   bf16* Bs1 = As1 + 128 * 72;
;   G_LOAD(ra0, rb0, 0);
;   if (nk > 1) G_LOAD(ra1, rb1, 1);
;   G_STORE(ra0, rb0, As, Bs);
;   __syncthreads();
;   for (int kt = 0; kt < nk; kt += 2) {
;     if (kt + 2 < nk) G_LOAD(ra0, rb0, kt + 2);
;     if (kt + 1 < nk) G_STORE(ra1, rb1, As1, Bs1);
;     G_COMPUTE(As, Bs);
;     __syncthreads();
;     if (kt + 1 < nk) {
;       if (kt + 3 < nk) G_LOAD(ra1, rb1, kt + 3);
;       if (kt + 2 < nk) G_STORE(ra0, rb0, As, Bs);
;       G_COMPUTE(As1, Bs1);
;       __syncthreads();
;     }
;   }
	v_lshl_add_u64 v[66:67], v[66:67], 0, s[96:97]
	s_add_u32 m0, s94, 0x0
	s_nop 1
	global_load_lds_dwordx4 v[66:67], off
	v_lshl_add_u64 v[68:69], v[68:69], 0, s[96:97]
	s_add_u32 m0, s94, 0x4000
	s_nop 1
	global_load_lds_dwordx4 v[68:69], off
	v_lshl_add_u64 v[70:71], v[70:71], 0, s[96:97]
	s_add_u32 m0, s94, 0x1000
	s_nop 1
	global_load_lds_dwordx4 v[70:71], off
	v_lshl_add_u64 v[72:73], v[72:73], 0, s[96:97]
	s_add_u32 m0, s94, 0x5000
	s_nop 1
	global_load_lds_dwordx4 v[72:73], off
	v_lshl_add_u64 v[74:75], v[74:75], 0, s[96:97]
	s_add_u32 m0, s94, 0x2000
	s_nop 1
	global_load_lds_dwordx4 v[74:75], off
	v_lshl_add_u64 v[76:77], v[76:77], 0, s[96:97]
	s_add_u32 m0, s94, 0x6000
	s_nop 1
	global_load_lds_dwordx4 v[76:77], off
	v_lshl_add_u64 v[80:81], v[80:81], 0, s[96:97]
	s_add_u32 m0, s94, 0x3000
	s_nop 1
	global_load_lds_dwordx4 v[80:81], off
	v_lshl_add_u64 v[78:79], v[78:79], 0, s[96:97]
	s_add_u32 m0, s94, 0x7000
	s_nop 1
	global_load_lds_dwordx4 v[78:79], off
	v_mfma_f32_32x32x16_bf16 v[0:15], v[114:117], v[110:113], v[0:15]
	ds_read_b128 v[88:91], v170 offset:32768
	ds_read_b128 v[92:95], v174 offset:49152
	ds_read_b128 v[98:101], v171 offset:32768
	ds_read_b128 v[102:105], v175 offset:49152
	ds_read_b128 v[106:109], v174 offset:53248
	ds_read_b128 v[110:113], v175 offset:53248
	s_waitcnt lgkmcnt(4)
	v_mfma_f32_32x32x16_bf16 v[48:63], v[88:91], v[92:95], v[48:63]
	s_waitcnt lgkmcnt(1)
	v_mfma_f32_32x32x16_bf16 v[32:47], v[88:91], v[106:109], v[32:47]
	ds_read_b128 v[88:91], v170 offset:36864
	ds_read_b128 v[114:117], v171 offset:36864
	s_waitcnt lgkmcnt(1)
	v_mfma_f32_32x32x16_bf16 v[16:31], v[88:91], v[92:95], v[16:31]
	v_mfma_f32_32x32x16_bf16 v[0:15], v[88:91], v[106:109], v[0:15]
	v_mfma_f32_32x32x16_bf16 v[48:63], v[98:101], v[102:105], v[48:63]
	v_mfma_f32_32x32x16_bf16 v[32:47], v[98:101], v[110:113], v[32:47]
	s_waitcnt lgkmcnt(0)
	v_mfma_f32_32x32x16_bf16 v[16:31], v[114:117], v[102:105], v[16:31]
	ds_read_b128 v[88:91], v172 offset:32768
	ds_read_b128 v[92:95], v176 offset:49152
	ds_read_b128 v[98:101], v173 offset:32768
	ds_read_b128 v[102:105], v177 offset:49152
	v_mfma_f32_32x32x16_bf16 v[0:15], v[114:117], v[110:113], v[0:15]
	ds_read_b128 v[106:109], v176 offset:53248
	ds_read_b128 v[110:113], v177 offset:53248
	s_waitcnt lgkmcnt(4)
	v_mfma_f32_32x32x16_bf16 v[48:63], v[88:91], v[92:95], v[48:63]
	s_waitcnt lgkmcnt(1)
	v_mfma_f32_32x32x16_bf16 v[32:47], v[88:91], v[106:109], v[32:47]
	ds_read_b128 v[88:91], v172 offset:36864
	ds_read_b128 v[114:117], v173 offset:36864
	s_waitcnt lgkmcnt(1)
	v_mfma_f32_32x32x16_bf16 v[16:31], v[88:91], v[92:95], v[16:31]
	v_mfma_f32_32x32x16_bf16 v[0:15], v[88:91], v[106:109], v[0:15]
	v_mfma_f32_32x32x16_bf16 v[48:63], v[98:101], v[102:105], v[48:63]
	v_mfma_f32_32x32x16_bf16 v[32:47], v[98:101], v[110:113], v[32:47]
	s_nop 0
	s_nop 0
	s_nop 0
	s_nop 0
	s_nop 0
	s_nop 0
	s_nop 0
	s_waitcnt lgkmcnt(0)
	s_waitcnt vmcnt(0)
	s_barrier
	v_lshl_add_u64 v[66:67], v[66:67], 0, s[96:97]
	s_add_u32 m0, s94, 0x8000
	s_nop 1
	global_load_lds_dwordx4 v[66:67], off
	v_lshl_add_u64 v[68:69], v[68:69], 0, s[96:97]
	s_add_u32 m0, s94, 0xc000
	s_nop 1
	global_load_lds_dwordx4 v[68:69], off
	v_lshl_add_u64 v[70:71], v[70:71], 0, s[96:97]
	s_add_u32 m0, s94, 0x9000
	s_nop 1
	global_load_lds_dwordx4 v[70:71], off
	v_lshl_add_u64 v[72:73], v[72:73], 0, s[96:97]
	s_add_u32 m0, s94, 0xd000
	s_nop 1
	global_load_lds_dwordx4 v[72:73], off
	v_lshl_add_u64 v[74:75], v[74:75], 0, s[96:97]
	s_add_u32 m0, s94, 0xa000
	s_nop 1
	global_load_lds_dwordx4 v[74:75], off
	v_lshl_add_u64 v[76:77], v[76:77], 0, s[96:97]
	s_add_u32 m0, s94, 0xe000
	s_nop 1
	global_load_lds_dwordx4 v[76:77], off
	v_lshl_add_u64 v[80:81], v[80:81], 0, s[96:97]
	s_add_u32 m0, s94, 0xb000
	s_nop 1
	global_load_lds_dwordx4 v[80:81], off
	v_lshl_add_u64 v[78:79], v[78:79], 0, s[96:97]
	s_add_u32 m0, s94, 0xf000
	s_nop 1
	global_load_lds_dwordx4 v[78:79], off
	v_mfma_f32_32x32x16_bf16 v[16:31], v[114:117], v[102:105], v[16:31]
	ds_read_b128 v[66:69], v170 offset:0
	ds_read_b128 v[70:73], v174 offset:16384
	ds_read_b128 v[74:77], v171 offset:0
	ds_read_b128 v[78:81], v175 offset:16384
	ds_read_b128 v[86:89], v174 offset:20480
	ds_read_b128 v[90:93], v175 offset:20480
	v_mfma_f32_32x32x16_bf16 v[0:15], v[114:117], v[110:113], v[0:15]
	s_waitcnt lgkmcnt(4)
	v_mfma_f32_32x32x16_bf16 v[48:63], v[66:69], v[70:73], v[48:63]
	s_waitcnt lgkmcnt(1)
	v_mfma_f32_32x32x16_bf16 v[32:47], v[66:69], v[86:89], v[32:47]
	ds_read_b128 v[66:69], v170 offset:4096
	ds_read_b128 v[98:101], v171 offset:4096
	s_waitcnt lgkmcnt(1)
	v_mfma_f32_32x32x16_bf16 v[16:31], v[66:69], v[70:73], v[16:31]
	v_mfma_f32_32x32x16_bf16 v[0:15], v[66:69], v[86:89], v[0:15]
	v_mfma_f32_32x32x16_bf16 v[48:63], v[74:77], v[78:81], v[48:63]
	v_mfma_f32_32x32x16_bf16 v[32:47], v[74:77], v[90:93], v[32:47]
	s_waitcnt lgkmcnt(0)
	v_mfma_f32_32x32x16_bf16 v[16:31], v[98:101], v[78:81], v[16:31]
	ds_read_b128 v[66:69], v172 offset:0
	ds_read_b128 v[70:73], v176 offset:16384
	ds_read_b128 v[74:77], v173 offset:0
	ds_read_b128 v[78:81], v177 offset:16384
	v_mfma_f32_32x32x16_bf16 v[0:15], v[98:101], v[90:93], v[0:15]
	ds_read_b128 v[86:89], v176 offset:20480
	ds_read_b128 v[90:93], v177 offset:20480
	s_waitcnt lgkmcnt(4)
	v_mfma_f32_32x32x16_bf16 v[48:63], v[66:69], v[70:73], v[48:63]
	s_waitcnt lgkmcnt(1)
	v_mfma_f32_32x32x16_bf16 v[32:47], v[66:69], v[86:89], v[32:47]
	ds_read_b128 v[66:69], v172 offset:4096
	ds_read_b128 v[98:101], v173 offset:4096
	s_waitcnt lgkmcnt(0)
	s_waitcnt vmcnt(0)
	s_barrier
; #define PIN(i) (gl_in(p.in[lnd(i)]))
; #define PW(T, off) ((T*)(lndp(p.ws) + (off)))
; DEVI float bf2f(bf16 h) { return __uint_as_float(((unsigned)h) << 16); }
; DEVI int accrow(int r, int lane) { return (r & 3) + 8 * (r >> 2) + 4 * (lane >> 5); }
; template <int EPI>
; DEVI void gemm_epi(const Params& p, const GJob& jb, f32x16 (&acc)[2][2], int rbase, int cbase, int lane) {
;   const float* i_rk_w0 = PIN(23);
;   const float* i_rk_a0 = PIN(26);
;   char* ar = PW(char, W_arena);
; #pragma unroll
;   for (int i = 0; i < 2; ++i) {
; #pragma unroll
;     for (int r = 0; r < 16; ++r) {
;       const int row = rbase + i * 32 + accrow(r, lane);
;       if (row < M) {
; #pragma unroll
;         for (int j = 0; j < 2; ++j) {
;           const int col = cbase + j * 32 + (lane & 31);
;           const float v = acc[i][j][r];
;           if (EPI == EPI_SSD_IN) {
;             if (col < 2048) ((bf16*)(ar + S_ZB))[(size_t)row * 2048 + col] = f2bf(v);
;             else if (col < 6144) ((bf16*)(ar + S_XBC))[(size_t)row * 4096 + col - 2048] = f2bf(v);
;             else if (col < 6176) ((float*)(ar + S_DTRAW))[(size_t)row * 32 + col - 6144] = v;
;           } else if (EPI == EPI_RESID) {
;             PW(bf16, W_Z)[(size_t)row * 1024 + col] = f2bf(ALPHA * bf2f(PW(bf16, W_Xb)[(size_t)row * 1024 + col]) + v);
;     ...
;     G_COMPUTE(As, Bs);
;     __syncthreads();
;     if (kt + 1 < nk) {
;       if (kt + 3 < nk) G_LOAD(ra1, rb1, kt + 3);
;       if (kt + 2 < nk) G_STORE(ra0, rb0, As, Bs);
;       G_COMPUTE(As1, Bs1);
;       __syncthreads();
;     }
;   }
	v_mfma_f32_32x32x16_bf16 v[16:31], v[66:69], v[70:73], v[16:31]
	v_mfma_f32_32x32x16_bf16 v[48:63], v[74:77], v[78:81], v[48:63]
	v_mfma_f32_32x32x16_bf16 v[32:47], v[74:77], v[90:93], v[32:47]
	v_mfma_f32_32x32x16_bf16 v[0:15], v[66:69], v[86:89], v[0:15]
	v_mfma_f32_32x32x16_bf16 v[16:31], v[98:101], v[78:81], v[16:31]
	ds_read_b128 v[66:69], v170 offset:32768
	ds_read_b128 v[70:73], v174 offset:49152
	ds_read_b128 v[74:77], v175 offset:49152
	ds_read_b128 v[78:81], v171 offset:32768
	ds_read_b128 v[86:89], v174 offset:53248
	s_waitcnt lgkmcnt(3)
	v_mfma_f32_32x32x16_bf16 v[48:63], v[66:69], v[70:73], v[48:63]
	s_waitcnt lgkmcnt(0)
	v_mfma_f32_32x32x16_bf16 v[32:47], v[66:69], v[86:89], v[32:47]
	ds_read_b128 v[66:69], v170 offset:36864
	v_mfma_f32_32x32x16_bf16 v[0:15], v[98:101], v[90:93], v[0:15]
	s_waitcnt lgkmcnt(0)
	v_mfma_f32_32x32x16_bf16 v[16:31], v[66:69], v[70:73], v[16:31]
	ds_read_b128 v[70:73], v171 offset:36864
	v_mfma_f32_32x32x16_bf16 v[0:15], v[66:69], v[86:89], v[0:15]
	ds_read_b128 v[66:69], v175 offset:53248
	v_mfma_f32_32x32x16_bf16 v[48:63], v[78:81], v[74:77], v[48:63]
	s_waitcnt lgkmcnt(0)
	v_mfma_f32_32x32x16_bf16 v[32:47], v[78:81], v[66:69], v[32:47]
	v_mfma_f32_32x32x16_bf16 v[16:31], v[70:73], v[74:77], v[16:31]
	v_mfma_f32_32x32x16_bf16 v[0:15], v[70:73], v[66:69], v[0:15]
	ds_read_b128 v[66:69], v172 offset:32768
	ds_read_b128 v[70:73], v176 offset:49152
	ds_read_b128 v[74:77], v176 offset:53248
	s_waitcnt lgkmcnt(1)
	v_mfma_f32_32x32x16_bf16 v[48:63], v[66:69], v[70:73], v[48:63]
	s_waitcnt lgkmcnt(0)
	v_mfma_f32_32x32x16_bf16 v[32:47], v[66:69], v[74:77], v[32:47]
	ds_read_b128 v[66:69], v172 offset:36864
	s_waitcnt lgkmcnt(0)
	v_mfma_f32_32x32x16_bf16 v[16:31], v[66:69], v[70:73], v[16:31]
	ds_read_b128 v[78:81], v177 offset:53248
	ds_read_b128 v[86:89], v177 offset:49152
	ds_read_b128 v[90:93], v173 offset:36864
	ds_read_b128 v[70:73], v173 offset:32768
	s_waitcnt lgkmcnt(0)
	s_barrier
	s_ashr_i32 s15, s14, 31
	s_lshl_b64 s[14:15], s[14:15], 3
	v_mfma_f32_32x32x16_bf16 v[0:15], v[66:69], v[74:77], v[0:15]
	s_add_u32 s14, s0, s14
	s_addc_u32 s15, s1, s15
	s_load_dwordx2 s[14:15], s[14:15], 0x0
	s_waitcnt lgkmcnt(0)
	s_mov_b32 s14, 26
	s_ashr_i32 s15, s14, 31
	v_mfma_f32_32x32x16_bf16 v[48:63], v[70:73], v[86:89], v[48:63]
	s_lshl_b64 s[14:15], s[14:15], 3
	s_add_u32 s14, s0, s14
	s_addc_u32 s15, s1, s15
	s_load_dwordx2 s[14:15], s[14:15], 0x0
	v_or_b32_e32 v66, s2, v65
	s_waitcnt lgkmcnt(0)
	v_or_b32_e32 v64, 32, v66
	v_mfma_f32_32x32x16_bf16 v[32:47], v[70:73], v[78:81], v[32:47]
	v_lshrrev_b32_e32 v72, 3, v84
	v_add_u32_e32 v70, s3, v85
	v_and_b32_e32 v71, 4, v72
	v_or_b32_e32 v68, v70, v71
	s_mov_b64 s[14:15], s[74:75]
	v_cmp_gt_i32_e32 vcc, s90, v68
	v_ashrrev_i32_e32 v67, 31, v66
	v_mfma_f32_32x32x16_bf16 v[16:31], v[90:93], v[86:89], v[16:31]
	v_ashrrev_i32_e32 v65, 31, v64
	v_mfma_f32_32x32x16_bf16 v[0:15], v[90:93], v[78:81], v[0:15]
	s_and_saveexec_b64 s[2:3], vcc
	s_cbranch_execz .LBB0_1319
	v_ashrrev_i32_e32 v69, 31, v68
	v_lshlrev_b64 v[68:69], 10, v[68:69]
	v_lshl_add_u64 v[74:75], v[68:69], 0, v[66:67]
	s_mov_b64 s[14:15], s[74:75]
	v_lshlrev_b64 v[74:75], 1, v[74:75]
	v_lshl_add_u64 v[68:69], v[68:69], 0, v[64:65]
	v_lshl_add_u64 v[76:77], s[14:15], 0, v[74:75]
	v_add_co_u32_e32 v76, vcc, 0xf724000, v76
	s_mov_b64 s[14:15], s[74:75]
	s_nop 0
	v_addc_co_u32_e32 v77, vcc, 0, v77, vcc
	global_load_ushort v73, v[76:77], off
	v_lshlrev_b64 v[68:69], 1, v[68:69]
	v_lshl_add_u64 v[74:75], s[14:15], 0, v[74:75]
	v_add_co_u32_e32 v74, vcc, 0xb5a4000, v74
	s_mov_b64 s[14:15], s[74:75]
	s_nop 0
	v_addc_co_u32_e32 v75, vcc, 0, v75, vcc
	s_waitcnt vmcnt(0)
	v_lshlrev_b32_e32 v73, 16, v73
	v_fmamk_f32 v48, v73, 0x3fd744fd, v48
	v_cvt_pk_bf16_f32 v48, v48, s0
	global_store_short v[74:75], v48, off
	s_nop 0
	v_lshl_add_u64 v[74:75], s[14:15], 0, v[68:69]
	v_add_co_u32_e32 v74, vcc, s80, v74
	s_mov_b64 s[14:15], s[74:75]
	s_nop 0
	v_addc_co_u32_e32 v75, vcc, 0, v75, vcc
	global_load_ushort v48, v[74:75], off
	s_waitcnt vmcnt(0)
	v_lshlrev_b32_e32 v48, 16, v48
	v_lshl_add_u64 v[68:69], s[14:15], 0, v[68:69]
	v_fmamk_f32 v32, v48, 0x3fd744fd, v32
	v_add_co_u32_e32 v68, vcc, 0xb5a4000, v68
	v_cvt_pk_bf16_f32 v32, v32, s0
	s_nop 0
	v_addc_co_u32_e32 v69, vcc, 0, v69, vcc
	global_store_short v[68:69], v32, off
